# attention lazy rescale (T=8 log2 units), FFN1 epilogue ssq loads batched + nt H stores, s_setprio removed from GEMM loops
# speedup vs baseline: 1.0464x; 1.0310x over previous
.LBB0_229:
	ds_read_b128 v[160:163], v156
	ds_read_b128 v[164:167], v156 offset:1024
	ds_read_b128 v[168:171], v156 offset:2048
	ds_read_b128 v[172:175], v156 offset:3072
	ds_read_b128 v[176:179], v157
	ds_read_b128 v[180:183], v157 offset:1024
	ds_read_b128 v[184:187], v157 offset:2048
	ds_read_b128 v[188:191], v157 offset:3072
	s_add_u32 s47, s52, 0xfffc0080
	s_addc_u32 s60, s53, -1
	s_cmp_eq_u32 s45, 12
	s_cselect_b32 s61, s7, s60
	s_cselect_b32 s60, s9, s47
	s_cselect_b32 s73, s26, s3
	s_cselect_b32 s72, s27, s2
	v_lshl_add_u64 v[150:151], s[52:53], 0, v[144:145]
	s_add_i32 m0, s58, 0xc000
	ds_read_b128 v[192:195], v158
	ds_read_b128 v[196:199], v158 offset:1024
	ds_read_b128 v[200:203], v158 offset:2048
	ds_read_b128 v[204:207], v158 offset:3072
	ds_read_b128 v[208:211], v158 offset:4096
	ds_read_b128 v[212:215], v158 offset:5120
	ds_read_b128 v[216:219], v158 offset:6144
	ds_read_b128 v[220:223], v158 offset:7168
	global_load_lds_dwordx4 v[150:151], off
	v_lshl_add_u64 v[150:151], v[150:151], 0, s[12:13]
	s_add_i32 m0, s58, 0xe000
	s_nop 0
	global_load_lds_dwordx4 v[150:151], off
	s_waitcnt vmcnt(8)
	s_waitcnt lgkmcnt(0)
	s_barrier
	s_waitcnt lgkmcnt(0)
	v_mfma_f32_16x16x32_bf16 v[124:127], v[160:163], v[192:195], v[124:127]
	v_mfma_f32_16x16x32_bf16 v[120:123], v[168:171], v[192:195], v[120:123]
	v_mfma_f32_16x16x32_bf16 v[116:119], v[160:163], v[200:203], v[116:119]
	v_mfma_f32_16x16x32_bf16 v[108:111], v[168:171], v[200:203], v[108:111]
	v_mfma_f32_16x16x32_bf16 v[100:103], v[160:163], v[208:211], v[100:103]
	v_mfma_f32_16x16x32_bf16 v[96:99], v[168:171], v[208:211], v[96:99]
	v_mfma_f32_16x16x32_bf16 v[84:87], v[160:163], v[216:219], v[84:87]
	v_mfma_f32_16x16x32_bf16 v[80:83], v[168:171], v[216:219], v[80:83]
	v_mfma_f32_16x16x32_bf16 v[124:127], v[164:167], v[196:199], v[124:127]
	v_mfma_f32_16x16x32_bf16 v[120:123], v[172:175], v[196:199], v[120:123]
	v_mfma_f32_16x16x32_bf16 v[116:119], v[164:167], v[204:207], v[116:119]
	v_mfma_f32_16x16x32_bf16 v[108:111], v[172:175], v[204:207], v[108:111]
	v_mfma_f32_16x16x32_bf16 v[100:103], v[164:167], v[212:215], v[100:103]
	v_mfma_f32_16x16x32_bf16 v[96:99], v[172:175], v[212:215], v[96:99]
	v_mfma_f32_16x16x32_bf16 v[84:87], v[164:167], v[220:223], v[84:87]
	v_mfma_f32_16x16x32_bf16 v[80:83], v[172:175], v[220:223], v[80:83]
	v_mfma_f32_16x16x32_bf16 v[112:115], v[176:179], v[192:195], v[112:115]
	v_mfma_f32_16x16x32_bf16 v[104:107], v[184:187], v[192:195], v[104:107]
	v_mfma_f32_16x16x32_bf16 v[92:95], v[176:179], v[200:203], v[92:95]
	v_mfma_f32_16x16x32_bf16 v[88:91], v[184:187], v[200:203], v[88:91]
	v_mfma_f32_16x16x32_bf16 v[76:79], v[176:179], v[208:211], v[76:79]
	v_mfma_f32_16x16x32_bf16 v[72:75], v[184:187], v[208:211], v[72:75]
	v_mfma_f32_16x16x32_bf16 v[68:71], v[176:179], v[216:219], v[68:71]
	v_mfma_f32_16x16x32_bf16 v[64:67], v[184:187], v[216:219], v[64:67]
	v_mfma_f32_16x16x32_bf16 v[112:115], v[180:183], v[196:199], v[112:115]
	v_mfma_f32_16x16x32_bf16 v[104:107], v[188:191], v[196:199], v[104:107]
	v_mfma_f32_16x16x32_bf16 v[92:95], v[180:183], v[204:207], v[92:95]
	v_mfma_f32_16x16x32_bf16 v[88:91], v[188:191], v[204:207], v[88:91]
	v_mfma_f32_16x16x32_bf16 v[76:79], v[180:183], v[212:215], v[76:79]
	v_mfma_f32_16x16x32_bf16 v[72:75], v[188:191], v[212:215], v[72:75]
	v_mfma_f32_16x16x32_bf16 v[68:71], v[180:183], v[220:223], v[68:71]
	v_mfma_f32_16x16x32_bf16 v[64:67], v[188:191], v[220:223], v[64:67]
	s_barrier
	s_add_i32 s47, s69, s57
	v_lshl_add_u64 v[150:151], s[72:73], 0, v[130:131]
	s_mov_b32 m0, s47
	ds_read_b128 v[192:195], v158 offset:16384
	ds_read_b128 v[196:199], v158 offset:17408
	ds_read_b128 v[200:203], v158 offset:18432
	ds_read_b128 v[204:207], v158 offset:19456
	ds_read_b128 v[208:211], v158 offset:20480
	ds_read_b128 v[212:215], v158 offset:21504
	ds_read_b128 v[216:219], v158 offset:22528
	ds_read_b128 v[220:223], v158 offset:23552
	global_load_lds_dwordx4 v[150:151], off
	v_lshl_add_u64 v[224:225], v[150:151], 0, s[12:13]
	s_add_i32 m0, s47, 0x2000
	s_add_i32 s47, s70, s57
	global_load_lds_dwordx4 v[224:225], off
	v_lshl_add_u64 v[224:225], v[150:151], 0, s[14:15]
	s_mov_b32 m0, s47
	s_nop 0
	global_load_lds_dwordx4 v[224:225], off
	v_lshl_add_u64 v[224:225], v[150:151], 0, s[16:17]
	s_add_i32 m0, s47, 0x2000
	s_nop 0
	global_load_lds_dwordx4 v[224:225], off
	v_lshl_add_u64 v[224:225], s[60:61], 0, v[128:129]
	s_mov_b32 m0, s58
	v_lshl_add_u64 v[226:227], v[224:225], 0, s[12:13]
	global_load_lds_dwordx4 v[224:225], off
	s_mov_b32 m0, s59
	s_nop 0
	global_load_lds_dwordx4 v[226:227], off
	s_waitcnt vmcnt(8)
	s_waitcnt lgkmcnt(0)
	s_barrier
	s_waitcnt lgkmcnt(0)
	v_mfma_f32_16x16x32_bf16 v[60:63], v[160:163], v[192:195], v[60:63]
	v_mfma_f32_16x16x32_bf16 v[56:59], v[168:171], v[192:195], v[56:59]
	v_mfma_f32_16x16x32_bf16 v[52:55], v[160:163], v[200:203], v[52:55]
	v_mfma_f32_16x16x32_bf16 v[48:51], v[168:171], v[200:203], v[48:51]
	v_mfma_f32_16x16x32_bf16 v[36:39], v[160:163], v[208:211], v[36:39]
	v_mfma_f32_16x16x32_bf16 v[32:35], v[168:171], v[208:211], v[32:35]
	v_mfma_f32_16x16x32_bf16 v[20:23], v[160:163], v[216:219], v[20:23]
	v_mfma_f32_16x16x32_bf16 v[16:19], v[168:171], v[216:219], v[16:19]
	v_mfma_f32_16x16x32_bf16 v[60:63], v[164:167], v[196:199], v[60:63]
	v_mfma_f32_16x16x32_bf16 v[56:59], v[172:175], v[196:199], v[56:59]
	v_mfma_f32_16x16x32_bf16 v[52:55], v[164:167], v[204:207], v[52:55]
	v_mfma_f32_16x16x32_bf16 v[48:51], v[172:175], v[204:207], v[48:51]
	v_mfma_f32_16x16x32_bf16 v[36:39], v[164:167], v[212:215], v[36:39]
	v_mfma_f32_16x16x32_bf16 v[32:35], v[172:175], v[212:215], v[32:35]
	v_mfma_f32_16x16x32_bf16 v[20:23], v[164:167], v[220:223], v[20:23]
	v_mfma_f32_16x16x32_bf16 v[16:19], v[172:175], v[220:223], v[16:19]
	v_mfma_f32_16x16x32_bf16 v[44:47], v[176:179], v[192:195], v[44:47]
	v_mfma_f32_16x16x32_bf16 v[40:43], v[184:187], v[192:195], v[40:43]
	v_mfma_f32_16x16x32_bf16 v[28:31], v[176:179], v[200:203], v[28:31]
	v_mfma_f32_16x16x32_bf16 v[24:27], v[184:187], v[200:203], v[24:27]
	v_mfma_f32_16x16x32_bf16 v[12:15], v[176:179], v[208:211], v[12:15]
	v_mfma_f32_16x16x32_bf16 v[8:11], v[184:187], v[208:211], v[8:11]
	v_mfma_f32_16x16x32_bf16 v[4:7], v[176:179], v[216:219], v[4:7]
	v_mfma_f32_16x16x32_bf16 v[0:3], v[184:187], v[216:219], v[0:3]
	v_mfma_f32_16x16x32_bf16 v[44:47], v[180:183], v[196:199], v[44:47]
	v_mfma_f32_16x16x32_bf16 v[40:43], v[188:191], v[196:199], v[40:43]
	v_mfma_f32_16x16x32_bf16 v[28:31], v[180:183], v[204:207], v[28:31]
	v_mfma_f32_16x16x32_bf16 v[24:27], v[188:191], v[204:207], v[24:27]
	v_mfma_f32_16x16x32_bf16 v[12:15], v[180:183], v[212:215], v[12:15]
	v_mfma_f32_16x16x32_bf16 v[8:11], v[188:191], v[212:215], v[8:11]
	v_mfma_f32_16x16x32_bf16 v[4:7], v[180:183], v[220:223], v[4:7]
	v_mfma_f32_16x16x32_bf16 v[0:3], v[188:191], v[220:223], v[0:3]
	s_barrier
	s_add_i32 s47, 0, 0x18000
	v_add_u32_e32 v132, s47, v154
	s_add_i32 s60, 0, 0x1c000
	ds_read_b128 v[160:163], v132
	ds_read_b128 v[164:167], v132 offset:1024
	ds_read_b128 v[168:171], v132 offset:2048
	ds_read_b128 v[172:175], v132 offset:3072
	v_add_u32_e32 v132, s60, v154
	ds_read_b128 v[176:179], v132
	ds_read_b128 v[180:183], v132 offset:1024
	ds_read_b128 v[184:187], v132 offset:2048
	ds_read_b128 v[188:191], v132 offset:3072
	s_mov_b32 m0, s62
	v_lshl_add_u64 v[226:227], v[224:225], 0, s[14:15]
	ds_read_b128 v[192:195], v158 offset:32768
	ds_read_b128 v[196:199], v158 offset:33792
	ds_read_b128 v[200:203], v158 offset:34816
	ds_read_b128 v[204:207], v158 offset:35840
	ds_read_b128 v[208:211], v158 offset:36864
	ds_read_b128 v[212:215], v158 offset:37888
	ds_read_b128 v[216:219], v158 offset:38912
	ds_read_b128 v[220:223], v158 offset:39936
	global_load_lds_dwordx4 v[226:227], off
	v_lshl_add_u64 v[226:227], v[224:225], 0, s[16:17]
	s_mov_b32 m0, s65
	s_nop 0
	global_load_lds_dwordx4 v[226:227], off
	s_waitcnt vmcnt(8)
	s_waitcnt lgkmcnt(0)
	s_barrier
	s_waitcnt lgkmcnt(0)
	v_mfma_f32_16x16x32_bf16 v[124:127], v[160:163], v[192:195], v[124:127]
	v_mfma_f32_16x16x32_bf16 v[120:123], v[168:171], v[192:195], v[120:123]
	v_mfma_f32_16x16x32_bf16 v[116:119], v[160:163], v[200:203], v[116:119]
	v_mfma_f32_16x16x32_bf16 v[108:111], v[168:171], v[200:203], v[108:111]
	v_mfma_f32_16x16x32_bf16 v[100:103], v[160:163], v[208:211], v[100:103]
	v_mfma_f32_16x16x32_bf16 v[96:99], v[168:171], v[208:211], v[96:99]
	v_mfma_f32_16x16x32_bf16 v[84:87], v[160:163], v[216:219], v[84:87]
	v_mfma_f32_16x16x32_bf16 v[80:83], v[168:171], v[216:219], v[80:83]
	v_mfma_f32_16x16x32_bf16 v[124:127], v[164:167], v[196:199], v[124:127]
	v_mfma_f32_16x16x32_bf16 v[120:123], v[172:175], v[196:199], v[120:123]
	v_mfma_f32_16x16x32_bf16 v[116:119], v[164:167], v[204:207], v[116:119]
	v_mfma_f32_16x16x32_bf16 v[108:111], v[172:175], v[204:207], v[108:111]
	v_mfma_f32_16x16x32_bf16 v[100:103], v[164:167], v[212:215], v[100:103]
	v_mfma_f32_16x16x32_bf16 v[96:99], v[172:175], v[212:215], v[96:99]
	v_mfma_f32_16x16x32_bf16 v[84:87], v[164:167], v[220:223], v[84:87]
	v_mfma_f32_16x16x32_bf16 v[80:83], v[172:175], v[220:223], v[80:83]
	v_mfma_f32_16x16x32_bf16 v[112:115], v[176:179], v[192:195], v[112:115]
	v_mfma_f32_16x16x32_bf16 v[104:107], v[184:187], v[192:195], v[104:107]
	v_mfma_f32_16x16x32_bf16 v[92:95], v[176:179], v[200:203], v[92:95]
	v_mfma_f32_16x16x32_bf16 v[88:91], v[184:187], v[200:203], v[88:91]
	v_mfma_f32_16x16x32_bf16 v[76:79], v[176:179], v[208:211], v[76:79]
	v_mfma_f32_16x16x32_bf16 v[72:75], v[184:187], v[208:211], v[72:75]
	v_mfma_f32_16x16x32_bf16 v[68:71], v[176:179], v[216:219], v[68:71]
	v_mfma_f32_16x16x32_bf16 v[64:67], v[184:187], v[216:219], v[64:67]
	v_mfma_f32_16x16x32_bf16 v[112:115], v[180:183], v[196:199], v[112:115]
	v_mfma_f32_16x16x32_bf16 v[104:107], v[188:191], v[196:199], v[104:107]
	v_mfma_f32_16x16x32_bf16 v[92:95], v[180:183], v[204:207], v[92:95]
	v_mfma_f32_16x16x32_bf16 v[88:91], v[188:191], v[204:207], v[88:91]
	v_mfma_f32_16x16x32_bf16 v[76:79], v[180:183], v[212:215], v[76:79]
	v_mfma_f32_16x16x32_bf16 v[72:75], v[188:191], v[212:215], v[72:75]
	v_mfma_f32_16x16x32_bf16 v[68:71], v[180:183], v[220:223], v[68:71]
	v_mfma_f32_16x16x32_bf16 v[64:67], v[188:191], v[220:223], v[64:67]
	s_barrier
	s_add_i32 s47, s47, s57
	v_lshl_add_u64 v[226:227], v[150:151], 0, s[30:31]
	s_mov_b32 m0, s47
	ds_read_b128 v[192:195], v158 offset:49152
	ds_read_b128 v[196:199], v158 offset:50176
	ds_read_b128 v[200:203], v158 offset:51200
	ds_read_b128 v[204:207], v158 offset:52224
	ds_read_b128 v[208:211], v158 offset:53248
	ds_read_b128 v[212:215], v158 offset:54272
	ds_read_b128 v[216:219], v158 offset:55296
	ds_read_b128 v[220:223], v158 offset:56320
	global_load_lds_dwordx4 v[226:227], off
	v_lshl_add_u64 v[226:227], v[150:151], 0, s[34:35]
	s_add_i32 m0, s47, 0x2000
	s_add_i32 s47, s60, s57
	global_load_lds_dwordx4 v[226:227], off
	v_lshl_add_u64 v[226:227], v[150:151], 0, s[36:37]
	s_mov_b32 m0, s47
	v_lshl_add_u64 v[150:151], v[150:151], 0, s[38:39]
	global_load_lds_dwordx4 v[226:227], off
	s_add_i32 m0, s47, 0x2000
	s_nop 0
	global_load_lds_dwordx4 v[150:151], off
	v_lshl_add_u64 v[150:151], v[224:225], 0, s[30:31]
	s_mov_b32 m0, s67
	s_nop 0
	global_load_lds_dwordx4 v[150:151], off
	v_lshl_add_u64 v[150:151], v[224:225], 0, s[34:35]
	s_mov_b32 m0, s68
	s_nop 0
	global_load_lds_dwordx4 v[150:151], off
	s_waitcnt vmcnt(8)
	s_waitcnt lgkmcnt(0)
	s_barrier
	s_waitcnt lgkmcnt(0)
	v_mfma_f32_16x16x32_bf16 v[60:63], v[160:163], v[192:195], v[60:63]
	v_mfma_f32_16x16x32_bf16 v[56:59], v[168:171], v[192:195], v[56:59]
	v_mfma_f32_16x16x32_bf16 v[52:55], v[160:163], v[200:203], v[52:55]
	v_mfma_f32_16x16x32_bf16 v[48:51], v[168:171], v[200:203], v[48:51]
	v_mfma_f32_16x16x32_bf16 v[36:39], v[160:163], v[208:211], v[36:39]
	v_mfma_f32_16x16x32_bf16 v[32:35], v[168:171], v[208:211], v[32:35]
	v_mfma_f32_16x16x32_bf16 v[20:23], v[160:163], v[216:219], v[20:23]
	v_mfma_f32_16x16x32_bf16 v[16:19], v[168:171], v[216:219], v[16:19]
	v_mfma_f32_16x16x32_bf16 v[60:63], v[164:167], v[196:199], v[60:63]
	v_mfma_f32_16x16x32_bf16 v[56:59], v[172:175], v[196:199], v[56:59]
	v_mfma_f32_16x16x32_bf16 v[52:55], v[164:167], v[204:207], v[52:55]
	v_mfma_f32_16x16x32_bf16 v[48:51], v[172:175], v[204:207], v[48:51]
	v_mfma_f32_16x16x32_bf16 v[36:39], v[164:167], v[212:215], v[36:39]
	v_mfma_f32_16x16x32_bf16 v[32:35], v[172:175], v[212:215], v[32:35]
	v_mfma_f32_16x16x32_bf16 v[20:23], v[164:167], v[220:223], v[20:23]
	v_mfma_f32_16x16x32_bf16 v[16:19], v[172:175], v[220:223], v[16:19]
	v_mfma_f32_16x16x32_bf16 v[44:47], v[176:179], v[192:195], v[44:47]
	v_mfma_f32_16x16x32_bf16 v[40:43], v[184:187], v[192:195], v[40:43]
	v_mfma_f32_16x16x32_bf16 v[28:31], v[176:179], v[200:203], v[28:31]
	v_mfma_f32_16x16x32_bf16 v[24:27], v[184:187], v[200:203], v[24:27]
	v_mfma_f32_16x16x32_bf16 v[12:15], v[176:179], v[208:211], v[12:15]
	v_mfma_f32_16x16x32_bf16 v[8:11], v[184:187], v[208:211], v[8:11]
	v_mfma_f32_16x16x32_bf16 v[4:7], v[176:179], v[216:219], v[4:7]
	v_mfma_f32_16x16x32_bf16 v[0:3], v[184:187], v[216:219], v[0:3]
	v_mfma_f32_16x16x32_bf16 v[44:47], v[180:183], v[196:199], v[44:47]
	v_mfma_f32_16x16x32_bf16 v[40:43], v[188:191], v[196:199], v[40:43]
	v_mfma_f32_16x16x32_bf16 v[28:31], v[180:183], v[204:207], v[28:31]
	v_mfma_f32_16x16x32_bf16 v[24:27], v[188:191], v[204:207], v[24:27]
	v_mfma_f32_16x16x32_bf16 v[12:15], v[180:183], v[212:215], v[12:15]
	v_mfma_f32_16x16x32_bf16 v[8:11], v[188:191], v[212:215], v[8:11]
	v_mfma_f32_16x16x32_bf16 v[4:7], v[180:183], v[220:223], v[4:7]
	v_mfma_f32_16x16x32_bf16 v[0:3], v[188:191], v[220:223], v[0:3]
	s_barrier
	s_add_i32 s45, s45, 2
	s_add_u32 s52, s52, 0x100
	s_addc_u32 s53, s53, 0
	s_add_u32 s2, s2, 0x100
	s_addc_u32 s3, s3, 0
	s_cmp_gt_u32 s45, 13
	s_cbranch_scc0 .LBB0_229
	s_and_b64 vcc, exec, s[40:41]
	s_cbranch_vccz .LBB0_232
	s_barrier

.LBB0_416:
	ds_read_b128 v[142:145], v138
	ds_read_b128 v[146:149], v138 offset:1024
	ds_read_b128 v[150:153], v138 offset:2048
	ds_read_b128 v[154:157], v138 offset:3072
	ds_read_b128 v[158:161], v139
	ds_read_b128 v[162:165], v139 offset:1024
	ds_read_b128 v[166:169], v139 offset:2048
	ds_read_b128 v[170:173], v139 offset:3072
	s_add_u32 s60, s50, 0xfffc0080
	s_addc_u32 s61, s51, -1
	s_cmp_eq_u32 s82, 12
	s_cselect_b32 s61, s26, s61
	s_cselect_b32 s60, s27, s60
	s_cselect_b32 s85, s41, s3
	s_cselect_b32 s84, s43, s2
	v_lshl_add_u64 v[206:207], s[50:51], 0, v[132:133]
	s_add_i32 m0, s67, 0xc000
	ds_read_b128 v[174:177], v140
	ds_read_b128 v[178:181], v140 offset:1024
	ds_read_b128 v[182:185], v140 offset:2048
	ds_read_b128 v[186:189], v140 offset:3072
	ds_read_b128 v[190:193], v140 offset:4096
	ds_read_b128 v[194:197], v140 offset:5120
	ds_read_b128 v[198:201], v140 offset:6144
	ds_read_b128 v[202:205], v140 offset:7168
	global_load_lds_dwordx4 v[206:207], off
	v_lshl_add_u64 v[206:207], v[206:207], 0, s[6:7]
	s_add_i32 m0, s67, 0xe000
	s_nop 0
	global_load_lds_dwordx4 v[206:207], off
	s_waitcnt vmcnt(8)
	s_waitcnt lgkmcnt(0)
	s_barrier
	s_waitcnt lgkmcnt(0)
	v_mfma_f32_16x16x32_bf16 v[124:127], v[142:145], v[174:177], v[124:127]
	v_mfma_f32_16x16x32_bf16 v[120:123], v[150:153], v[174:177], v[120:123]
	v_mfma_f32_16x16x32_bf16 v[116:119], v[142:145], v[182:185], v[116:119]
	v_mfma_f32_16x16x32_bf16 v[112:115], v[150:153], v[182:185], v[112:115]
	v_mfma_f32_16x16x32_bf16 v[100:103], v[142:145], v[190:193], v[100:103]
	v_mfma_f32_16x16x32_bf16 v[96:99], v[150:153], v[190:193], v[96:99]
	v_mfma_f32_16x16x32_bf16 v[84:87], v[142:145], v[198:201], v[84:87]
	v_mfma_f32_16x16x32_bf16 v[80:83], v[150:153], v[198:201], v[80:83]
	v_mfma_f32_16x16x32_bf16 v[124:127], v[146:149], v[178:181], v[124:127]
	v_mfma_f32_16x16x32_bf16 v[120:123], v[154:157], v[178:181], v[120:123]
	v_mfma_f32_16x16x32_bf16 v[116:119], v[146:149], v[186:189], v[116:119]
	v_mfma_f32_16x16x32_bf16 v[112:115], v[154:157], v[186:189], v[112:115]
	v_mfma_f32_16x16x32_bf16 v[100:103], v[146:149], v[194:197], v[100:103]
	v_mfma_f32_16x16x32_bf16 v[96:99], v[154:157], v[194:197], v[96:99]
	v_mfma_f32_16x16x32_bf16 v[84:87], v[146:149], v[202:205], v[84:87]
	v_mfma_f32_16x16x32_bf16 v[80:83], v[154:157], v[202:205], v[80:83]
	v_mfma_f32_16x16x32_bf16 v[108:111], v[158:161], v[174:177], v[108:111]
	v_mfma_f32_16x16x32_bf16 v[104:107], v[166:169], v[174:177], v[104:107]
	v_mfma_f32_16x16x32_bf16 v[92:95], v[158:161], v[182:185], v[92:95]
	v_mfma_f32_16x16x32_bf16 v[88:91], v[166:169], v[182:185], v[88:91]
	v_mfma_f32_16x16x32_bf16 v[76:79], v[158:161], v[190:193], v[76:79]
	v_mfma_f32_16x16x32_bf16 v[72:75], v[166:169], v[190:193], v[72:75]
	v_mfma_f32_16x16x32_bf16 v[68:71], v[158:161], v[198:201], v[68:71]
	v_mfma_f32_16x16x32_bf16 v[64:67], v[166:169], v[198:201], v[64:67]
	v_mfma_f32_16x16x32_bf16 v[108:111], v[162:165], v[178:181], v[108:111]
	v_mfma_f32_16x16x32_bf16 v[104:107], v[170:173], v[178:181], v[104:107]
	v_mfma_f32_16x16x32_bf16 v[92:95], v[162:165], v[186:189], v[92:95]
	v_mfma_f32_16x16x32_bf16 v[88:91], v[170:173], v[186:189], v[88:91]
	v_mfma_f32_16x16x32_bf16 v[76:79], v[162:165], v[194:197], v[76:79]
	v_mfma_f32_16x16x32_bf16 v[72:75], v[170:173], v[194:197], v[72:75]
	v_mfma_f32_16x16x32_bf16 v[68:71], v[162:165], v[202:205], v[68:71]
	v_mfma_f32_16x16x32_bf16 v[64:67], v[170:173], v[202:205], v[64:67]
	s_barrier
	s_add_i32 s83, s74, s66
	v_lshl_add_u64 v[206:207], s[84:85], 0, v[130:131]
	s_mov_b32 m0, s83
	ds_read_b128 v[174:177], v140 offset:16384
	ds_read_b128 v[178:181], v140 offset:17408
	ds_read_b128 v[182:185], v140 offset:18432
	ds_read_b128 v[186:189], v140 offset:19456
	ds_read_b128 v[190:193], v140 offset:20480
	ds_read_b128 v[194:197], v140 offset:21504
	ds_read_b128 v[198:201], v140 offset:22528
	ds_read_b128 v[202:205], v140 offset:23552
	global_load_lds_dwordx4 v[206:207], off
	v_lshl_add_u64 v[208:209], v[206:207], 0, s[6:7]
	s_add_i32 m0, s83, 0x2000
	s_add_i32 s83, s75, s66
	global_load_lds_dwordx4 v[208:209], off
	v_lshl_add_u64 v[208:209], v[206:207], 0, s[8:9]
	s_mov_b32 m0, s83
	s_nop 0
	global_load_lds_dwordx4 v[208:209], off
	v_lshl_add_u64 v[208:209], v[206:207], 0, s[12:13]
	s_add_i32 m0, s83, 0x2000
	s_nop 0
	global_load_lds_dwordx4 v[208:209], off
	v_lshl_add_u64 v[208:209], s[60:61], 0, v[128:129]
	s_mov_b32 m0, s67
	v_lshl_add_u64 v[210:211], v[208:209], 0, s[6:7]
	global_load_lds_dwordx4 v[208:209], off
	s_mov_b32 m0, s68
	s_nop 0
	global_load_lds_dwordx4 v[210:211], off
	s_waitcnt vmcnt(8)
	s_waitcnt lgkmcnt(0)
	s_barrier
	s_waitcnt lgkmcnt(0)
	v_mfma_f32_16x16x32_bf16 v[60:63], v[142:145], v[174:177], v[60:63]
	v_mfma_f32_16x16x32_bf16 v[56:59], v[150:153], v[174:177], v[56:59]
	v_mfma_f32_16x16x32_bf16 v[52:55], v[142:145], v[182:185], v[52:55]
	v_mfma_f32_16x16x32_bf16 v[48:51], v[150:153], v[182:185], v[48:51]
	v_mfma_f32_16x16x32_bf16 v[36:39], v[142:145], v[190:193], v[36:39]
	v_mfma_f32_16x16x32_bf16 v[32:35], v[150:153], v[190:193], v[32:35]
	v_mfma_f32_16x16x32_bf16 v[20:23], v[142:145], v[198:201], v[20:23]
	v_mfma_f32_16x16x32_bf16 v[16:19], v[150:153], v[198:201], v[16:19]
	v_mfma_f32_16x16x32_bf16 v[60:63], v[146:149], v[178:181], v[60:63]
	v_mfma_f32_16x16x32_bf16 v[56:59], v[154:157], v[178:181], v[56:59]
	v_mfma_f32_16x16x32_bf16 v[52:55], v[146:149], v[186:189], v[52:55]
	v_mfma_f32_16x16x32_bf16 v[48:51], v[154:157], v[186:189], v[48:51]
	v_mfma_f32_16x16x32_bf16 v[36:39], v[146:149], v[194:197], v[36:39]
	v_mfma_f32_16x16x32_bf16 v[32:35], v[154:157], v[194:197], v[32:35]
	v_mfma_f32_16x16x32_bf16 v[20:23], v[146:149], v[202:205], v[20:23]
	v_mfma_f32_16x16x32_bf16 v[16:19], v[154:157], v[202:205], v[16:19]
	v_mfma_f32_16x16x32_bf16 v[44:47], v[158:161], v[174:177], v[44:47]
	v_mfma_f32_16x16x32_bf16 v[40:43], v[166:169], v[174:177], v[40:43]
	v_mfma_f32_16x16x32_bf16 v[28:31], v[158:161], v[182:185], v[28:31]
	v_mfma_f32_16x16x32_bf16 v[24:27], v[166:169], v[182:185], v[24:27]
	v_mfma_f32_16x16x32_bf16 v[12:15], v[158:161], v[190:193], v[12:15]
	v_mfma_f32_16x16x32_bf16 v[8:11], v[166:169], v[190:193], v[8:11]
	v_mfma_f32_16x16x32_bf16 v[4:7], v[158:161], v[198:201], v[4:7]
	v_mfma_f32_16x16x32_bf16 v[0:3], v[166:169], v[198:201], v[0:3]
	v_mfma_f32_16x16x32_bf16 v[44:47], v[162:165], v[178:181], v[44:47]
	v_mfma_f32_16x16x32_bf16 v[40:43], v[170:173], v[178:181], v[40:43]
	v_mfma_f32_16x16x32_bf16 v[28:31], v[162:165], v[186:189], v[28:31]
	v_mfma_f32_16x16x32_bf16 v[24:27], v[170:173], v[186:189], v[24:27]
	v_mfma_f32_16x16x32_bf16 v[12:15], v[162:165], v[194:197], v[12:15]
	v_mfma_f32_16x16x32_bf16 v[8:11], v[170:173], v[194:197], v[8:11]
	v_mfma_f32_16x16x32_bf16 v[4:7], v[162:165], v[202:205], v[4:7]
	v_mfma_f32_16x16x32_bf16 v[0:3], v[170:173], v[202:205], v[0:3]
	s_barrier
	s_add_i32 s60, 0, 0x18000
	v_add_u32_e32 v141, s60, v136
	s_add_i32 s61, 0, 0x1c000
	ds_read_b128 v[142:145], v141
	ds_read_b128 v[146:149], v141 offset:1024
	ds_read_b128 v[150:153], v141 offset:2048
	ds_read_b128 v[154:157], v141 offset:3072
	v_add_u32_e32 v141, s61, v136
	ds_read_b128 v[158:161], v141
	ds_read_b128 v[162:165], v141 offset:1024
	ds_read_b128 v[166:169], v141 offset:2048
	ds_read_b128 v[170:173], v141 offset:3072
	s_mov_b32 m0, s69
	v_lshl_add_u64 v[210:211], v[208:209], 0, s[8:9]
	ds_read_b128 v[174:177], v140 offset:32768
	ds_read_b128 v[178:181], v140 offset:33792
	ds_read_b128 v[182:185], v140 offset:34816
	ds_read_b128 v[186:189], v140 offset:35840
	ds_read_b128 v[190:193], v140 offset:36864
	ds_read_b128 v[194:197], v140 offset:37888
	ds_read_b128 v[198:201], v140 offset:38912
	ds_read_b128 v[202:205], v140 offset:39936
	global_load_lds_dwordx4 v[210:211], off
	v_lshl_add_u64 v[210:211], v[208:209], 0, s[12:13]
	s_mov_b32 m0, s70
	s_nop 0
	global_load_lds_dwordx4 v[210:211], off
	s_waitcnt vmcnt(8)
	s_waitcnt lgkmcnt(0)
	s_barrier
	s_waitcnt lgkmcnt(0)
	v_mfma_f32_16x16x32_bf16 v[124:127], v[142:145], v[174:177], v[124:127]
	v_mfma_f32_16x16x32_bf16 v[120:123], v[150:153], v[174:177], v[120:123]
	v_mfma_f32_16x16x32_bf16 v[116:119], v[142:145], v[182:185], v[116:119]
	v_mfma_f32_16x16x32_bf16 v[112:115], v[150:153], v[182:185], v[112:115]
	v_mfma_f32_16x16x32_bf16 v[100:103], v[142:145], v[190:193], v[100:103]
	v_mfma_f32_16x16x32_bf16 v[96:99], v[150:153], v[190:193], v[96:99]
	v_mfma_f32_16x16x32_bf16 v[84:87], v[142:145], v[198:201], v[84:87]
	v_mfma_f32_16x16x32_bf16 v[80:83], v[150:153], v[198:201], v[80:83]
	v_mfma_f32_16x16x32_bf16 v[124:127], v[146:149], v[178:181], v[124:127]
	v_mfma_f32_16x16x32_bf16 v[120:123], v[154:157], v[178:181], v[120:123]
	v_mfma_f32_16x16x32_bf16 v[116:119], v[146:149], v[186:189], v[116:119]
	v_mfma_f32_16x16x32_bf16 v[112:115], v[154:157], v[186:189], v[112:115]
	v_mfma_f32_16x16x32_bf16 v[100:103], v[146:149], v[194:197], v[100:103]
	v_mfma_f32_16x16x32_bf16 v[96:99], v[154:157], v[194:197], v[96:99]
	v_mfma_f32_16x16x32_bf16 v[84:87], v[146:149], v[202:205], v[84:87]
	v_mfma_f32_16x16x32_bf16 v[80:83], v[154:157], v[202:205], v[80:83]
	v_mfma_f32_16x16x32_bf16 v[108:111], v[158:161], v[174:177], v[108:111]
	v_mfma_f32_16x16x32_bf16 v[104:107], v[166:169], v[174:177], v[104:107]
	v_mfma_f32_16x16x32_bf16 v[92:95], v[158:161], v[182:185], v[92:95]
	v_mfma_f32_16x16x32_bf16 v[88:91], v[166:169], v[182:185], v[88:91]
	v_mfma_f32_16x16x32_bf16 v[76:79], v[158:161], v[190:193], v[76:79]
	v_mfma_f32_16x16x32_bf16 v[72:75], v[166:169], v[190:193], v[72:75]
	v_mfma_f32_16x16x32_bf16 v[68:71], v[158:161], v[198:201], v[68:71]
	v_mfma_f32_16x16x32_bf16 v[64:67], v[166:169], v[198:201], v[64:67]
	v_mfma_f32_16x16x32_bf16 v[108:111], v[162:165], v[178:181], v[108:111]
	v_mfma_f32_16x16x32_bf16 v[104:107], v[170:173], v[178:181], v[104:107]
	v_mfma_f32_16x16x32_bf16 v[92:95], v[162:165], v[186:189], v[92:95]
	v_mfma_f32_16x16x32_bf16 v[88:91], v[170:173], v[186:189], v[88:91]
	v_mfma_f32_16x16x32_bf16 v[76:79], v[162:165], v[194:197], v[76:79]
	v_mfma_f32_16x16x32_bf16 v[72:75], v[170:173], v[194:197], v[72:75]
	v_mfma_f32_16x16x32_bf16 v[68:71], v[162:165], v[202:205], v[68:71]
	v_mfma_f32_16x16x32_bf16 v[64:67], v[170:173], v[202:205], v[64:67]
	s_barrier
	s_add_i32 s60, s60, s66
	v_lshl_add_u64 v[210:211], v[206:207], 0, s[18:19]
	s_mov_b32 m0, s60
	ds_read_b128 v[174:177], v140 offset:49152
	ds_read_b128 v[178:181], v140 offset:50176
	ds_read_b128 v[182:185], v140 offset:51200
	ds_read_b128 v[186:189], v140 offset:52224
	ds_read_b128 v[190:193], v140 offset:53248
	ds_read_b128 v[194:197], v140 offset:54272
	ds_read_b128 v[198:201], v140 offset:55296
	ds_read_b128 v[202:205], v140 offset:56320
	global_load_lds_dwordx4 v[210:211], off
	v_lshl_add_u64 v[210:211], v[206:207], 0, s[22:23]
	s_add_i32 m0, s60, 0x2000
	s_add_i32 s60, s61, s66
	global_load_lds_dwordx4 v[210:211], off
	v_lshl_add_u64 v[210:211], v[206:207], 0, s[24:25]
	s_mov_b32 m0, s60
	v_lshl_add_u64 v[206:207], v[206:207], 0, s[28:29]
	global_load_lds_dwordx4 v[210:211], off
	s_add_i32 m0, s60, 0x2000
	s_nop 0
	global_load_lds_dwordx4 v[206:207], off
	v_lshl_add_u64 v[206:207], v[208:209], 0, s[18:19]
	s_mov_b32 m0, s71
	s_nop 0
	global_load_lds_dwordx4 v[206:207], off
	v_lshl_add_u64 v[206:207], v[208:209], 0, s[22:23]
	s_mov_b32 m0, s72
	s_nop 0
	global_load_lds_dwordx4 v[206:207], off
	s_waitcnt vmcnt(8)
	s_waitcnt lgkmcnt(0)
	s_barrier
	s_waitcnt lgkmcnt(0)
	v_mfma_f32_16x16x32_bf16 v[60:63], v[142:145], v[174:177], v[60:63]
	v_mfma_f32_16x16x32_bf16 v[56:59], v[150:153], v[174:177], v[56:59]
	v_mfma_f32_16x16x32_bf16 v[52:55], v[142:145], v[182:185], v[52:55]
	v_mfma_f32_16x16x32_bf16 v[48:51], v[150:153], v[182:185], v[48:51]
	v_mfma_f32_16x16x32_bf16 v[36:39], v[142:145], v[190:193], v[36:39]
	v_mfma_f32_16x16x32_bf16 v[32:35], v[150:153], v[190:193], v[32:35]
	v_mfma_f32_16x16x32_bf16 v[20:23], v[142:145], v[198:201], v[20:23]
	v_mfma_f32_16x16x32_bf16 v[16:19], v[150:153], v[198:201], v[16:19]
	v_mfma_f32_16x16x32_bf16 v[60:63], v[146:149], v[178:181], v[60:63]
	v_mfma_f32_16x16x32_bf16 v[56:59], v[154:157], v[178:181], v[56:59]
	v_mfma_f32_16x16x32_bf16 v[52:55], v[146:149], v[186:189], v[52:55]
	v_mfma_f32_16x16x32_bf16 v[48:51], v[154:157], v[186:189], v[48:51]
	v_mfma_f32_16x16x32_bf16 v[36:39], v[146:149], v[194:197], v[36:39]
	v_mfma_f32_16x16x32_bf16 v[32:35], v[154:157], v[194:197], v[32:35]
	v_mfma_f32_16x16x32_bf16 v[20:23], v[146:149], v[202:205], v[20:23]
	v_mfma_f32_16x16x32_bf16 v[16:19], v[154:157], v[202:205], v[16:19]
	v_mfma_f32_16x16x32_bf16 v[44:47], v[158:161], v[174:177], v[44:47]
	v_mfma_f32_16x16x32_bf16 v[40:43], v[166:169], v[174:177], v[40:43]
	v_mfma_f32_16x16x32_bf16 v[28:31], v[158:161], v[182:185], v[28:31]
	v_mfma_f32_16x16x32_bf16 v[24:27], v[166:169], v[182:185], v[24:27]
	v_mfma_f32_16x16x32_bf16 v[12:15], v[158:161], v[190:193], v[12:15]
	v_mfma_f32_16x16x32_bf16 v[8:11], v[166:169], v[190:193], v[8:11]
	v_mfma_f32_16x16x32_bf16 v[4:7], v[158:161], v[198:201], v[4:7]
	v_mfma_f32_16x16x32_bf16 v[0:3], v[166:169], v[198:201], v[0:3]
	v_mfma_f32_16x16x32_bf16 v[44:47], v[162:165], v[178:181], v[44:47]
	v_mfma_f32_16x16x32_bf16 v[40:43], v[170:173], v[178:181], v[40:43]
	v_mfma_f32_16x16x32_bf16 v[28:31], v[162:165], v[186:189], v[28:31]
	v_mfma_f32_16x16x32_bf16 v[24:27], v[170:173], v[186:189], v[24:27]
	v_mfma_f32_16x16x32_bf16 v[12:15], v[162:165], v[194:197], v[12:15]
	v_mfma_f32_16x16x32_bf16 v[8:11], v[170:173], v[194:197], v[8:11]
	v_mfma_f32_16x16x32_bf16 v[4:7], v[162:165], v[202:205], v[4:7]
	v_mfma_f32_16x16x32_bf16 v[0:3], v[170:173], v[202:205], v[0:3]
	s_barrier
	s_add_i32 s82, s82, 2
	s_add_u32 s50, s50, 0x100
	s_addc_u32 s51, s51, 0
	s_add_u32 s2, s2, 0x100
	s_addc_u32 s3, s3, 0
	s_cmp_gt_u32 s82, 13
	s_cbranch_scc0 .LBB0_416
	s_and_b64 vcc, exec, s[30:31]
	s_cbranch_vccz .LBB0_419
	s_barrier

.LBB0_432:
	ds_read_b128 v[142:145], v138
	ds_read_b128 v[146:149], v138 offset:1024
	ds_read_b128 v[150:153], v138 offset:2048
	ds_read_b128 v[154:157], v138 offset:3072
	ds_read_b128 v[158:161], v139
	ds_read_b128 v[162:165], v139 offset:1024
	ds_read_b128 v[166:169], v139 offset:2048
	ds_read_b128 v[170:173], v139 offset:3072
	s_add_u32 s60, s48, 0xfffc0080
	s_addc_u32 s61, s49, -1
	s_cmp_eq_u32 s74, 12
	s_cselect_b32 s61, s26, s61
	s_cselect_b32 s60, s27, s60
	s_cselect_b32 s77, s39, s3
	s_cselect_b32 s76, s41, s2
	v_lshl_add_u64 v[206:207], s[48:49], 0, v[132:133]
	s_add_i32 m0, s56, 0xc000
	ds_read_b128 v[174:177], v140
	ds_read_b128 v[178:181], v140 offset:1024
	ds_read_b128 v[182:185], v140 offset:2048
	ds_read_b128 v[186:189], v140 offset:3072
	ds_read_b128 v[190:193], v140 offset:4096
	ds_read_b128 v[194:197], v140 offset:5120
	ds_read_b128 v[198:201], v140 offset:6144
	ds_read_b128 v[202:205], v140 offset:7168
	global_load_lds_dwordx4 v[206:207], off
	v_lshl_add_u64 v[206:207], v[206:207], 0, s[6:7]
	s_add_i32 m0, s56, 0xe000
	s_nop 0
	global_load_lds_dwordx4 v[206:207], off
	s_waitcnt vmcnt(8)
	s_waitcnt lgkmcnt(0)
	s_barrier
	s_waitcnt lgkmcnt(0)
	v_mfma_f32_16x16x32_bf16 v[124:127], v[142:145], v[174:177], v[124:127]
	v_mfma_f32_16x16x32_bf16 v[120:123], v[150:153], v[174:177], v[120:123]
	v_mfma_f32_16x16x32_bf16 v[116:119], v[142:145], v[182:185], v[116:119]
	v_mfma_f32_16x16x32_bf16 v[112:115], v[150:153], v[182:185], v[112:115]
	v_mfma_f32_16x16x32_bf16 v[100:103], v[142:145], v[190:193], v[100:103]
	v_mfma_f32_16x16x32_bf16 v[96:99], v[150:153], v[190:193], v[96:99]
	v_mfma_f32_16x16x32_bf16 v[84:87], v[142:145], v[198:201], v[84:87]
	v_mfma_f32_16x16x32_bf16 v[80:83], v[150:153], v[198:201], v[80:83]
	v_mfma_f32_16x16x32_bf16 v[124:127], v[146:149], v[178:181], v[124:127]
	v_mfma_f32_16x16x32_bf16 v[120:123], v[154:157], v[178:181], v[120:123]
	v_mfma_f32_16x16x32_bf16 v[116:119], v[146:149], v[186:189], v[116:119]
	v_mfma_f32_16x16x32_bf16 v[112:115], v[154:157], v[186:189], v[112:115]
	v_mfma_f32_16x16x32_bf16 v[100:103], v[146:149], v[194:197], v[100:103]
	v_mfma_f32_16x16x32_bf16 v[96:99], v[154:157], v[194:197], v[96:99]
	v_mfma_f32_16x16x32_bf16 v[84:87], v[146:149], v[202:205], v[84:87]
	v_mfma_f32_16x16x32_bf16 v[80:83], v[154:157], v[202:205], v[80:83]
	v_mfma_f32_16x16x32_bf16 v[108:111], v[158:161], v[174:177], v[108:111]
	v_mfma_f32_16x16x32_bf16 v[104:107], v[166:169], v[174:177], v[104:107]
	v_mfma_f32_16x16x32_bf16 v[92:95], v[158:161], v[182:185], v[92:95]
	v_mfma_f32_16x16x32_bf16 v[88:91], v[166:169], v[182:185], v[88:91]
	v_mfma_f32_16x16x32_bf16 v[76:79], v[158:161], v[190:193], v[76:79]
	v_mfma_f32_16x16x32_bf16 v[72:75], v[166:169], v[190:193], v[72:75]
	v_mfma_f32_16x16x32_bf16 v[68:71], v[158:161], v[198:201], v[68:71]
	v_mfma_f32_16x16x32_bf16 v[64:67], v[166:169], v[198:201], v[64:67]
	v_mfma_f32_16x16x32_bf16 v[108:111], v[162:165], v[178:181], v[108:111]
	v_mfma_f32_16x16x32_bf16 v[104:107], v[170:173], v[178:181], v[104:107]
	v_mfma_f32_16x16x32_bf16 v[92:95], v[162:165], v[186:189], v[92:95]
	v_mfma_f32_16x16x32_bf16 v[88:91], v[170:173], v[186:189], v[88:91]
	v_mfma_f32_16x16x32_bf16 v[76:79], v[162:165], v[194:197], v[76:79]
	v_mfma_f32_16x16x32_bf16 v[72:75], v[170:173], v[194:197], v[72:75]
	v_mfma_f32_16x16x32_bf16 v[68:71], v[162:165], v[202:205], v[68:71]
	v_mfma_f32_16x16x32_bf16 v[64:67], v[170:173], v[202:205], v[64:67]
	s_barrier
	s_add_i32 s75, s68, s58
	v_lshl_add_u64 v[206:207], s[76:77], 0, v[130:131]
	s_mov_b32 m0, s75
	ds_read_b128 v[174:177], v140 offset:16384
	ds_read_b128 v[178:181], v140 offset:17408
	ds_read_b128 v[182:185], v140 offset:18432
	ds_read_b128 v[186:189], v140 offset:19456
	ds_read_b128 v[190:193], v140 offset:20480
	ds_read_b128 v[194:197], v140 offset:21504
	ds_read_b128 v[198:201], v140 offset:22528
	ds_read_b128 v[202:205], v140 offset:23552
	global_load_lds_dwordx4 v[206:207], off
	v_lshl_add_u64 v[208:209], v[206:207], 0, s[6:7]
	s_add_i32 m0, s75, 0x2000
	s_add_i32 s75, s69, s58
	global_load_lds_dwordx4 v[208:209], off
	v_lshl_add_u64 v[208:209], v[206:207], 0, s[8:9]
	s_mov_b32 m0, s75
	s_nop 0
	global_load_lds_dwordx4 v[208:209], off
	v_lshl_add_u64 v[208:209], v[206:207], 0, s[12:13]
	s_add_i32 m0, s75, 0x2000
	s_nop 0
	global_load_lds_dwordx4 v[208:209], off
	v_lshl_add_u64 v[208:209], s[60:61], 0, v[128:129]
	s_mov_b32 m0, s56
	v_lshl_add_u64 v[210:211], v[208:209], 0, s[6:7]
	global_load_lds_dwordx4 v[208:209], off
	s_mov_b32 m0, s57
	s_nop 0
	global_load_lds_dwordx4 v[210:211], off
	s_waitcnt vmcnt(8)
	s_waitcnt lgkmcnt(0)
	s_barrier
	s_waitcnt lgkmcnt(0)
	v_mfma_f32_16x16x32_bf16 v[60:63], v[142:145], v[174:177], v[60:63]
	v_mfma_f32_16x16x32_bf16 v[56:59], v[150:153], v[174:177], v[56:59]
	v_mfma_f32_16x16x32_bf16 v[52:55], v[142:145], v[182:185], v[52:55]
	v_mfma_f32_16x16x32_bf16 v[48:51], v[150:153], v[182:185], v[48:51]
	v_mfma_f32_16x16x32_bf16 v[36:39], v[142:145], v[190:193], v[36:39]
	v_mfma_f32_16x16x32_bf16 v[32:35], v[150:153], v[190:193], v[32:35]
	v_mfma_f32_16x16x32_bf16 v[20:23], v[142:145], v[198:201], v[20:23]
	v_mfma_f32_16x16x32_bf16 v[16:19], v[150:153], v[198:201], v[16:19]
	v_mfma_f32_16x16x32_bf16 v[60:63], v[146:149], v[178:181], v[60:63]
	v_mfma_f32_16x16x32_bf16 v[56:59], v[154:157], v[178:181], v[56:59]
	v_mfma_f32_16x16x32_bf16 v[52:55], v[146:149], v[186:189], v[52:55]
	v_mfma_f32_16x16x32_bf16 v[48:51], v[154:157], v[186:189], v[48:51]
	v_mfma_f32_16x16x32_bf16 v[36:39], v[146:149], v[194:197], v[36:39]
	v_mfma_f32_16x16x32_bf16 v[32:35], v[154:157], v[194:197], v[32:35]
	v_mfma_f32_16x16x32_bf16 v[20:23], v[146:149], v[202:205], v[20:23]
	v_mfma_f32_16x16x32_bf16 v[16:19], v[154:157], v[202:205], v[16:19]
	v_mfma_f32_16x16x32_bf16 v[44:47], v[158:161], v[174:177], v[44:47]
	v_mfma_f32_16x16x32_bf16 v[40:43], v[166:169], v[174:177], v[40:43]
	v_mfma_f32_16x16x32_bf16 v[28:31], v[158:161], v[182:185], v[28:31]
	v_mfma_f32_16x16x32_bf16 v[24:27], v[166:169], v[182:185], v[24:27]
	v_mfma_f32_16x16x32_bf16 v[12:15], v[158:161], v[190:193], v[12:15]
	v_mfma_f32_16x16x32_bf16 v[8:11], v[166:169], v[190:193], v[8:11]
	v_mfma_f32_16x16x32_bf16 v[4:7], v[158:161], v[198:201], v[4:7]
	v_mfma_f32_16x16x32_bf16 v[0:3], v[166:169], v[198:201], v[0:3]
	v_mfma_f32_16x16x32_bf16 v[44:47], v[162:165], v[178:181], v[44:47]
	v_mfma_f32_16x16x32_bf16 v[40:43], v[170:173], v[178:181], v[40:43]
	v_mfma_f32_16x16x32_bf16 v[28:31], v[162:165], v[186:189], v[28:31]
	v_mfma_f32_16x16x32_bf16 v[24:27], v[170:173], v[186:189], v[24:27]
	v_mfma_f32_16x16x32_bf16 v[12:15], v[162:165], v[194:197], v[12:15]
	v_mfma_f32_16x16x32_bf16 v[8:11], v[170:173], v[194:197], v[8:11]
	v_mfma_f32_16x16x32_bf16 v[4:7], v[162:165], v[202:205], v[4:7]
	v_mfma_f32_16x16x32_bf16 v[0:3], v[170:173], v[202:205], v[0:3]
	s_barrier
	s_add_i32 s60, 0, 0x18000
	v_add_u32_e32 v141, s60, v136
	s_add_i32 s61, 0, 0x1c000
	ds_read_b128 v[142:145], v141
	ds_read_b128 v[146:149], v141 offset:1024
	ds_read_b128 v[150:153], v141 offset:2048
	ds_read_b128 v[154:157], v141 offset:3072
	v_add_u32_e32 v141, s61, v136
	ds_read_b128 v[158:161], v141
	ds_read_b128 v[162:165], v141 offset:1024
	ds_read_b128 v[166:169], v141 offset:2048
	ds_read_b128 v[170:173], v141 offset:3072
	s_mov_b32 m0, s59
	v_lshl_add_u64 v[210:211], v[208:209], 0, s[8:9]
	ds_read_b128 v[174:177], v140 offset:32768
	ds_read_b128 v[178:181], v140 offset:33792
	ds_read_b128 v[182:185], v140 offset:34816
	ds_read_b128 v[186:189], v140 offset:35840
	ds_read_b128 v[190:193], v140 offset:36864
	ds_read_b128 v[194:197], v140 offset:37888
	ds_read_b128 v[198:201], v140 offset:38912
	ds_read_b128 v[202:205], v140 offset:39936
	global_load_lds_dwordx4 v[210:211], off
	v_lshl_add_u64 v[210:211], v[208:209], 0, s[12:13]
	s_mov_b32 m0, s62
	s_nop 0
	global_load_lds_dwordx4 v[210:211], off
	s_waitcnt vmcnt(8)
	s_waitcnt lgkmcnt(0)
	s_barrier
	s_waitcnt lgkmcnt(0)
	v_mfma_f32_16x16x32_bf16 v[124:127], v[142:145], v[174:177], v[124:127]
	v_mfma_f32_16x16x32_bf16 v[120:123], v[150:153], v[174:177], v[120:123]
	v_mfma_f32_16x16x32_bf16 v[116:119], v[142:145], v[182:185], v[116:119]
	v_mfma_f32_16x16x32_bf16 v[112:115], v[150:153], v[182:185], v[112:115]
	v_mfma_f32_16x16x32_bf16 v[100:103], v[142:145], v[190:193], v[100:103]
	v_mfma_f32_16x16x32_bf16 v[96:99], v[150:153], v[190:193], v[96:99]
	v_mfma_f32_16x16x32_bf16 v[84:87], v[142:145], v[198:201], v[84:87]
	v_mfma_f32_16x16x32_bf16 v[80:83], v[150:153], v[198:201], v[80:83]
	v_mfma_f32_16x16x32_bf16 v[124:127], v[146:149], v[178:181], v[124:127]
	v_mfma_f32_16x16x32_bf16 v[120:123], v[154:157], v[178:181], v[120:123]
	v_mfma_f32_16x16x32_bf16 v[116:119], v[146:149], v[186:189], v[116:119]
	v_mfma_f32_16x16x32_bf16 v[112:115], v[154:157], v[186:189], v[112:115]
	v_mfma_f32_16x16x32_bf16 v[100:103], v[146:149], v[194:197], v[100:103]
	v_mfma_f32_16x16x32_bf16 v[96:99], v[154:157], v[194:197], v[96:99]
	v_mfma_f32_16x16x32_bf16 v[84:87], v[146:149], v[202:205], v[84:87]
	v_mfma_f32_16x16x32_bf16 v[80:83], v[154:157], v[202:205], v[80:83]
	v_mfma_f32_16x16x32_bf16 v[108:111], v[158:161], v[174:177], v[108:111]
	v_mfma_f32_16x16x32_bf16 v[104:107], v[166:169], v[174:177], v[104:107]
	v_mfma_f32_16x16x32_bf16 v[92:95], v[158:161], v[182:185], v[92:95]
	v_mfma_f32_16x16x32_bf16 v[88:91], v[166:169], v[182:185], v[88:91]
	v_mfma_f32_16x16x32_bf16 v[76:79], v[158:161], v[190:193], v[76:79]
	v_mfma_f32_16x16x32_bf16 v[72:75], v[166:169], v[190:193], v[72:75]
	v_mfma_f32_16x16x32_bf16 v[68:71], v[158:161], v[198:201], v[68:71]
	v_mfma_f32_16x16x32_bf16 v[64:67], v[166:169], v[198:201], v[64:67]
	v_mfma_f32_16x16x32_bf16 v[108:111], v[162:165], v[178:181], v[108:111]
	v_mfma_f32_16x16x32_bf16 v[104:107], v[170:173], v[178:181], v[104:107]
	v_mfma_f32_16x16x32_bf16 v[92:95], v[162:165], v[186:189], v[92:95]
	v_mfma_f32_16x16x32_bf16 v[88:91], v[170:173], v[186:189], v[88:91]
	v_mfma_f32_16x16x32_bf16 v[76:79], v[162:165], v[194:197], v[76:79]
	v_mfma_f32_16x16x32_bf16 v[72:75], v[170:173], v[194:197], v[72:75]
	v_mfma_f32_16x16x32_bf16 v[68:71], v[162:165], v[202:205], v[68:71]
	v_mfma_f32_16x16x32_bf16 v[64:67], v[170:173], v[202:205], v[64:67]
	s_barrier
	s_add_i32 s60, s60, s58
	v_lshl_add_u64 v[210:211], v[206:207], 0, s[16:17]
	s_mov_b32 m0, s60
	ds_read_b128 v[174:177], v140 offset:49152
	ds_read_b128 v[178:181], v140 offset:50176
	ds_read_b128 v[182:185], v140 offset:51200
	ds_read_b128 v[186:189], v140 offset:52224
	ds_read_b128 v[190:193], v140 offset:53248
	ds_read_b128 v[194:197], v140 offset:54272
	ds_read_b128 v[198:201], v140 offset:55296
	ds_read_b128 v[202:205], v140 offset:56320
	global_load_lds_dwordx4 v[210:211], off
	v_lshl_add_u64 v[210:211], v[206:207], 0, s[18:19]
	s_add_i32 m0, s60, 0x2000
	s_add_i32 s60, s61, s58
	global_load_lds_dwordx4 v[210:211], off
	v_lshl_add_u64 v[210:211], v[206:207], 0, s[22:23]
	s_mov_b32 m0, s60
	v_lshl_add_u64 v[206:207], v[206:207], 0, s[24:25]
	global_load_lds_dwordx4 v[210:211], off
	s_add_i32 m0, s60, 0x2000
	s_nop 0
	global_load_lds_dwordx4 v[206:207], off
	v_lshl_add_u64 v[206:207], v[208:209], 0, s[16:17]
	s_mov_b32 m0, s66
	s_nop 0
	global_load_lds_dwordx4 v[206:207], off
	v_lshl_add_u64 v[206:207], v[208:209], 0, s[18:19]
	s_mov_b32 m0, s67
	s_nop 0
	global_load_lds_dwordx4 v[206:207], off
	s_waitcnt vmcnt(8)
	s_waitcnt lgkmcnt(0)
	s_barrier
	s_waitcnt lgkmcnt(0)
	v_mfma_f32_16x16x32_bf16 v[60:63], v[142:145], v[174:177], v[60:63]
	v_mfma_f32_16x16x32_bf16 v[56:59], v[150:153], v[174:177], v[56:59]
	v_mfma_f32_16x16x32_bf16 v[52:55], v[142:145], v[182:185], v[52:55]
	v_mfma_f32_16x16x32_bf16 v[48:51], v[150:153], v[182:185], v[48:51]
	v_mfma_f32_16x16x32_bf16 v[36:39], v[142:145], v[190:193], v[36:39]
	v_mfma_f32_16x16x32_bf16 v[32:35], v[150:153], v[190:193], v[32:35]
	v_mfma_f32_16x16x32_bf16 v[20:23], v[142:145], v[198:201], v[20:23]
	v_mfma_f32_16x16x32_bf16 v[16:19], v[150:153], v[198:201], v[16:19]
	v_mfma_f32_16x16x32_bf16 v[60:63], v[146:149], v[178:181], v[60:63]
	v_mfma_f32_16x16x32_bf16 v[56:59], v[154:157], v[178:181], v[56:59]
	v_mfma_f32_16x16x32_bf16 v[52:55], v[146:149], v[186:189], v[52:55]
	v_mfma_f32_16x16x32_bf16 v[48:51], v[154:157], v[186:189], v[48:51]
	v_mfma_f32_16x16x32_bf16 v[36:39], v[146:149], v[194:197], v[36:39]
	v_mfma_f32_16x16x32_bf16 v[32:35], v[154:157], v[194:197], v[32:35]
	v_mfma_f32_16x16x32_bf16 v[20:23], v[146:149], v[202:205], v[20:23]
	v_mfma_f32_16x16x32_bf16 v[16:19], v[154:157], v[202:205], v[16:19]
	v_mfma_f32_16x16x32_bf16 v[44:47], v[158:161], v[174:177], v[44:47]
	v_mfma_f32_16x16x32_bf16 v[40:43], v[166:169], v[174:177], v[40:43]
	v_mfma_f32_16x16x32_bf16 v[28:31], v[158:161], v[182:185], v[28:31]
	v_mfma_f32_16x16x32_bf16 v[24:27], v[166:169], v[182:185], v[24:27]
	v_mfma_f32_16x16x32_bf16 v[12:15], v[158:161], v[190:193], v[12:15]
	v_mfma_f32_16x16x32_bf16 v[8:11], v[166:169], v[190:193], v[8:11]
	v_mfma_f32_16x16x32_bf16 v[4:7], v[158:161], v[198:201], v[4:7]
	v_mfma_f32_16x16x32_bf16 v[0:3], v[166:169], v[198:201], v[0:3]
	v_mfma_f32_16x16x32_bf16 v[44:47], v[162:165], v[178:181], v[44:47]
	v_mfma_f32_16x16x32_bf16 v[40:43], v[170:173], v[178:181], v[40:43]
	v_mfma_f32_16x16x32_bf16 v[28:31], v[162:165], v[186:189], v[28:31]
	v_mfma_f32_16x16x32_bf16 v[24:27], v[170:173], v[186:189], v[24:27]
	v_mfma_f32_16x16x32_bf16 v[12:15], v[162:165], v[194:197], v[12:15]
	v_mfma_f32_16x16x32_bf16 v[8:11], v[170:173], v[194:197], v[8:11]
	v_mfma_f32_16x16x32_bf16 v[4:7], v[162:165], v[202:205], v[4:7]
	v_mfma_f32_16x16x32_bf16 v[0:3], v[170:173], v[202:205], v[0:3]
	s_barrier
	s_add_i32 s74, s74, 2
	s_add_u32 s48, s48, 0x100
	s_addc_u32 s49, s49, 0
	s_add_u32 s2, s2, 0x100
	s_addc_u32 s3, s3, 0
	s_cmp_gt_u32 s74, 13
	s_cbranch_scc0 .LBB0_432
	s_and_b64 vcc, exec, s[28:29]
	s_cbranch_vccz .LBB0_435
	s_barrier

.LBB0_505:
	s_add_u32 s58, s50, s49
	s_addc_u32 s59, s51, 0
	ds_read_b128 v[146:149], v157
	ds_read_b128 v[150:153], v157 offset:1024
	ds_read_b128 v[162:165], v157 offset:2048
	ds_read_b128 v[166:169], v157 offset:3072
	ds_read_b128 v[170:173], v158
	ds_read_b128 v[174:177], v158 offset:1024
	ds_read_b128 v[178:181], v158 offset:2048
	ds_read_b128 v[182:185], v158 offset:3072
	s_add_u32 s60, s58, 0x100
	s_addc_u32 s61, s59, 0
	s_and_b64 s[56:57], s[2:3], exec
	s_cselect_b32 s56, s33, s60
	s_cselect_b32 s57, s7, s61
	s_add_u32 s49, s52, s49
	s_addc_u32 s60, s53, 0
	s_add_u32 s49, s49, 0x100
	s_addc_u32 s60, s60, 0
	s_and_b64 s[2:3], s[2:3], exec
	s_cselect_b32 s2, s43, s49
	s_cselect_b32 s3, s41, s60
	s_add_i32 s61, 0, 0x18000
	s_add_i32 s60, 0, 0x1c000
	s_add_i32 s80, s75, s66
	s_add_i32 s78, s76, s66
	s_add_i32 s49, s61, s66
	s_add_i32 s82, s60, s66
	s_add_i32 m0, s67, 0xc000
	s_add_i32 s84, s67, 0xe000
	s_add_i32 s79, s80, 0x2000
	s_add_i32 s62, s78, 0x2000
	s_add_i32 s83, s49, 0x2000
	s_add_i32 s81, s82, 0x2000
	v_lshl_add_u64 v[218:219], s[58:59], 0, v[128:129]
	v_lshl_add_u64 v[220:221], v[218:219], 0, s[30:31]
	ds_read_b128 v[186:189], v159
	ds_read_b128 v[190:193], v159 offset:1024
	ds_read_b128 v[194:197], v159 offset:2048
	ds_read_b128 v[198:201], v159 offset:3072
	ds_read_b128 v[202:205], v159 offset:4096
	ds_read_b128 v[206:209], v159 offset:5120
	ds_read_b128 v[210:213], v159 offset:6144
	ds_read_b128 v[214:217], v159 offset:7168
	global_load_lds_dwordx4 v[220:221], off
	v_lshl_add_u64 v[218:219], v[218:219], 0, s[34:35]
	s_mov_b32 m0, s84
	s_nop 0
	global_load_lds_dwordx4 v[218:219], off
	s_waitcnt vmcnt(8)
	s_waitcnt lgkmcnt(0)
	s_barrier
	s_waitcnt lgkmcnt(0)
	v_mfma_f32_16x16x32_bf16 v[124:127], v[146:149], v[186:189], v[124:127]
	v_mfma_f32_16x16x32_bf16 v[120:123], v[162:165], v[186:189], v[120:123]
	v_mfma_f32_16x16x32_bf16 v[116:119], v[146:149], v[194:197], v[116:119]
	v_mfma_f32_16x16x32_bf16 v[112:115], v[162:165], v[194:197], v[112:115]
	v_mfma_f32_16x16x32_bf16 v[108:111], v[146:149], v[202:205], v[108:111]
	v_mfma_f32_16x16x32_bf16 v[104:107], v[162:165], v[202:205], v[104:107]
	v_mfma_f32_16x16x32_bf16 v[100:103], v[146:149], v[210:213], v[100:103]
	v_mfma_f32_16x16x32_bf16 v[96:99], v[162:165], v[210:213], v[96:99]
	v_mfma_f32_16x16x32_bf16 v[124:127], v[150:153], v[190:193], v[124:127]
	v_mfma_f32_16x16x32_bf16 v[120:123], v[166:169], v[190:193], v[120:123]
	v_mfma_f32_16x16x32_bf16 v[116:119], v[150:153], v[198:201], v[116:119]
	v_mfma_f32_16x16x32_bf16 v[112:115], v[166:169], v[198:201], v[112:115]
	v_mfma_f32_16x16x32_bf16 v[108:111], v[150:153], v[206:209], v[108:111]
	v_mfma_f32_16x16x32_bf16 v[104:107], v[166:169], v[206:209], v[104:107]
	v_mfma_f32_16x16x32_bf16 v[100:103], v[150:153], v[214:217], v[100:103]
	v_mfma_f32_16x16x32_bf16 v[96:99], v[166:169], v[214:217], v[96:99]
	v_mfma_f32_16x16x32_bf16 v[60:63], v[170:173], v[186:189], v[60:63]
	v_mfma_f32_16x16x32_bf16 v[56:59], v[178:181], v[186:189], v[56:59]
	v_mfma_f32_16x16x32_bf16 v[52:55], v[170:173], v[194:197], v[52:55]
	v_mfma_f32_16x16x32_bf16 v[48:51], v[178:181], v[194:197], v[48:51]
	v_mfma_f32_16x16x32_bf16 v[44:47], v[170:173], v[202:205], v[44:47]
	v_mfma_f32_16x16x32_bf16 v[40:43], v[178:181], v[202:205], v[40:43]
	v_mfma_f32_16x16x32_bf16 v[36:39], v[170:173], v[210:213], v[36:39]
	v_mfma_f32_16x16x32_bf16 v[32:35], v[178:181], v[210:213], v[32:35]
	v_mfma_f32_16x16x32_bf16 v[60:63], v[174:177], v[190:193], v[60:63]
	v_mfma_f32_16x16x32_bf16 v[56:59], v[182:185], v[190:193], v[56:59]
	v_mfma_f32_16x16x32_bf16 v[52:55], v[174:177], v[198:201], v[52:55]
	v_mfma_f32_16x16x32_bf16 v[48:51], v[182:185], v[198:201], v[48:51]
	v_mfma_f32_16x16x32_bf16 v[44:47], v[174:177], v[206:209], v[44:47]
	v_mfma_f32_16x16x32_bf16 v[40:43], v[182:185], v[206:209], v[40:43]
	v_mfma_f32_16x16x32_bf16 v[36:39], v[174:177], v[214:217], v[36:39]
	v_mfma_f32_16x16x32_bf16 v[32:35], v[182:185], v[214:217], v[32:35]
	s_barrier
	s_mov_b32 m0, s80
	v_lshl_add_u64 v[218:219], s[2:3], 0, v[130:131]
	ds_read_b128 v[186:189], v159 offset:16384
	ds_read_b128 v[190:193], v159 offset:17408
	ds_read_b128 v[194:197], v159 offset:18432
	ds_read_b128 v[198:201], v159 offset:19456
	ds_read_b128 v[202:205], v159 offset:20480
	ds_read_b128 v[206:209], v159 offset:21504
	ds_read_b128 v[210:213], v159 offset:22528
	ds_read_b128 v[214:217], v159 offset:23552
	global_load_lds_dwordx4 v[218:219], off
	v_lshl_add_u64 v[220:221], v[218:219], 0, s[12:13]
	s_mov_b32 m0, s79
	s_nop 0
	global_load_lds_dwordx4 v[220:221], off
	v_lshl_add_u64 v[220:221], v[218:219], 0, s[14:15]
	s_mov_b32 m0, s78
	s_nop 0
	global_load_lds_dwordx4 v[220:221], off
	v_lshl_add_u64 v[220:221], v[218:219], 0, s[16:17]
	s_mov_b32 m0, s62
	s_nop 0
	global_load_lds_dwordx4 v[220:221], off
	v_lshl_add_u64 v[220:221], s[56:57], 0, v[128:129]
	s_mov_b32 m0, s67
	v_lshl_add_u64 v[222:223], v[220:221], 0, s[12:13]
	global_load_lds_dwordx4 v[220:221], off
	s_mov_b32 m0, s68
	s_nop 0
	global_load_lds_dwordx4 v[222:223], off
	s_waitcnt vmcnt(8)
	s_waitcnt lgkmcnt(0)
	s_barrier
	s_waitcnt lgkmcnt(0)
	v_mfma_f32_16x16x32_bf16 v[92:95], v[146:149], v[186:189], v[92:95]
	v_mfma_f32_16x16x32_bf16 v[88:91], v[162:165], v[186:189], v[88:91]
	v_mfma_f32_16x16x32_bf16 v[84:87], v[146:149], v[194:197], v[84:87]
	v_mfma_f32_16x16x32_bf16 v[80:83], v[162:165], v[194:197], v[80:83]
	v_mfma_f32_16x16x32_bf16 v[76:79], v[146:149], v[202:205], v[76:79]
	v_mfma_f32_16x16x32_bf16 v[72:75], v[162:165], v[202:205], v[72:75]
	v_mfma_f32_16x16x32_bf16 v[68:71], v[146:149], v[210:213], v[68:71]
	v_mfma_f32_16x16x32_bf16 v[64:67], v[162:165], v[210:213], v[64:67]
	v_mfma_f32_16x16x32_bf16 v[92:95], v[150:153], v[190:193], v[92:95]
	v_mfma_f32_16x16x32_bf16 v[88:91], v[166:169], v[190:193], v[88:91]
	v_mfma_f32_16x16x32_bf16 v[84:87], v[150:153], v[198:201], v[84:87]
	v_mfma_f32_16x16x32_bf16 v[80:83], v[166:169], v[198:201], v[80:83]
	v_mfma_f32_16x16x32_bf16 v[76:79], v[150:153], v[206:209], v[76:79]
	v_mfma_f32_16x16x32_bf16 v[72:75], v[166:169], v[206:209], v[72:75]
	v_mfma_f32_16x16x32_bf16 v[68:71], v[150:153], v[214:217], v[68:71]
	v_mfma_f32_16x16x32_bf16 v[64:67], v[166:169], v[214:217], v[64:67]
	v_mfma_f32_16x16x32_bf16 v[28:31], v[170:173], v[186:189], v[28:31]
	v_mfma_f32_16x16x32_bf16 v[24:27], v[178:181], v[186:189], v[24:27]
	v_mfma_f32_16x16x32_bf16 v[20:23], v[170:173], v[194:197], v[20:23]
	v_mfma_f32_16x16x32_bf16 v[16:19], v[178:181], v[194:197], v[16:19]
	v_mfma_f32_16x16x32_bf16 v[12:15], v[170:173], v[202:205], v[12:15]
	v_mfma_f32_16x16x32_bf16 v[8:11], v[178:181], v[202:205], v[8:11]
	v_mfma_f32_16x16x32_bf16 v[4:7], v[170:173], v[210:213], v[4:7]
	v_mfma_f32_16x16x32_bf16 v[0:3], v[178:181], v[210:213], v[0:3]
	v_mfma_f32_16x16x32_bf16 v[28:31], v[174:177], v[190:193], v[28:31]
	v_mfma_f32_16x16x32_bf16 v[24:27], v[182:185], v[190:193], v[24:27]
	v_mfma_f32_16x16x32_bf16 v[20:23], v[174:177], v[198:201], v[20:23]
	v_mfma_f32_16x16x32_bf16 v[16:19], v[182:185], v[198:201], v[16:19]
	v_mfma_f32_16x16x32_bf16 v[12:15], v[174:177], v[206:209], v[12:15]
	v_mfma_f32_16x16x32_bf16 v[8:11], v[182:185], v[206:209], v[8:11]
	v_mfma_f32_16x16x32_bf16 v[4:7], v[174:177], v[214:217], v[4:7]
	v_mfma_f32_16x16x32_bf16 v[0:3], v[182:185], v[214:217], v[0:3]
	s_barrier
	v_add_u32_e32 v161, s61, v156
	ds_read_b128 v[146:149], v161
	ds_read_b128 v[150:153], v161 offset:1024
	ds_read_b128 v[162:165], v161 offset:2048
	ds_read_b128 v[166:169], v161 offset:3072
	v_add_u32_e32 v161, s60, v156
	ds_read_b128 v[170:173], v161
	ds_read_b128 v[174:177], v161 offset:1024
	ds_read_b128 v[178:181], v161 offset:2048
	ds_read_b128 v[182:185], v161 offset:3072
	s_mov_b32 m0, s69
	v_lshl_add_u64 v[222:223], v[220:221], 0, s[14:15]
	ds_read_b128 v[186:189], v159 offset:32768
	ds_read_b128 v[190:193], v159 offset:33792
	ds_read_b128 v[194:197], v159 offset:34816
	ds_read_b128 v[198:201], v159 offset:35840
	ds_read_b128 v[202:205], v159 offset:36864
	ds_read_b128 v[206:209], v159 offset:37888
	ds_read_b128 v[210:213], v159 offset:38912
	ds_read_b128 v[214:217], v159 offset:39936
	global_load_lds_dwordx4 v[222:223], off
	v_lshl_add_u64 v[222:223], v[220:221], 0, s[16:17]
	s_mov_b32 m0, s70
	s_nop 0
	global_load_lds_dwordx4 v[222:223], off
	s_waitcnt vmcnt(8)
	s_waitcnt lgkmcnt(0)
	s_barrier
	s_waitcnt lgkmcnt(0)
	v_mfma_f32_16x16x32_bf16 v[124:127], v[146:149], v[186:189], v[124:127]
	v_mfma_f32_16x16x32_bf16 v[120:123], v[162:165], v[186:189], v[120:123]
	v_mfma_f32_16x16x32_bf16 v[116:119], v[146:149], v[194:197], v[116:119]
	v_mfma_f32_16x16x32_bf16 v[112:115], v[162:165], v[194:197], v[112:115]
	v_mfma_f32_16x16x32_bf16 v[108:111], v[146:149], v[202:205], v[108:111]
	v_mfma_f32_16x16x32_bf16 v[104:107], v[162:165], v[202:205], v[104:107]
	v_mfma_f32_16x16x32_bf16 v[100:103], v[146:149], v[210:213], v[100:103]
	v_mfma_f32_16x16x32_bf16 v[96:99], v[162:165], v[210:213], v[96:99]
	v_mfma_f32_16x16x32_bf16 v[124:127], v[150:153], v[190:193], v[124:127]
	v_mfma_f32_16x16x32_bf16 v[120:123], v[166:169], v[190:193], v[120:123]
	v_mfma_f32_16x16x32_bf16 v[116:119], v[150:153], v[198:201], v[116:119]
	v_mfma_f32_16x16x32_bf16 v[112:115], v[166:169], v[198:201], v[112:115]
	v_mfma_f32_16x16x32_bf16 v[108:111], v[150:153], v[206:209], v[108:111]
	v_mfma_f32_16x16x32_bf16 v[104:107], v[166:169], v[206:209], v[104:107]
	v_mfma_f32_16x16x32_bf16 v[100:103], v[150:153], v[214:217], v[100:103]
	v_mfma_f32_16x16x32_bf16 v[96:99], v[166:169], v[214:217], v[96:99]
	v_mfma_f32_16x16x32_bf16 v[60:63], v[170:173], v[186:189], v[60:63]
	v_mfma_f32_16x16x32_bf16 v[56:59], v[178:181], v[186:189], v[56:59]
	v_mfma_f32_16x16x32_bf16 v[52:55], v[170:173], v[194:197], v[52:55]
	v_mfma_f32_16x16x32_bf16 v[48:51], v[178:181], v[194:197], v[48:51]
	v_mfma_f32_16x16x32_bf16 v[44:47], v[170:173], v[202:205], v[44:47]
	v_mfma_f32_16x16x32_bf16 v[40:43], v[178:181], v[202:205], v[40:43]
	v_mfma_f32_16x16x32_bf16 v[36:39], v[170:173], v[210:213], v[36:39]
	v_mfma_f32_16x16x32_bf16 v[32:35], v[178:181], v[210:213], v[32:35]
	v_mfma_f32_16x16x32_bf16 v[60:63], v[174:177], v[190:193], v[60:63]
	v_mfma_f32_16x16x32_bf16 v[56:59], v[182:185], v[190:193], v[56:59]
	v_mfma_f32_16x16x32_bf16 v[52:55], v[174:177], v[198:201], v[52:55]
	v_mfma_f32_16x16x32_bf16 v[48:51], v[182:185], v[198:201], v[48:51]
	v_mfma_f32_16x16x32_bf16 v[44:47], v[174:177], v[206:209], v[44:47]
	v_mfma_f32_16x16x32_bf16 v[40:43], v[182:185], v[206:209], v[40:43]
	v_mfma_f32_16x16x32_bf16 v[36:39], v[174:177], v[214:217], v[36:39]
	v_mfma_f32_16x16x32_bf16 v[32:35], v[182:185], v[214:217], v[32:35]
	s_barrier
	s_mov_b32 m0, s49
	v_lshl_add_u64 v[222:223], v[218:219], 0, s[24:25]
	ds_read_b128 v[186:189], v159 offset:49152
	ds_read_b128 v[190:193], v159 offset:50176
	ds_read_b128 v[194:197], v159 offset:51200
	ds_read_b128 v[198:201], v159 offset:52224
	ds_read_b128 v[202:205], v159 offset:53248
	ds_read_b128 v[206:209], v159 offset:54272
	ds_read_b128 v[210:213], v159 offset:55296
	ds_read_b128 v[214:217], v159 offset:56320
	global_load_lds_dwordx4 v[222:223], off
	v_lshl_add_u64 v[222:223], v[218:219], 0, s[28:29]
	s_mov_b32 m0, s83
	s_nop 0
	global_load_lds_dwordx4 v[222:223], off
	v_lshl_add_u64 v[222:223], v[218:219], 0, s[30:31]
	s_mov_b32 m0, s82
	v_lshl_add_u64 v[218:219], v[218:219], 0, s[34:35]
	global_load_lds_dwordx4 v[222:223], off
	s_mov_b32 m0, s81
	s_nop 0
	global_load_lds_dwordx4 v[218:219], off
	v_lshl_add_u64 v[218:219], v[220:221], 0, s[24:25]
	s_mov_b32 m0, s72
	s_nop 0
	global_load_lds_dwordx4 v[218:219], off
	v_lshl_add_u64 v[218:219], v[220:221], 0, s[28:29]
	s_mov_b32 m0, s73
	s_nop 0
	global_load_lds_dwordx4 v[218:219], off
	s_waitcnt vmcnt(8)
	s_waitcnt lgkmcnt(0)
	s_barrier
	s_waitcnt lgkmcnt(0)
	v_mfma_f32_16x16x32_bf16 v[92:95], v[146:149], v[186:189], v[92:95]
	v_mfma_f32_16x16x32_bf16 v[88:91], v[162:165], v[186:189], v[88:91]
	v_mfma_f32_16x16x32_bf16 v[84:87], v[146:149], v[194:197], v[84:87]
	v_mfma_f32_16x16x32_bf16 v[80:83], v[162:165], v[194:197], v[80:83]
	v_mfma_f32_16x16x32_bf16 v[76:79], v[146:149], v[202:205], v[76:79]
	v_mfma_f32_16x16x32_bf16 v[72:75], v[162:165], v[202:205], v[72:75]
	v_mfma_f32_16x16x32_bf16 v[68:71], v[146:149], v[210:213], v[68:71]
	v_mfma_f32_16x16x32_bf16 v[64:67], v[162:165], v[210:213], v[64:67]
	v_mfma_f32_16x16x32_bf16 v[92:95], v[150:153], v[190:193], v[92:95]
	v_mfma_f32_16x16x32_bf16 v[88:91], v[166:169], v[190:193], v[88:91]
	v_mfma_f32_16x16x32_bf16 v[84:87], v[150:153], v[198:201], v[84:87]
	v_mfma_f32_16x16x32_bf16 v[80:83], v[166:169], v[198:201], v[80:83]
	v_mfma_f32_16x16x32_bf16 v[76:79], v[150:153], v[206:209], v[76:79]
	v_mfma_f32_16x16x32_bf16 v[72:75], v[166:169], v[206:209], v[72:75]
	v_mfma_f32_16x16x32_bf16 v[68:71], v[150:153], v[214:217], v[68:71]
	v_mfma_f32_16x16x32_bf16 v[64:67], v[166:169], v[214:217], v[64:67]
	v_mfma_f32_16x16x32_bf16 v[28:31], v[170:173], v[186:189], v[28:31]
	v_mfma_f32_16x16x32_bf16 v[24:27], v[178:181], v[186:189], v[24:27]
	v_mfma_f32_16x16x32_bf16 v[20:23], v[170:173], v[194:197], v[20:23]
	v_mfma_f32_16x16x32_bf16 v[16:19], v[178:181], v[194:197], v[16:19]
	v_mfma_f32_16x16x32_bf16 v[12:15], v[170:173], v[202:205], v[12:15]
	v_mfma_f32_16x16x32_bf16 v[8:11], v[178:181], v[202:205], v[8:11]
	v_mfma_f32_16x16x32_bf16 v[4:7], v[170:173], v[210:213], v[4:7]
	v_mfma_f32_16x16x32_bf16 v[0:3], v[178:181], v[210:213], v[0:3]
	v_mfma_f32_16x16x32_bf16 v[28:31], v[174:177], v[190:193], v[28:31]
	v_mfma_f32_16x16x32_bf16 v[24:27], v[182:185], v[190:193], v[24:27]
	v_mfma_f32_16x16x32_bf16 v[20:23], v[174:177], v[198:201], v[20:23]
	v_mfma_f32_16x16x32_bf16 v[16:19], v[182:185], v[198:201], v[16:19]
	v_mfma_f32_16x16x32_bf16 v[12:15], v[174:177], v[206:209], v[12:15]
	v_mfma_f32_16x16x32_bf16 v[8:11], v[182:185], v[206:209], v[8:11]
	v_mfma_f32_16x16x32_bf16 v[4:7], v[174:177], v[214:217], v[4:7]
	v_mfma_f32_16x16x32_bf16 v[0:3], v[182:185], v[214:217], v[0:3]
	s_barrier
	s_movk_i32 s49, 0x100
	s_andn2_b64 vcc, exec, s[54:55]
	s_mov_b64 s[2:3], -1
	s_mov_b64 s[54:55], 0
	s_cbranch_vccz .LBB0_505
	s_and_b64 vcc, exec, s[36:37]
	s_cbranch_vccz .LBB0_508
	s_barrier

.LBB0_556:
	ds_read_b128 v[0:3], v139
	ds_read_b128 v[4:7], v139 offset:1024
	ds_read_b128 v[8:11], v139 offset:2048
	ds_read_b128 v[12:15], v139 offset:3072
	ds_read_b128 v[16:19], v140
	ds_read_b128 v[20:23], v140 offset:1024
	ds_read_b128 v[24:27], v140 offset:2048
	ds_read_b128 v[28:31], v140 offset:3072
	s_ashr_i32 s53, s52, 31
	s_lshl_b64 s[26:27], s[52:53], 16
	s_add_u32 s54, s33, s26
	s_addc_u32 s55, s62, s27
	s_and_b64 s[26:27], s[4:5], exec
	s_cselect_b32 s27, s55, s3
	s_cselect_b32 s26, s54, s2
	s_ashr_i32 s51, s50, 31
	s_lshl_b64 s[56:57], s[50:51], 16
	s_add_u32 s56, s60, s56
	s_addc_u32 s57, s65, s57
	s_and_b64 s[82:83], s[4:5], exec
	s_cselect_b32 s59, s57, s59
	s_cselect_b32 s58, s56, s58
	v_lshl_add_u64 v[64:65], s[2:3], 0, v[130:131]
	s_mov_b32 m0, s75
	v_lshl_add_u64 v[66:67], v[64:65], 0, s[30:31]
	ds_read_b128 v[32:35], v141
	ds_read_b128 v[36:39], v141 offset:1024
	ds_read_b128 v[40:43], v141 offset:2048
	ds_read_b128 v[44:47], v141 offset:3072
	ds_read_b128 v[48:51], v141 offset:4096
	ds_read_b128 v[52:55], v141 offset:5120
	ds_read_b128 v[56:59], v141 offset:6144
	ds_read_b128 v[60:63], v141 offset:7168
	global_load_lds_dwordx4 v[66:67], off
	v_lshl_add_u64 v[64:65], v[64:65], 0, s[34:35]
	s_mov_b32 m0, s76
	s_nop 0
	global_load_lds_dwordx4 v[64:65], off
	s_waitcnt vmcnt(8)
	s_waitcnt lgkmcnt(0)
	s_barrier
	s_waitcnt lgkmcnt(0)
	v_mfma_f32_16x16x32_bf16 v[88:91], v[0:3], v[56:59], 0
	v_mfma_f32_16x16x32_bf16 v[64:67], v[0:3], v[32:35], 0
	v_mfma_f32_16x16x32_bf16 v[68:71], v[8:11], v[32:35], 0
	v_mfma_f32_16x16x32_bf16 v[72:75], v[0:3], v[40:43], 0
	v_mfma_f32_16x16x32_bf16 v[76:79], v[8:11], v[40:43], 0
	v_mfma_f32_16x16x32_bf16 v[80:83], v[0:3], v[48:51], 0
	v_mfma_f32_16x16x32_bf16 v[84:87], v[8:11], v[48:51], 0
	v_mfma_f32_16x16x32_bf16 v[96:99], v[4:7], v[60:63], v[88:91]
	v_mfma_f32_16x16x32_bf16 v[88:91], v[8:11], v[56:59], 0
	v_mfma_f32_16x16x32_bf16 v[64:67], v[4:7], v[36:39], v[64:67]
	v_mfma_f32_16x16x32_bf16 v[68:71], v[12:15], v[36:39], v[68:71]
	v_mfma_f32_16x16x32_bf16 v[72:75], v[4:7], v[44:47], v[72:75]
	v_mfma_f32_16x16x32_bf16 v[76:79], v[12:15], v[44:47], v[76:79]
	v_mfma_f32_16x16x32_bf16 v[80:83], v[4:7], v[52:55], v[80:83]
	v_mfma_f32_16x16x32_bf16 v[84:87], v[12:15], v[52:55], v[84:87]
	v_mfma_f32_16x16x32_bf16 v[100:103], v[12:15], v[60:63], v[88:91]
	v_mfma_f32_16x16x32_bf16 v[88:91], v[16:19], v[32:35], 0
	v_mfma_f32_16x16x32_bf16 v[32:35], v[24:27], v[32:35], 0
	v_mfma_f32_16x16x32_bf16 v[104:107], v[20:23], v[36:39], v[88:91]
	v_mfma_f32_16x16x32_bf16 v[32:35], v[28:31], v[36:39], v[32:35]
	v_mfma_f32_16x16x32_bf16 v[36:39], v[16:19], v[40:43], 0
	v_mfma_f32_16x16x32_bf16 v[40:43], v[24:27], v[40:43], 0
	v_mfma_f32_16x16x32_bf16 v[36:39], v[20:23], v[44:47], v[36:39]
	v_mfma_f32_16x16x32_bf16 v[40:43], v[28:31], v[44:47], v[40:43]
	v_mfma_f32_16x16x32_bf16 v[44:47], v[16:19], v[48:51], 0
	v_mfma_f32_16x16x32_bf16 v[48:51], v[24:27], v[48:51], 0
	v_mfma_f32_16x16x32_bf16 v[142:145], v[28:31], v[52:55], v[48:51]
	v_mfma_f32_16x16x32_bf16 v[48:51], v[16:19], v[56:59], 0
	v_mfma_f32_16x16x32_bf16 v[146:149], v[20:23], v[60:63], v[48:51]
	v_mfma_f32_16x16x32_bf16 v[48:51], v[24:27], v[56:59], 0
	v_mfma_f32_16x16x32_bf16 v[44:47], v[20:23], v[52:55], v[44:47]
	v_mfma_f32_16x16x32_bf16 v[56:59], v[28:31], v[60:63], v[48:51]
	s_barrier
	s_add_i32 s2, s61, s68
	v_lshl_add_u64 v[248:249], s[58:59], 0, v[128:129]
	s_mov_b32 m0, s2
	s_nop 0
	ds_read_b128 v[48:51], v141 offset:16384
	ds_read_b128 v[52:55], v141 offset:17408
	ds_read_b128 v[60:63], v141 offset:18432
	ds_read_b128 v[88:91], v141 offset:19456
	ds_read_b128 v[92:95], v141 offset:20480
	ds_read_b128 v[108:111], v141 offset:21504
	ds_read_b128 v[112:115], v141 offset:22528
	ds_read_b128 v[116:119], v141 offset:23552
	global_load_lds_dwordx4 v[248:249], off
	v_lshl_add_u64 v[120:121], v[248:249], 0, s[12:13]
	s_add_i32 m0, s2, 0x2000
	s_add_i32 s2, s74, s68
	global_load_lds_dwordx4 v[120:121], off
	v_lshl_add_u64 v[120:121], v[248:249], 0, s[14:15]
	s_mov_b32 m0, s2
	v_lshl_add_u64 v[250:251], s[26:27], 0, v[130:131]
	global_load_lds_dwordx4 v[120:121], off
	v_lshl_add_u64 v[120:121], v[248:249], 0, s[16:17]
	s_add_i32 m0, s2, 0x2000
	s_nop 0
	global_load_lds_dwordx4 v[120:121], off
	s_mov_b32 m0, s49
	v_lshl_add_u64 v[120:121], v[250:251], 0, s[12:13]
	global_load_lds_dwordx4 v[250:251], off
	s_mov_b32 m0, s69
	s_nop 0
	global_load_lds_dwordx4 v[120:121], off
	s_waitcnt vmcnt(8)
	s_waitcnt lgkmcnt(0)
	s_barrier
	s_waitcnt lgkmcnt(0)
	v_mfma_f32_16x16x32_bf16 v[120:123], v[0:3], v[48:51], 0
	v_mfma_f32_16x16x32_bf16 v[150:153], v[4:7], v[52:55], v[120:123]
	v_mfma_f32_16x16x32_bf16 v[120:123], v[8:11], v[48:51], 0
	v_mfma_f32_16x16x32_bf16 v[156:159], v[12:15], v[52:55], v[120:123]
	v_mfma_f32_16x16x32_bf16 v[120:123], v[0:3], v[60:63], 0
	v_mfma_f32_16x16x32_bf16 v[160:163], v[4:7], v[88:91], v[120:123]
	v_mfma_f32_16x16x32_bf16 v[120:123], v[8:11], v[60:63], 0
	v_mfma_f32_16x16x32_bf16 v[164:167], v[12:15], v[88:91], v[120:123]
	v_mfma_f32_16x16x32_bf16 v[120:123], v[0:3], v[92:95], 0
	v_mfma_f32_16x16x32_bf16 v[0:3], v[0:3], v[112:115], 0
	v_mfma_f32_16x16x32_bf16 v[168:171], v[4:7], v[108:111], v[120:123]
	v_mfma_f32_16x16x32_bf16 v[0:3], v[4:7], v[116:119], v[0:3]
	v_mfma_f32_16x16x32_bf16 v[4:7], v[8:11], v[112:115], 0
	v_mfma_f32_16x16x32_bf16 v[120:123], v[8:11], v[92:95], 0
	v_mfma_f32_16x16x32_bf16 v[4:7], v[12:15], v[116:119], v[4:7]
	v_mfma_f32_16x16x32_bf16 v[172:175], v[12:15], v[108:111], v[120:123]
	v_mfma_f32_16x16x32_bf16 v[8:11], v[16:19], v[48:51], 0
	v_mfma_f32_16x16x32_bf16 v[12:15], v[24:27], v[48:51], 0
	v_mfma_f32_16x16x32_bf16 v[48:51], v[16:19], v[60:63], 0
	v_mfma_f32_16x16x32_bf16 v[176:179], v[20:23], v[88:91], v[48:51]
	v_mfma_f32_16x16x32_bf16 v[48:51], v[24:27], v[60:63], 0
	v_mfma_f32_16x16x32_bf16 v[180:183], v[28:31], v[88:91], v[48:51]
	v_mfma_f32_16x16x32_bf16 v[48:51], v[16:19], v[92:95], 0
	v_mfma_f32_16x16x32_bf16 v[16:19], v[16:19], v[112:115], 0
	v_mfma_f32_16x16x32_bf16 v[8:11], v[20:23], v[52:55], v[8:11]
	v_mfma_f32_16x16x32_bf16 v[12:15], v[28:31], v[52:55], v[12:15]
	v_mfma_f32_16x16x32_bf16 v[184:187], v[20:23], v[108:111], v[48:51]
	v_mfma_f32_16x16x32_bf16 v[48:51], v[24:27], v[92:95], 0
	v_mfma_f32_16x16x32_bf16 v[192:195], v[20:23], v[116:119], v[16:19]
	v_mfma_f32_16x16x32_bf16 v[16:19], v[24:27], v[112:115], 0
	v_mfma_f32_16x16x32_bf16 v[188:191], v[28:31], v[108:111], v[48:51]
	v_mfma_f32_16x16x32_bf16 v[196:199], v[28:31], v[116:119], v[16:19]
	s_barrier
	s_add_i32 s2, 0, 0x18000
	s_nop 2
	v_add_u32_e32 v16, s2, v137
	s_add_i32 s3, 0, 0x1c000
	ds_read_b128 v[200:203], v16
	ds_read_b128 v[204:207], v16 offset:1024
	ds_read_b128 v[208:211], v16 offset:2048
	ds_read_b128 v[212:215], v16 offset:3072
	v_add_u32_e32 v16, s3, v137
	ds_read_b128 v[216:219], v16
	ds_read_b128 v[220:223], v16 offset:1024
	ds_read_b128 v[224:227], v16 offset:2048
	ds_read_b128 v[228:231], v16 offset:3072
	s_mov_b32 m0, s70
	v_lshl_add_u64 v[16:17], v[250:251], 0, s[14:15]
	ds_read_b128 v[24:27], v141 offset:32768
	ds_read_b128 v[28:31], v141 offset:33792
	ds_read_b128 v[60:63], v141 offset:34816
	ds_read_b128 v[108:111], v141 offset:35840
	ds_read_b128 v[232:235], v141 offset:36864
	ds_read_b128 v[236:239], v141 offset:37888
	ds_read_b128 v[240:243], v141 offset:38912
	ds_read_b128 v[244:247], v141 offset:39936
	global_load_lds_dwordx4 v[16:17], off
	v_lshl_add_u64 v[16:17], v[250:251], 0, s[16:17]
	s_mov_b32 m0, s71
	s_nop 0
	global_load_lds_dwordx4 v[16:17], off
	s_waitcnt vmcnt(8)
	s_waitcnt lgkmcnt(0)
	s_barrier
	s_waitcnt lgkmcnt(0)
	v_mfma_f32_16x16x32_bf16 v[16:19], v[200:203], v[24:27], v[64:67]
	v_mfma_f32_16x16x32_bf16 v[112:115], v[204:207], v[28:31], v[16:19]
	v_mfma_f32_16x16x32_bf16 v[16:19], v[208:211], v[24:27], v[68:71]
	v_mfma_f32_16x16x32_bf16 v[116:119], v[212:215], v[28:31], v[16:19]
	v_mfma_f32_16x16x32_bf16 v[16:19], v[200:203], v[60:63], v[72:75]
	v_mfma_f32_16x16x32_bf16 v[88:91], v[204:207], v[108:111], v[16:19]
	v_mfma_f32_16x16x32_bf16 v[16:19], v[208:211], v[60:63], v[76:79]
	v_mfma_f32_16x16x32_bf16 v[92:95], v[212:215], v[108:111], v[16:19]
	v_mfma_f32_16x16x32_bf16 v[16:19], v[200:203], v[232:235], v[80:83]
	v_mfma_f32_16x16x32_bf16 v[48:51], v[204:207], v[236:239], v[16:19]
	v_mfma_f32_16x16x32_bf16 v[16:19], v[208:211], v[232:235], v[84:87]
	v_mfma_f32_16x16x32_bf16 v[52:55], v[212:215], v[236:239], v[16:19]
	v_mfma_f32_16x16x32_bf16 v[16:19], v[200:203], v[240:243], v[96:99]
	v_mfma_f32_16x16x32_bf16 v[20:23], v[208:211], v[240:243], v[100:103]
	v_mfma_f32_16x16x32_bf16 v[16:19], v[204:207], v[244:247], v[16:19]
	v_mfma_f32_16x16x32_bf16 v[20:23], v[212:215], v[244:247], v[20:23]
	v_mfma_f32_16x16x32_bf16 v[64:67], v[216:219], v[24:27], v[104:107]
	v_mfma_f32_16x16x32_bf16 v[24:27], v[224:227], v[24:27], v[32:35]
	v_mfma_f32_16x16x32_bf16 v[124:127], v[228:231], v[28:31], v[24:27]
	v_mfma_f32_16x16x32_bf16 v[24:27], v[216:219], v[60:63], v[36:39]
	v_mfma_f32_16x16x32_bf16 v[104:107], v[220:223], v[108:111], v[24:27]
	v_mfma_f32_16x16x32_bf16 v[24:27], v[224:227], v[60:63], v[40:43]
	v_mfma_f32_16x16x32_bf16 v[108:111], v[228:231], v[108:111], v[24:27]
	v_mfma_f32_16x16x32_bf16 v[24:27], v[216:219], v[232:235], v[44:47]
	v_mfma_f32_16x16x32_bf16 v[72:75], v[220:223], v[236:239], v[24:27]
	v_mfma_f32_16x16x32_bf16 v[24:27], v[224:227], v[232:235], v[142:145]
	v_mfma_f32_16x16x32_bf16 v[76:79], v[228:231], v[236:239], v[24:27]
	v_mfma_f32_16x16x32_bf16 v[24:27], v[216:219], v[240:243], v[146:149]
	v_mfma_f32_16x16x32_bf16 v[40:43], v[220:223], v[244:247], v[24:27]
	v_mfma_f32_16x16x32_bf16 v[24:27], v[224:227], v[240:243], v[56:59]
	v_mfma_f32_16x16x32_bf16 v[120:123], v[220:223], v[28:31], v[64:67]
	v_mfma_f32_16x16x32_bf16 v[44:47], v[228:231], v[244:247], v[24:27]
	s_barrier
	s_add_i32 s2, s2, s68
	s_nop 2
	v_lshl_add_u64 v[24:25], v[248:249], 0, s[24:25]
	s_mov_b32 m0, s2
	ds_read_b128 v[32:35], v141 offset:49152
	ds_read_b128 v[36:39], v141 offset:50176
	ds_read_b128 v[68:71], v141 offset:51200
	ds_read_b128 v[142:145], v141 offset:52224
	ds_read_b128 v[146:149], v141 offset:53248
	ds_read_b128 v[232:235], v141 offset:54272
	ds_read_b128 v[236:239], v141 offset:55296
	ds_read_b128 v[240:243], v141 offset:56320
	global_load_lds_dwordx4 v[24:25], off
	v_lshl_add_u64 v[24:25], v[248:249], 0, s[28:29]
	s_add_i32 m0, s2, 0x2000
	s_add_i32 s2, s3, s68
	global_load_lds_dwordx4 v[24:25], off
	v_lshl_add_u64 v[24:25], v[248:249], 0, s[30:31]
	s_mov_b32 m0, s2
	s_nop 0
	global_load_lds_dwordx4 v[24:25], off
	v_lshl_add_u64 v[24:25], v[248:249], 0, s[34:35]
	s_add_i32 m0, s2, 0x2000
	s_nop 0
	global_load_lds_dwordx4 v[24:25], off
	v_lshl_add_u64 v[24:25], v[250:251], 0, s[24:25]
	s_mov_b32 m0, s72
	s_nop 0
	global_load_lds_dwordx4 v[24:25], off
	v_lshl_add_u64 v[24:25], v[250:251], 0, s[28:29]
	s_mov_b32 m0, s73
	s_nop 0
	global_load_lds_dwordx4 v[24:25], off
	s_waitcnt vmcnt(8)
	s_waitcnt lgkmcnt(0)
	s_barrier
	s_waitcnt lgkmcnt(0)
	v_mfma_f32_16x16x32_bf16 v[24:27], v[200:203], v[32:35], v[150:153]
	v_mfma_f32_16x16x32_bf16 v[80:83], v[204:207], v[36:39], v[24:27]
	v_mfma_f32_16x16x32_bf16 v[24:27], v[208:211], v[32:35], v[156:159]
	v_mfma_f32_16x16x32_bf16 v[84:87], v[212:215], v[36:39], v[24:27]
	v_mfma_f32_16x16x32_bf16 v[24:27], v[200:203], v[68:71], v[160:163]
	v_mfma_f32_16x16x32_bf16 v[56:59], v[204:207], v[142:145], v[24:27]
	v_mfma_f32_16x16x32_bf16 v[24:27], v[208:211], v[68:71], v[164:167]
	v_mfma_f32_16x16x32_bf16 v[60:63], v[212:215], v[142:145], v[24:27]
	v_mfma_f32_16x16x32_bf16 v[24:27], v[200:203], v[146:149], v[168:171]
	v_mfma_f32_16x16x32_bf16 v[28:31], v[208:211], v[146:149], v[172:175]
	v_mfma_f32_16x16x32_bf16 v[0:3], v[200:203], v[236:239], v[0:3]
	v_mfma_f32_16x16x32_bf16 v[4:7], v[208:211], v[236:239], v[4:7]
	v_mfma_f32_16x16x32_bf16 v[24:27], v[204:207], v[232:235], v[24:27]
	v_mfma_f32_16x16x32_bf16 v[28:31], v[212:215], v[232:235], v[28:31]
	v_mfma_f32_16x16x32_bf16 v[0:3], v[204:207], v[240:243], v[0:3]
	v_mfma_f32_16x16x32_bf16 v[4:7], v[212:215], v[240:243], v[4:7]
	v_mfma_f32_16x16x32_bf16 v[8:11], v[216:219], v[32:35], v[8:11]
	v_mfma_f32_16x16x32_bf16 v[96:99], v[220:223], v[36:39], v[8:11]
	v_mfma_f32_16x16x32_bf16 v[8:11], v[224:227], v[32:35], v[12:15]
	v_mfma_f32_16x16x32_bf16 v[100:103], v[228:231], v[36:39], v[8:11]
	v_mfma_f32_16x16x32_bf16 v[8:11], v[216:219], v[68:71], v[176:179]
	v_mfma_f32_16x16x32_bf16 v[64:67], v[220:223], v[142:145], v[8:11]
	v_mfma_f32_16x16x32_bf16 v[8:11], v[224:227], v[68:71], v[180:183]
	v_mfma_f32_16x16x32_bf16 v[68:71], v[228:231], v[142:145], v[8:11]
	v_mfma_f32_16x16x32_bf16 v[8:11], v[216:219], v[146:149], v[184:187]
	v_mfma_f32_16x16x32_bf16 v[32:35], v[220:223], v[232:235], v[8:11]
	v_mfma_f32_16x16x32_bf16 v[8:11], v[224:227], v[146:149], v[188:191]
	v_mfma_f32_16x16x32_bf16 v[36:39], v[228:231], v[232:235], v[8:11]
	v_mfma_f32_16x16x32_bf16 v[8:11], v[216:219], v[236:239], v[192:195]
	v_mfma_f32_16x16x32_bf16 v[12:15], v[224:227], v[236:239], v[196:199]
	v_mfma_f32_16x16x32_bf16 v[8:11], v[220:223], v[240:243], v[8:11]
	v_mfma_f32_16x16x32_bf16 v[12:15], v[228:231], v[240:243], v[12:15]
	s_barrier
	s_andn2_b64 vcc, exec, s[36:37]
	s_cbranch_vccnz .LBB0_558
	s_barrier

.LBB0_574:
	ds_read_b128 v[0:3], v141
	ds_read_b128 v[4:7], v141 offset:1024
	ds_read_b128 v[8:11], v141 offset:2048
	ds_read_b128 v[12:15], v141 offset:3072
	ds_read_b128 v[16:19], v142
	ds_read_b128 v[20:23], v142 offset:1024
	ds_read_b128 v[24:27], v142 offset:2048
	ds_read_b128 v[28:31], v142 offset:3072
	s_ashr_i32 s51, s50, 31
	s_lshl_b64 s[26:27], s[50:51], 16
	s_add_u32 s54, s60, s26
	s_addc_u32 s55, s65, s27
	s_and_b64 s[26:27], s[6:7], exec
	s_cselect_b32 s27, s55, s3
	s_cselect_b32 s26, s54, s2
	s_ashr_i32 s49, s48, 31
	s_lshl_b64 s[56:57], s[48:49], 16
	s_add_u32 s56, s33, s56
	s_addc_u32 s57, s62, s57
	s_and_b64 s[82:83], s[6:7], exec
	s_cselect_b32 s59, s57, s59
	s_cselect_b32 s58, s56, s58
	v_lshl_add_u64 v[64:65], s[2:3], 0, v[130:131]
	s_mov_b32 m0, s75
	v_lshl_add_u64 v[66:67], v[64:65], 0, s[30:31]
	ds_read_b128 v[32:35], v143
	ds_read_b128 v[36:39], v143 offset:1024
	ds_read_b128 v[40:43], v143 offset:2048
	ds_read_b128 v[44:47], v143 offset:3072
	ds_read_b128 v[48:51], v143 offset:4096
	ds_read_b128 v[52:55], v143 offset:5120
	ds_read_b128 v[56:59], v143 offset:6144
	ds_read_b128 v[60:63], v143 offset:7168
	global_load_lds_dwordx4 v[66:67], off
	v_lshl_add_u64 v[64:65], v[64:65], 0, s[34:35]
	s_mov_b32 m0, s76
	s_nop 0
	global_load_lds_dwordx4 v[64:65], off
	s_waitcnt vmcnt(8)
	s_waitcnt lgkmcnt(0)
	s_barrier
	s_waitcnt lgkmcnt(0)
	v_mfma_f32_16x16x32_bf16 v[64:67], v[0:3], v[32:35], 0
	v_mfma_f32_16x16x32_bf16 v[68:71], v[8:11], v[32:35], 0
	v_mfma_f32_16x16x32_bf16 v[72:75], v[0:3], v[40:43], 0
	v_mfma_f32_16x16x32_bf16 v[76:79], v[8:11], v[40:43], 0
	v_mfma_f32_16x16x32_bf16 v[80:83], v[0:3], v[48:51], 0
	v_mfma_f32_16x16x32_bf16 v[84:87], v[8:11], v[48:51], 0
	v_mfma_f32_16x16x32_bf16 v[88:91], v[0:3], v[56:59], 0
	v_mfma_f32_16x16x32_bf16 v[92:95], v[8:11], v[56:59], 0
	v_mfma_f32_16x16x32_bf16 v[64:67], v[4:7], v[36:39], v[64:67]
	v_mfma_f32_16x16x32_bf16 v[68:71], v[12:15], v[36:39], v[68:71]
	v_mfma_f32_16x16x32_bf16 v[72:75], v[4:7], v[44:47], v[72:75]
	v_mfma_f32_16x16x32_bf16 v[76:79], v[12:15], v[44:47], v[76:79]
	v_mfma_f32_16x16x32_bf16 v[80:83], v[4:7], v[52:55], v[80:83]
	v_mfma_f32_16x16x32_bf16 v[84:87], v[12:15], v[52:55], v[84:87]
	v_mfma_f32_16x16x32_bf16 v[88:91], v[4:7], v[60:63], v[88:91]
	v_mfma_f32_16x16x32_bf16 v[92:95], v[12:15], v[60:63], v[92:95]
	v_mfma_f32_16x16x32_bf16 v[96:99], v[16:19], v[32:35], 0
	v_mfma_f32_16x16x32_bf16 v[32:35], v[24:27], v[32:35], 0
	v_mfma_f32_16x16x32_bf16 v[104:107], v[20:23], v[36:39], v[96:99]
	v_mfma_f32_16x16x32_bf16 v[36:39], v[28:31], v[36:39], v[32:35]
	v_mfma_f32_16x16x32_bf16 v[32:35], v[16:19], v[40:43], 0
	v_mfma_f32_16x16x32_bf16 v[108:111], v[20:23], v[44:47], v[32:35]
	v_mfma_f32_16x16x32_bf16 v[32:35], v[24:27], v[40:43], 0
	v_mfma_f32_16x16x32_bf16 v[40:43], v[28:31], v[44:47], v[32:35]
	v_mfma_f32_16x16x32_bf16 v[32:35], v[16:19], v[48:51], 0
	v_mfma_f32_16x16x32_bf16 v[44:47], v[20:23], v[52:55], v[32:35]
	v_mfma_f32_16x16x32_bf16 v[32:35], v[24:27], v[48:51], 0
	v_mfma_f32_16x16x32_bf16 v[48:51], v[28:31], v[52:55], v[32:35]
	v_mfma_f32_16x16x32_bf16 v[32:35], v[16:19], v[56:59], 0
	v_mfma_f32_16x16x32_bf16 v[52:55], v[20:23], v[60:63], v[32:35]
	v_mfma_f32_16x16x32_bf16 v[32:35], v[24:27], v[56:59], 0
	v_mfma_f32_16x16x32_bf16 v[56:59], v[28:31], v[60:63], v[32:35]
	s_barrier
	s_add_i32 s2, s74, s68
	v_lshl_add_u64 v[152:153], s[58:59], 0, v[128:129]
	s_mov_b32 m0, s2
	s_nop 1
	ds_read_b128 v[32:35], v143 offset:16384
	ds_read_b128 v[60:63], v143 offset:17408
	ds_read_b128 v[96:99], v143 offset:18432
	ds_read_b128 v[100:103], v143 offset:19456
	ds_read_b128 v[112:115], v143 offset:20480
	ds_read_b128 v[116:119], v143 offset:21504
	ds_read_b128 v[120:123], v143 offset:22528
	ds_read_b128 v[124:127], v143 offset:23552
	global_load_lds_dwordx4 v[152:153], off
	v_lshl_add_u64 v[144:145], v[152:153], 0, s[12:13]
	s_add_i32 m0, s2, 0x2000
	s_add_i32 s2, s61, s68
	global_load_lds_dwordx4 v[144:145], off
	v_lshl_add_u64 v[144:145], v[152:153], 0, s[14:15]
	s_mov_b32 m0, s2
	v_lshl_add_u64 v[248:249], s[26:27], 0, v[130:131]
	global_load_lds_dwordx4 v[144:145], off
	v_lshl_add_u64 v[144:145], v[152:153], 0, s[16:17]
	s_add_i32 m0, s2, 0x2000
	s_nop 0
	global_load_lds_dwordx4 v[144:145], off
	s_mov_b32 m0, s53
	v_lshl_add_u64 v[144:145], v[248:249], 0, s[12:13]
	global_load_lds_dwordx4 v[248:249], off
	s_mov_b32 m0, s69
	s_nop 0
	global_load_lds_dwordx4 v[144:145], off
	s_waitcnt vmcnt(8)
	s_waitcnt lgkmcnt(0)
	s_barrier
	s_waitcnt lgkmcnt(0)
	v_mfma_f32_16x16x32_bf16 v[144:147], v[0:3], v[32:35], 0
	v_mfma_f32_16x16x32_bf16 v[156:159], v[0:3], v[96:99], 0
	v_mfma_f32_16x16x32_bf16 v[164:167], v[0:3], v[112:115], 0
	v_mfma_f32_16x16x32_bf16 v[0:3], v[0:3], v[120:123], 0
	v_mfma_f32_16x16x32_bf16 v[144:147], v[4:7], v[60:63], v[144:147]
	v_mfma_f32_16x16x32_bf16 v[156:159], v[4:7], v[100:103], v[156:159]
	v_mfma_f32_16x16x32_bf16 v[164:167], v[4:7], v[116:119], v[164:167]
	v_mfma_f32_16x16x32_bf16 v[0:3], v[4:7], v[124:127], v[0:3]
	v_mfma_f32_16x16x32_bf16 v[4:7], v[8:11], v[120:123], 0
	v_mfma_f32_16x16x32_bf16 v[148:151], v[8:11], v[32:35], 0
	v_mfma_f32_16x16x32_bf16 v[160:163], v[8:11], v[96:99], 0
	v_mfma_f32_16x16x32_bf16 v[168:171], v[8:11], v[112:115], 0
	v_mfma_f32_16x16x32_bf16 v[8:11], v[12:15], v[124:127], v[4:7]
	v_mfma_f32_16x16x32_bf16 v[148:151], v[12:15], v[60:63], v[148:151]
	v_mfma_f32_16x16x32_bf16 v[160:163], v[12:15], v[100:103], v[160:163]
	v_mfma_f32_16x16x32_bf16 v[168:171], v[12:15], v[116:119], v[168:171]
	v_mfma_f32_16x16x32_bf16 v[4:7], v[16:19], v[32:35], 0
	v_mfma_f32_16x16x32_bf16 v[12:15], v[20:23], v[60:63], v[4:7]
	v_mfma_f32_16x16x32_bf16 v[4:7], v[24:27], v[32:35], 0
	v_mfma_f32_16x16x32_bf16 v[172:175], v[28:31], v[60:63], v[4:7]
	v_mfma_f32_16x16x32_bf16 v[4:7], v[16:19], v[96:99], 0
	v_mfma_f32_16x16x32_bf16 v[176:179], v[20:23], v[100:103], v[4:7]
	v_mfma_f32_16x16x32_bf16 v[4:7], v[24:27], v[96:99], 0
	v_mfma_f32_16x16x32_bf16 v[180:183], v[28:31], v[100:103], v[4:7]
	v_mfma_f32_16x16x32_bf16 v[4:7], v[16:19], v[112:115], 0
	v_mfma_f32_16x16x32_bf16 v[184:187], v[20:23], v[116:119], v[4:7]
	v_mfma_f32_16x16x32_bf16 v[4:7], v[24:27], v[112:115], 0
	v_mfma_f32_16x16x32_bf16 v[188:191], v[28:31], v[116:119], v[4:7]
	v_mfma_f32_16x16x32_bf16 v[4:7], v[16:19], v[120:123], 0
	v_mfma_f32_16x16x32_bf16 v[192:195], v[20:23], v[124:127], v[4:7]
	v_mfma_f32_16x16x32_bf16 v[4:7], v[24:27], v[120:123], 0
	v_mfma_f32_16x16x32_bf16 v[196:199], v[28:31], v[124:127], v[4:7]
	s_barrier
	s_add_i32 s2, 0, 0x18000
	v_add_u32_e32 v16, s2, v139
	s_add_i32 s3, 0, 0x1c000
	s_nop 1
	ds_read_b128 v[4:7], v16
	ds_read_b128 v[28:31], v16 offset:1024
	ds_read_b128 v[200:203], v16 offset:2048
	ds_read_b128 v[204:207], v16 offset:3072
	v_add_u32_e32 v16, s3, v139
	ds_read_b128 v[208:211], v16
	ds_read_b128 v[212:215], v16 offset:1024
	ds_read_b128 v[216:219], v16 offset:2048
	ds_read_b128 v[220:223], v16 offset:3072
	s_mov_b32 m0, s70
	v_lshl_add_u64 v[24:25], v[248:249], 0, s[14:15]
	ds_read_b128 v[16:19], v143 offset:32768
	ds_read_b128 v[20:23], v143 offset:33792
	ds_read_b128 v[224:227], v143 offset:34816
	ds_read_b128 v[228:231], v143 offset:35840
	ds_read_b128 v[232:235], v143 offset:36864
	ds_read_b128 v[236:239], v143 offset:37888
	ds_read_b128 v[240:243], v143 offset:38912
	ds_read_b128 v[244:247], v143 offset:39936
	global_load_lds_dwordx4 v[24:25], off
	v_lshl_add_u64 v[24:25], v[248:249], 0, s[16:17]
	s_mov_b32 m0, s71
	s_nop 0
	global_load_lds_dwordx4 v[24:25], off
	s_waitcnt vmcnt(8)
	s_waitcnt lgkmcnt(0)
	s_barrier
	s_waitcnt lgkmcnt(0)
	v_mfma_f32_16x16x32_bf16 v[24:27], v[4:7], v[16:19], v[64:67]
	v_mfma_f32_16x16x32_bf16 v[116:119], v[28:31], v[20:23], v[24:27]
	v_mfma_f32_16x16x32_bf16 v[24:27], v[200:203], v[16:19], v[68:71]
	v_mfma_f32_16x16x32_bf16 v[112:115], v[204:207], v[20:23], v[24:27]
	v_mfma_f32_16x16x32_bf16 v[24:27], v[4:7], v[224:227], v[72:75]
	v_mfma_f32_16x16x32_bf16 v[100:103], v[28:31], v[228:231], v[24:27]
	v_mfma_f32_16x16x32_bf16 v[24:27], v[200:203], v[224:227], v[76:79]
	v_mfma_f32_16x16x32_bf16 v[96:99], v[204:207], v[228:231], v[24:27]
	v_mfma_f32_16x16x32_bf16 v[24:27], v[4:7], v[232:235], v[80:83]
	v_mfma_f32_16x16x32_bf16 v[68:71], v[28:31], v[236:239], v[24:27]
	v_mfma_f32_16x16x32_bf16 v[24:27], v[200:203], v[232:235], v[84:87]
	v_mfma_f32_16x16x32_bf16 v[60:63], v[204:207], v[236:239], v[24:27]
	v_mfma_f32_16x16x32_bf16 v[24:27], v[4:7], v[240:243], v[88:91]
	v_mfma_f32_16x16x32_bf16 v[32:35], v[28:31], v[244:247], v[24:27]
	v_mfma_f32_16x16x32_bf16 v[24:27], v[200:203], v[240:243], v[92:95]
	v_mfma_f32_16x16x32_bf16 v[24:27], v[204:207], v[244:247], v[24:27]
	v_mfma_f32_16x16x32_bf16 v[64:67], v[208:211], v[16:19], v[104:107]
	v_mfma_f32_16x16x32_bf16 v[16:19], v[216:219], v[16:19], v[36:39]
	v_mfma_f32_16x16x32_bf16 v[120:123], v[220:223], v[20:23], v[16:19]
	v_mfma_f32_16x16x32_bf16 v[16:19], v[208:211], v[224:227], v[108:111]
	v_mfma_f32_16x16x32_bf16 v[108:111], v[212:215], v[228:231], v[16:19]
	v_mfma_f32_16x16x32_bf16 v[16:19], v[216:219], v[224:227], v[40:43]
	v_mfma_f32_16x16x32_bf16 v[104:107], v[220:223], v[228:231], v[16:19]
	v_mfma_f32_16x16x32_bf16 v[16:19], v[208:211], v[232:235], v[44:47]
	v_mfma_f32_16x16x32_bf16 v[80:83], v[212:215], v[236:239], v[16:19]
	v_mfma_f32_16x16x32_bf16 v[16:19], v[216:219], v[232:235], v[48:51]
	v_mfma_f32_16x16x32_bf16 v[72:75], v[220:223], v[236:239], v[16:19]
	v_mfma_f32_16x16x32_bf16 v[16:19], v[208:211], v[240:243], v[52:55]
	v_mfma_f32_16x16x32_bf16 v[44:47], v[212:215], v[244:247], v[16:19]
	v_mfma_f32_16x16x32_bf16 v[16:19], v[216:219], v[240:243], v[56:59]
	v_mfma_f32_16x16x32_bf16 v[124:127], v[212:215], v[20:23], v[64:67]
	v_mfma_f32_16x16x32_bf16 v[40:43], v[220:223], v[244:247], v[16:19]
	s_barrier
	s_add_i32 s2, s2, s68
	s_nop 2
	v_lshl_add_u64 v[16:17], v[152:153], 0, s[24:25]
	s_mov_b32 m0, s2
	ds_read_b128 v[36:39], v143 offset:49152
	ds_read_b128 v[56:59], v143 offset:50176
	ds_read_b128 v[224:227], v143 offset:51200
	ds_read_b128 v[228:231], v143 offset:52224
	ds_read_b128 v[232:235], v143 offset:53248
	ds_read_b128 v[236:239], v143 offset:54272
	ds_read_b128 v[240:243], v143 offset:55296
	ds_read_b128 v[244:247], v143 offset:56320
	global_load_lds_dwordx4 v[16:17], off
	v_lshl_add_u64 v[16:17], v[152:153], 0, s[28:29]
	s_add_i32 m0, s2, 0x2000
	s_add_i32 s2, s3, s68
	global_load_lds_dwordx4 v[16:17], off
	v_lshl_add_u64 v[16:17], v[152:153], 0, s[30:31]
	s_mov_b32 m0, s2
	s_nop 0
	global_load_lds_dwordx4 v[16:17], off
	v_lshl_add_u64 v[16:17], v[152:153], 0, s[34:35]
	s_add_i32 m0, s2, 0x2000
	s_nop 0
	global_load_lds_dwordx4 v[16:17], off
	v_lshl_add_u64 v[16:17], v[248:249], 0, s[24:25]
	s_mov_b32 m0, s72
	s_nop 0
	global_load_lds_dwordx4 v[16:17], off
	v_lshl_add_u64 v[16:17], v[248:249], 0, s[28:29]
	s_mov_b32 m0, s73
	s_nop 0
	global_load_lds_dwordx4 v[16:17], off
	s_waitcnt vmcnt(8)
	s_waitcnt lgkmcnt(0)
	s_barrier
	s_waitcnt lgkmcnt(0)
	v_mfma_f32_16x16x32_bf16 v[16:19], v[4:7], v[36:39], v[144:147]
	v_mfma_f32_16x16x32_bf16 v[84:87], v[28:31], v[56:59], v[16:19]
	v_mfma_f32_16x16x32_bf16 v[16:19], v[200:203], v[36:39], v[148:151]
	v_mfma_f32_16x16x32_bf16 v[76:79], v[204:207], v[56:59], v[16:19]
	v_mfma_f32_16x16x32_bf16 v[16:19], v[4:7], v[224:227], v[156:159]
	v_mfma_f32_16x16x32_bf16 v[52:55], v[28:31], v[228:231], v[16:19]
	v_mfma_f32_16x16x32_bf16 v[16:19], v[200:203], v[224:227], v[160:163]
	v_mfma_f32_16x16x32_bf16 v[48:51], v[204:207], v[228:231], v[16:19]
	v_mfma_f32_16x16x32_bf16 v[16:19], v[4:7], v[232:235], v[164:167]
	v_mfma_f32_16x16x32_bf16 v[0:3], v[4:7], v[240:243], v[0:3]
	v_mfma_f32_16x16x32_bf16 v[20:23], v[28:31], v[236:239], v[16:19]
	v_mfma_f32_16x16x32_bf16 v[16:19], v[200:203], v[232:235], v[168:171]
	v_mfma_f32_16x16x32_bf16 v[4:7], v[28:31], v[244:247], v[0:3]
	v_mfma_f32_16x16x32_bf16 v[0:3], v[200:203], v[240:243], v[8:11]
	v_mfma_f32_16x16x32_bf16 v[16:19], v[204:207], v[236:239], v[16:19]
	v_mfma_f32_16x16x32_bf16 v[0:3], v[204:207], v[244:247], v[0:3]
	v_mfma_f32_16x16x32_bf16 v[8:11], v[208:211], v[36:39], v[12:15]
	v_mfma_f32_16x16x32_bf16 v[92:95], v[212:215], v[56:59], v[8:11]
	v_mfma_f32_16x16x32_bf16 v[8:11], v[216:219], v[36:39], v[172:175]
	v_mfma_f32_16x16x32_bf16 v[88:91], v[220:223], v[56:59], v[8:11]
	v_mfma_f32_16x16x32_bf16 v[8:11], v[208:211], v[224:227], v[176:179]
	v_mfma_f32_16x16x32_bf16 v[64:67], v[212:215], v[228:231], v[8:11]
	v_mfma_f32_16x16x32_bf16 v[8:11], v[216:219], v[224:227], v[180:183]
	v_mfma_f32_16x16x32_bf16 v[56:59], v[220:223], v[228:231], v[8:11]
	v_mfma_f32_16x16x32_bf16 v[8:11], v[208:211], v[232:235], v[184:187]
	v_mfma_f32_16x16x32_bf16 v[36:39], v[212:215], v[236:239], v[8:11]
	v_mfma_f32_16x16x32_bf16 v[8:11], v[216:219], v[232:235], v[188:191]
	v_mfma_f32_16x16x32_bf16 v[28:31], v[220:223], v[236:239], v[8:11]
	v_mfma_f32_16x16x32_bf16 v[8:11], v[208:211], v[240:243], v[192:195]
	v_mfma_f32_16x16x32_bf16 v[12:15], v[212:215], v[244:247], v[8:11]
	v_mfma_f32_16x16x32_bf16 v[8:11], v[216:219], v[240:243], v[196:199]
	v_mfma_f32_16x16x32_bf16 v[8:11], v[220:223], v[244:247], v[8:11]
	s_barrier
	s_andn2_b64 vcc, exec, s[36:37]
	s_cbranch_vccnz .LBB0_576
	s_barrier

.LBB0_595:
	s_add_u32 s58, s50, s60
	s_addc_u32 s59, s51, 0
	s_add_u32 s61, s58, 0x100
	ds_read_b128 v[128:131], v149
	ds_read_b128 v[132:135], v149 offset:1024
	ds_read_b128 v[156:159], v149 offset:2048
	ds_read_b128 v[160:163], v149 offset:3072
	ds_read_b128 v[164:167], v150
	ds_read_b128 v[168:171], v150 offset:1024
	ds_read_b128 v[172:175], v150 offset:2048
	ds_read_b128 v[176:179], v150 offset:3072
	s_addc_u32 s76, s59, 0
	s_and_b64 s[56:57], s[2:3], exec
	s_cselect_b32 s56, s6, s61
	s_cselect_b32 s57, s7, s76
	s_add_u32 s60, s52, s60
	s_addc_u32 s61, s53, 0
	s_add_u32 s60, s60, 0x100
	s_addc_u32 s61, s61, 0
	s_and_b64 s[2:3], s[2:3], exec
	s_cselect_b32 s2, s45, s60
	s_cselect_b32 s3, s43, s61
	s_add_i32 s78, 0, 0x1c000
	s_add_i32 s79, 0, 0x18000
	s_add_i32 s61, s78, s65
	s_add_i32 s83, s72, s65
	s_add_i32 s81, s73, s65
	s_add_i32 s77, s79, s65
	s_add_i32 s60, s61, 0x2000
	s_add_i32 m0, s49, 0xc000
	s_add_i32 s84, s49, 0xe000
	s_add_i32 s82, s83, 0x2000
	s_add_i32 s80, s81, 0x2000
	s_add_i32 s76, s77, 0x2000
	v_lshl_add_u64 v[144:145], s[58:59], 0, v[138:139]
	s_mov_b64 s[58:59], 0x20080
	v_lshl_add_u64 v[152:153], v[144:145], 0, s[58:59]
	s_mov_b64 s[58:59], 0x30080
	ds_read_b128 v[180:183], v151
	ds_read_b128 v[184:187], v151 offset:1024
	ds_read_b128 v[188:191], v151 offset:2048
	ds_read_b128 v[192:195], v151 offset:3072
	ds_read_b128 v[196:199], v151 offset:4096
	ds_read_b128 v[200:203], v151 offset:5120
	ds_read_b128 v[204:207], v151 offset:6144
	ds_read_b128 v[208:211], v151 offset:7168
	global_load_lds_dwordx4 v[152:153], off
	v_lshl_add_u64 v[144:145], v[144:145], 0, s[58:59]
	s_mov_b32 m0, s84
	s_nop 0
	global_load_lds_dwordx4 v[144:145], off
	s_waitcnt vmcnt(8)
	s_waitcnt lgkmcnt(0)
	s_barrier
	s_waitcnt lgkmcnt(0)
	v_mfma_f32_16x16x32_bf16 v[124:127], v[128:131], v[180:183], v[124:127]
	v_mfma_f32_16x16x32_bf16 v[120:123], v[156:159], v[180:183], v[120:123]
	v_mfma_f32_16x16x32_bf16 v[116:119], v[128:131], v[188:191], v[116:119]
	v_mfma_f32_16x16x32_bf16 v[112:115], v[156:159], v[188:191], v[112:115]
	v_mfma_f32_16x16x32_bf16 v[108:111], v[128:131], v[196:199], v[108:111]
	v_mfma_f32_16x16x32_bf16 v[104:107], v[156:159], v[196:199], v[104:107]
	v_mfma_f32_16x16x32_bf16 v[100:103], v[128:131], v[204:207], v[100:103]
	v_mfma_f32_16x16x32_bf16 v[96:99], v[156:159], v[204:207], v[96:99]
	v_mfma_f32_16x16x32_bf16 v[124:127], v[132:135], v[184:187], v[124:127]
	v_mfma_f32_16x16x32_bf16 v[120:123], v[160:163], v[184:187], v[120:123]
	v_mfma_f32_16x16x32_bf16 v[116:119], v[132:135], v[192:195], v[116:119]
	v_mfma_f32_16x16x32_bf16 v[112:115], v[160:163], v[192:195], v[112:115]
	v_mfma_f32_16x16x32_bf16 v[108:111], v[132:135], v[200:203], v[108:111]
	v_mfma_f32_16x16x32_bf16 v[104:107], v[160:163], v[200:203], v[104:107]
	v_mfma_f32_16x16x32_bf16 v[100:103], v[132:135], v[208:211], v[100:103]
	v_mfma_f32_16x16x32_bf16 v[96:99], v[160:163], v[208:211], v[96:99]
	v_mfma_f32_16x16x32_bf16 v[68:71], v[164:167], v[180:183], v[68:71]
	v_mfma_f32_16x16x32_bf16 v[64:67], v[172:175], v[180:183], v[64:67]
	v_mfma_f32_16x16x32_bf16 v[56:59], v[164:167], v[188:191], v[56:59]
	v_mfma_f32_16x16x32_bf16 v[48:51], v[172:175], v[188:191], v[48:51]
	v_mfma_f32_16x16x32_bf16 v[44:47], v[164:167], v[196:199], v[44:47]
	v_mfma_f32_16x16x32_bf16 v[40:43], v[172:175], v[196:199], v[40:43]
	v_mfma_f32_16x16x32_bf16 v[36:39], v[164:167], v[204:207], v[36:39]
	v_mfma_f32_16x16x32_bf16 v[32:35], v[172:175], v[204:207], v[32:35]
	v_mfma_f32_16x16x32_bf16 v[68:71], v[168:171], v[184:187], v[68:71]
	v_mfma_f32_16x16x32_bf16 v[64:67], v[176:179], v[184:187], v[64:67]
	v_mfma_f32_16x16x32_bf16 v[56:59], v[168:171], v[192:195], v[56:59]
	v_mfma_f32_16x16x32_bf16 v[48:51], v[176:179], v[192:195], v[48:51]
	v_mfma_f32_16x16x32_bf16 v[44:47], v[168:171], v[200:203], v[44:47]
	v_mfma_f32_16x16x32_bf16 v[40:43], v[176:179], v[200:203], v[40:43]
	v_mfma_f32_16x16x32_bf16 v[36:39], v[168:171], v[208:211], v[36:39]
	v_mfma_f32_16x16x32_bf16 v[32:35], v[176:179], v[208:211], v[32:35]
	s_barrier
	s_mov_b32 m0, s83
	v_lshl_add_u64 v[144:145], s[2:3], 0, v[136:137]
	ds_read_b128 v[180:183], v151 offset:16384
	ds_read_b128 v[184:187], v151 offset:17408
	ds_read_b128 v[188:191], v151 offset:18432
	ds_read_b128 v[192:195], v151 offset:19456
	ds_read_b128 v[196:199], v151 offset:20480
	ds_read_b128 v[200:203], v151 offset:21504
	ds_read_b128 v[204:207], v151 offset:22528
	ds_read_b128 v[208:211], v151 offset:23552
	global_load_lds_dwordx4 v[144:145], off
	v_lshl_add_u64 v[152:153], v[144:145], 0, s[12:13]
	s_mov_b32 m0, s82
	s_nop 0
	global_load_lds_dwordx4 v[152:153], off
	v_lshl_add_u64 v[152:153], v[144:145], 0, s[14:15]
	s_mov_b32 m0, s81
	s_nop 0
	global_load_lds_dwordx4 v[152:153], off
	v_lshl_add_u64 v[152:153], v[144:145], 0, s[16:17]
	s_mov_b32 m0, s80
	s_nop 0
	global_load_lds_dwordx4 v[152:153], off
	v_lshl_add_u64 v[152:153], s[56:57], 0, v[138:139]
	s_mov_b32 m0, s49
	v_lshl_add_u64 v[212:213], v[152:153], 0, s[14:15]
	global_load_lds_dwordx4 v[152:153], off
	s_mov_b32 m0, s66
	s_nop 0
	global_load_lds_dwordx4 v[212:213], off
	s_waitcnt vmcnt(8)
	s_waitcnt lgkmcnt(0)
	s_barrier
	s_waitcnt lgkmcnt(0)
	v_mfma_f32_16x16x32_bf16 v[92:95], v[128:131], v[180:183], v[92:95]
	v_mfma_f32_16x16x32_bf16 v[88:91], v[156:159], v[180:183], v[88:91]
	v_mfma_f32_16x16x32_bf16 v[84:87], v[128:131], v[188:191], v[84:87]
	v_mfma_f32_16x16x32_bf16 v[80:83], v[156:159], v[188:191], v[80:83]
	v_mfma_f32_16x16x32_bf16 v[76:79], v[128:131], v[196:199], v[76:79]
	v_mfma_f32_16x16x32_bf16 v[72:75], v[156:159], v[196:199], v[72:75]
	v_mfma_f32_16x16x32_bf16 v[60:63], v[128:131], v[204:207], v[60:63]
	v_mfma_f32_16x16x32_bf16 v[52:55], v[156:159], v[204:207], v[52:55]
	v_mfma_f32_16x16x32_bf16 v[92:95], v[132:135], v[184:187], v[92:95]
	v_mfma_f32_16x16x32_bf16 v[88:91], v[160:163], v[184:187], v[88:91]
	v_mfma_f32_16x16x32_bf16 v[84:87], v[132:135], v[192:195], v[84:87]
	v_mfma_f32_16x16x32_bf16 v[80:83], v[160:163], v[192:195], v[80:83]
	v_mfma_f32_16x16x32_bf16 v[76:79], v[132:135], v[200:203], v[76:79]
	v_mfma_f32_16x16x32_bf16 v[72:75], v[160:163], v[200:203], v[72:75]
	v_mfma_f32_16x16x32_bf16 v[60:63], v[132:135], v[208:211], v[60:63]
	v_mfma_f32_16x16x32_bf16 v[52:55], v[160:163], v[208:211], v[52:55]
	v_mfma_f32_16x16x32_bf16 v[28:31], v[164:167], v[180:183], v[28:31]
	v_mfma_f32_16x16x32_bf16 v[24:27], v[172:175], v[180:183], v[24:27]
	v_mfma_f32_16x16x32_bf16 v[20:23], v[164:167], v[188:191], v[20:23]
	v_mfma_f32_16x16x32_bf16 v[16:19], v[172:175], v[188:191], v[16:19]
	v_mfma_f32_16x16x32_bf16 v[12:15], v[164:167], v[196:199], v[12:15]
	v_mfma_f32_16x16x32_bf16 v[8:11], v[172:175], v[196:199], v[8:11]
	v_mfma_f32_16x16x32_bf16 v[4:7], v[164:167], v[204:207], v[4:7]
	v_mfma_f32_16x16x32_bf16 v[0:3], v[172:175], v[204:207], v[0:3]
	v_mfma_f32_16x16x32_bf16 v[28:31], v[168:171], v[184:187], v[28:31]
	v_mfma_f32_16x16x32_bf16 v[24:27], v[176:179], v[184:187], v[24:27]
	v_mfma_f32_16x16x32_bf16 v[20:23], v[168:171], v[192:195], v[20:23]
	v_mfma_f32_16x16x32_bf16 v[16:19], v[176:179], v[192:195], v[16:19]
	v_mfma_f32_16x16x32_bf16 v[12:15], v[168:171], v[200:203], v[12:15]
	v_mfma_f32_16x16x32_bf16 v[8:11], v[176:179], v[200:203], v[8:11]
	v_mfma_f32_16x16x32_bf16 v[4:7], v[168:171], v[208:211], v[4:7]
	v_mfma_f32_16x16x32_bf16 v[0:3], v[176:179], v[208:211], v[0:3]
	s_barrier
	v_add_u32_e32 v155, s79, v147
	ds_read_b128 v[128:131], v155
	ds_read_b128 v[132:135], v155 offset:1024
	ds_read_b128 v[156:159], v155 offset:2048
	ds_read_b128 v[160:163], v155 offset:3072
	v_add_u32_e32 v155, s78, v147
	ds_read_b128 v[164:167], v155
	ds_read_b128 v[168:171], v155 offset:1024
	ds_read_b128 v[172:175], v155 offset:2048
	ds_read_b128 v[176:179], v155 offset:3072
	s_mov_b32 m0, s67
	v_lshl_add_u64 v[212:213], v[152:153], 0, s[18:19]
	ds_read_b128 v[180:183], v151 offset:32768
	ds_read_b128 v[184:187], v151 offset:33792
	ds_read_b128 v[188:191], v151 offset:34816
	ds_read_b128 v[192:195], v151 offset:35840
	ds_read_b128 v[196:199], v151 offset:36864
	ds_read_b128 v[200:203], v151 offset:37888
	ds_read_b128 v[204:207], v151 offset:38912
	ds_read_b128 v[208:211], v151 offset:39936
	global_load_lds_dwordx4 v[212:213], off
	v_lshl_add_u64 v[212:213], v[152:153], 0, s[22:23]
	s_mov_b32 m0, s68
	s_nop 0
	global_load_lds_dwordx4 v[212:213], off
	s_waitcnt vmcnt(8)
	s_waitcnt lgkmcnt(0)
	s_barrier
	s_waitcnt lgkmcnt(0)
	v_mfma_f32_16x16x32_bf16 v[124:127], v[128:131], v[180:183], v[124:127]
	v_mfma_f32_16x16x32_bf16 v[120:123], v[156:159], v[180:183], v[120:123]
	v_mfma_f32_16x16x32_bf16 v[116:119], v[128:131], v[188:191], v[116:119]
	v_mfma_f32_16x16x32_bf16 v[112:115], v[156:159], v[188:191], v[112:115]
	v_mfma_f32_16x16x32_bf16 v[108:111], v[128:131], v[196:199], v[108:111]
	v_mfma_f32_16x16x32_bf16 v[104:107], v[156:159], v[196:199], v[104:107]
	v_mfma_f32_16x16x32_bf16 v[100:103], v[128:131], v[204:207], v[100:103]
	v_mfma_f32_16x16x32_bf16 v[96:99], v[156:159], v[204:207], v[96:99]
	v_mfma_f32_16x16x32_bf16 v[124:127], v[132:135], v[184:187], v[124:127]
	v_mfma_f32_16x16x32_bf16 v[120:123], v[160:163], v[184:187], v[120:123]
	v_mfma_f32_16x16x32_bf16 v[116:119], v[132:135], v[192:195], v[116:119]
	v_mfma_f32_16x16x32_bf16 v[112:115], v[160:163], v[192:195], v[112:115]
	v_mfma_f32_16x16x32_bf16 v[108:111], v[132:135], v[200:203], v[108:111]
	v_mfma_f32_16x16x32_bf16 v[104:107], v[160:163], v[200:203], v[104:107]
	v_mfma_f32_16x16x32_bf16 v[100:103], v[132:135], v[208:211], v[100:103]
	v_mfma_f32_16x16x32_bf16 v[96:99], v[160:163], v[208:211], v[96:99]
	v_mfma_f32_16x16x32_bf16 v[68:71], v[164:167], v[180:183], v[68:71]
	v_mfma_f32_16x16x32_bf16 v[64:67], v[172:175], v[180:183], v[64:67]
	v_mfma_f32_16x16x32_bf16 v[56:59], v[164:167], v[188:191], v[56:59]
	v_mfma_f32_16x16x32_bf16 v[48:51], v[172:175], v[188:191], v[48:51]
	v_mfma_f32_16x16x32_bf16 v[44:47], v[164:167], v[196:199], v[44:47]
	v_mfma_f32_16x16x32_bf16 v[40:43], v[172:175], v[196:199], v[40:43]
	v_mfma_f32_16x16x32_bf16 v[36:39], v[164:167], v[204:207], v[36:39]
	v_mfma_f32_16x16x32_bf16 v[32:35], v[172:175], v[204:207], v[32:35]
	v_mfma_f32_16x16x32_bf16 v[68:71], v[168:171], v[184:187], v[68:71]
	v_mfma_f32_16x16x32_bf16 v[64:67], v[176:179], v[184:187], v[64:67]
	v_mfma_f32_16x16x32_bf16 v[56:59], v[168:171], v[192:195], v[56:59]
	v_mfma_f32_16x16x32_bf16 v[48:51], v[176:179], v[192:195], v[48:51]
	v_mfma_f32_16x16x32_bf16 v[44:47], v[168:171], v[200:203], v[44:47]
	v_mfma_f32_16x16x32_bf16 v[40:43], v[176:179], v[200:203], v[40:43]
	v_mfma_f32_16x16x32_bf16 v[36:39], v[168:171], v[208:211], v[36:39]
	v_mfma_f32_16x16x32_bf16 v[32:35], v[176:179], v[208:211], v[32:35]
	s_barrier
	s_mov_b32 m0, s77
	v_lshl_add_u64 v[212:213], v[144:145], 0, s[30:31]
	ds_read_b128 v[180:183], v151 offset:49152
	ds_read_b128 v[184:187], v151 offset:50176
	ds_read_b128 v[188:191], v151 offset:51200
	ds_read_b128 v[192:195], v151 offset:52224
	ds_read_b128 v[196:199], v151 offset:53248
	ds_read_b128 v[200:203], v151 offset:54272
	ds_read_b128 v[204:207], v151 offset:55296
	ds_read_b128 v[208:211], v151 offset:56320
	global_load_lds_dwordx4 v[212:213], off
	v_lshl_add_u64 v[212:213], v[144:145], 0, s[34:35]
	s_mov_b32 m0, s76
	s_nop 0
	global_load_lds_dwordx4 v[212:213], off
	v_lshl_add_u64 v[212:213], v[144:145], 0, s[36:37]
	s_mov_b32 m0, s61
	v_lshl_add_u64 v[144:145], v[144:145], 0, s[38:39]
	global_load_lds_dwordx4 v[212:213], off
	s_mov_b32 m0, s60
	s_nop 0
	global_load_lds_dwordx4 v[144:145], off
	v_lshl_add_u64 v[144:145], v[152:153], 0, s[30:31]
	s_mov_b32 m0, s70
	s_nop 0
	global_load_lds_dwordx4 v[144:145], off
	v_lshl_add_u64 v[144:145], v[152:153], 0, s[36:37]
	s_mov_b32 m0, s71
	s_nop 0
	global_load_lds_dwordx4 v[144:145], off
	s_waitcnt vmcnt(8)
	s_waitcnt lgkmcnt(0)
	s_barrier
	s_waitcnt lgkmcnt(0)
	v_mfma_f32_16x16x32_bf16 v[92:95], v[128:131], v[180:183], v[92:95]
	v_mfma_f32_16x16x32_bf16 v[88:91], v[156:159], v[180:183], v[88:91]
	v_mfma_f32_16x16x32_bf16 v[84:87], v[128:131], v[188:191], v[84:87]
	v_mfma_f32_16x16x32_bf16 v[80:83], v[156:159], v[188:191], v[80:83]
	v_mfma_f32_16x16x32_bf16 v[76:79], v[128:131], v[196:199], v[76:79]
	v_mfma_f32_16x16x32_bf16 v[72:75], v[156:159], v[196:199], v[72:75]
	v_mfma_f32_16x16x32_bf16 v[60:63], v[128:131], v[204:207], v[60:63]
	v_mfma_f32_16x16x32_bf16 v[52:55], v[156:159], v[204:207], v[52:55]
	v_mfma_f32_16x16x32_bf16 v[92:95], v[132:135], v[184:187], v[92:95]
	v_mfma_f32_16x16x32_bf16 v[88:91], v[160:163], v[184:187], v[88:91]
	v_mfma_f32_16x16x32_bf16 v[84:87], v[132:135], v[192:195], v[84:87]
	v_mfma_f32_16x16x32_bf16 v[80:83], v[160:163], v[192:195], v[80:83]
	v_mfma_f32_16x16x32_bf16 v[76:79], v[132:135], v[200:203], v[76:79]
	v_mfma_f32_16x16x32_bf16 v[72:75], v[160:163], v[200:203], v[72:75]
	v_mfma_f32_16x16x32_bf16 v[60:63], v[132:135], v[208:211], v[60:63]
	v_mfma_f32_16x16x32_bf16 v[52:55], v[160:163], v[208:211], v[52:55]
	v_mfma_f32_16x16x32_bf16 v[28:31], v[164:167], v[180:183], v[28:31]
	v_mfma_f32_16x16x32_bf16 v[24:27], v[172:175], v[180:183], v[24:27]
	v_mfma_f32_16x16x32_bf16 v[20:23], v[164:167], v[188:191], v[20:23]
	v_mfma_f32_16x16x32_bf16 v[16:19], v[172:175], v[188:191], v[16:19]
	v_mfma_f32_16x16x32_bf16 v[12:15], v[164:167], v[196:199], v[12:15]
	v_mfma_f32_16x16x32_bf16 v[8:11], v[172:175], v[196:199], v[8:11]
	v_mfma_f32_16x16x32_bf16 v[4:7], v[164:167], v[204:207], v[4:7]
	v_mfma_f32_16x16x32_bf16 v[0:3], v[172:175], v[204:207], v[0:3]
	v_mfma_f32_16x16x32_bf16 v[28:31], v[168:171], v[184:187], v[28:31]
	v_mfma_f32_16x16x32_bf16 v[24:27], v[176:179], v[184:187], v[24:27]
	v_mfma_f32_16x16x32_bf16 v[20:23], v[168:171], v[192:195], v[20:23]
	v_mfma_f32_16x16x32_bf16 v[16:19], v[176:179], v[192:195], v[16:19]
	v_mfma_f32_16x16x32_bf16 v[12:15], v[168:171], v[200:203], v[12:15]
	v_mfma_f32_16x16x32_bf16 v[8:11], v[176:179], v[200:203], v[8:11]
	v_mfma_f32_16x16x32_bf16 v[4:7], v[168:171], v[208:211], v[4:7]
	v_mfma_f32_16x16x32_bf16 v[0:3], v[176:179], v[208:211], v[0:3]
	s_barrier
	s_movk_i32 s60, 0x100
	s_andn2_b64 vcc, exec, s[54:55]
	s_mov_b64 s[2:3], -1
	s_mov_b64 s[54:55], 0
	s_cbranch_vccz .LBB0_595
	s_and_b64 vcc, exec, s[40:41]
	s_cbranch_vccz .LBB0_598
	s_barrier

.LBB0_614:
	s_add_u32 s54, s48, s60
	s_addc_u32 s55, s49, 0
	s_add_u32 s61, s54, 0x100
	ds_read_b128 v[138:141], v135
	ds_read_b128 v[142:145], v135 offset:1024
	ds_read_b128 v[146:149], v135 offset:2048
	ds_read_b128 v[150:153], v135 offset:3072
	ds_read_b128 v[156:159], v136
	ds_read_b128 v[160:163], v136 offset:1024
	ds_read_b128 v[164:167], v136 offset:2048
	ds_read_b128 v[168:171], v136 offset:3072
	s_addc_u32 s75, s55, 0
	s_and_b64 s[52:53], s[2:3], exec
	s_cselect_b32 s52, s73, s61
	s_cselect_b32 s53, s39, s75
	s_add_u32 s60, s44, s60
	s_addc_u32 s61, s45, 0
	s_add_u32 s60, s60, 0x100
	s_addc_u32 s61, s61, 0
	s_and_b64 s[2:3], s[2:3], exec
	s_cselect_b32 s2, s74, s60
	s_cselect_b32 s3, s37, s61
	s_add_i32 s77, 0, 0x1c000
	s_add_i32 s78, 0, 0x18000
	s_add_i32 s61, s77, s58
	s_add_i32 s82, s68, s58
	s_add_i32 s80, s69, s58
	s_add_i32 s76, s78, s58
	s_add_i32 s60, s61, 0x2000
	s_add_i32 m0, s59, 0xc000
	s_add_i32 s83, s59, 0xe000
	s_add_i32 s81, s82, 0x2000
	s_add_i32 s79, s80, 0x2000
	s_add_i32 s75, s76, 0x2000
	v_lshl_add_u64 v[204:205], s[54:55], 0, v[128:129]
	v_lshl_add_u64 v[206:207], v[204:205], 0, s[24:25]
	ds_read_b128 v[172:175], v137
	ds_read_b128 v[176:179], v137 offset:1024
	ds_read_b128 v[180:183], v137 offset:2048
	ds_read_b128 v[184:187], v137 offset:3072
	ds_read_b128 v[188:191], v137 offset:4096
	ds_read_b128 v[192:195], v137 offset:5120
	ds_read_b128 v[196:199], v137 offset:6144
	ds_read_b128 v[200:203], v137 offset:7168
	global_load_lds_dwordx4 v[206:207], off
	v_lshl_add_u64 v[204:205], v[204:205], 0, s[28:29]
	s_mov_b32 m0, s83
	s_nop 0
	global_load_lds_dwordx4 v[204:205], off
	s_waitcnt vmcnt(8)
	s_waitcnt lgkmcnt(0)
	s_barrier
	s_waitcnt lgkmcnt(0)
	v_mfma_f32_16x16x32_bf16 v[124:127], v[138:141], v[172:175], v[124:127]
	v_mfma_f32_16x16x32_bf16 v[120:123], v[146:149], v[172:175], v[120:123]
	v_mfma_f32_16x16x32_bf16 v[116:119], v[138:141], v[180:183], v[116:119]
	v_mfma_f32_16x16x32_bf16 v[112:115], v[146:149], v[180:183], v[112:115]
	v_mfma_f32_16x16x32_bf16 v[100:103], v[138:141], v[188:191], v[100:103]
	v_mfma_f32_16x16x32_bf16 v[96:99], v[146:149], v[188:191], v[96:99]
	v_mfma_f32_16x16x32_bf16 v[84:87], v[138:141], v[196:199], v[84:87]
	v_mfma_f32_16x16x32_bf16 v[80:83], v[146:149], v[196:199], v[80:83]
	v_mfma_f32_16x16x32_bf16 v[124:127], v[142:145], v[176:179], v[124:127]
	v_mfma_f32_16x16x32_bf16 v[120:123], v[150:153], v[176:179], v[120:123]
	v_mfma_f32_16x16x32_bf16 v[116:119], v[142:145], v[184:187], v[116:119]
	v_mfma_f32_16x16x32_bf16 v[112:115], v[150:153], v[184:187], v[112:115]
	v_mfma_f32_16x16x32_bf16 v[100:103], v[142:145], v[192:195], v[100:103]
	v_mfma_f32_16x16x32_bf16 v[96:99], v[150:153], v[192:195], v[96:99]
	v_mfma_f32_16x16x32_bf16 v[84:87], v[142:145], v[200:203], v[84:87]
	v_mfma_f32_16x16x32_bf16 v[80:83], v[150:153], v[200:203], v[80:83]
	v_mfma_f32_16x16x32_bf16 v[108:111], v[156:159], v[172:175], v[108:111]
	v_mfma_f32_16x16x32_bf16 v[104:107], v[164:167], v[172:175], v[104:107]
	v_mfma_f32_16x16x32_bf16 v[92:95], v[156:159], v[180:183], v[92:95]
	v_mfma_f32_16x16x32_bf16 v[88:91], v[164:167], v[180:183], v[88:91]
	v_mfma_f32_16x16x32_bf16 v[76:79], v[156:159], v[188:191], v[76:79]
	v_mfma_f32_16x16x32_bf16 v[72:75], v[164:167], v[188:191], v[72:75]
	v_mfma_f32_16x16x32_bf16 v[68:71], v[156:159], v[196:199], v[68:71]
	v_mfma_f32_16x16x32_bf16 v[64:67], v[164:167], v[196:199], v[64:67]
	v_mfma_f32_16x16x32_bf16 v[108:111], v[160:163], v[176:179], v[108:111]
	v_mfma_f32_16x16x32_bf16 v[104:107], v[168:171], v[176:179], v[104:107]
	v_mfma_f32_16x16x32_bf16 v[92:95], v[160:163], v[184:187], v[92:95]
	v_mfma_f32_16x16x32_bf16 v[88:91], v[168:171], v[184:187], v[88:91]
	v_mfma_f32_16x16x32_bf16 v[76:79], v[160:163], v[192:195], v[76:79]
	v_mfma_f32_16x16x32_bf16 v[72:75], v[168:171], v[192:195], v[72:75]
	v_mfma_f32_16x16x32_bf16 v[68:71], v[160:163], v[200:203], v[68:71]
	v_mfma_f32_16x16x32_bf16 v[64:67], v[168:171], v[200:203], v[64:67]
	s_barrier
	s_mov_b32 m0, s82
	v_lshl_add_u64 v[204:205], s[2:3], 0, v[130:131]
	ds_read_b128 v[172:175], v137 offset:16384
	ds_read_b128 v[176:179], v137 offset:17408
	ds_read_b128 v[180:183], v137 offset:18432
	ds_read_b128 v[184:187], v137 offset:19456
	ds_read_b128 v[188:191], v137 offset:20480
	ds_read_b128 v[192:195], v137 offset:21504
	ds_read_b128 v[196:199], v137 offset:22528
	ds_read_b128 v[200:203], v137 offset:23552
	global_load_lds_dwordx4 v[204:205], off
	v_lshl_add_u64 v[206:207], v[204:205], 0, s[4:5]
	s_mov_b32 m0, s81
	s_nop 0
	global_load_lds_dwordx4 v[206:207], off
	v_lshl_add_u64 v[206:207], v[204:205], 0, s[6:7]
	s_mov_b32 m0, s80
	s_nop 0
	global_load_lds_dwordx4 v[206:207], off
	v_lshl_add_u64 v[206:207], v[204:205], 0, s[12:13]
	s_mov_b32 m0, s79
	s_nop 0
	global_load_lds_dwordx4 v[206:207], off
	v_lshl_add_u64 v[206:207], s[52:53], 0, v[128:129]
	s_mov_b32 m0, s59
	v_lshl_add_u64 v[208:209], v[206:207], 0, s[4:5]
	global_load_lds_dwordx4 v[206:207], off
	s_mov_b32 m0, s62
	s_nop 0
	global_load_lds_dwordx4 v[208:209], off
	s_waitcnt vmcnt(8)
	s_waitcnt lgkmcnt(0)
	s_barrier
	s_waitcnt lgkmcnt(0)
	v_mfma_f32_16x16x32_bf16 v[60:63], v[138:141], v[172:175], v[60:63]
	v_mfma_f32_16x16x32_bf16 v[56:59], v[146:149], v[172:175], v[56:59]
	v_mfma_f32_16x16x32_bf16 v[52:55], v[138:141], v[180:183], v[52:55]
	v_mfma_f32_16x16x32_bf16 v[48:51], v[146:149], v[180:183], v[48:51]
	v_mfma_f32_16x16x32_bf16 v[36:39], v[138:141], v[188:191], v[36:39]
	v_mfma_f32_16x16x32_bf16 v[32:35], v[146:149], v[188:191], v[32:35]
	v_mfma_f32_16x16x32_bf16 v[20:23], v[138:141], v[196:199], v[20:23]
	v_mfma_f32_16x16x32_bf16 v[16:19], v[146:149], v[196:199], v[16:19]
	v_mfma_f32_16x16x32_bf16 v[60:63], v[142:145], v[176:179], v[60:63]
	v_mfma_f32_16x16x32_bf16 v[56:59], v[150:153], v[176:179], v[56:59]
	v_mfma_f32_16x16x32_bf16 v[52:55], v[142:145], v[184:187], v[52:55]
	v_mfma_f32_16x16x32_bf16 v[48:51], v[150:153], v[184:187], v[48:51]
	v_mfma_f32_16x16x32_bf16 v[36:39], v[142:145], v[192:195], v[36:39]
	v_mfma_f32_16x16x32_bf16 v[32:35], v[150:153], v[192:195], v[32:35]
	v_mfma_f32_16x16x32_bf16 v[20:23], v[142:145], v[200:203], v[20:23]
	v_mfma_f32_16x16x32_bf16 v[16:19], v[150:153], v[200:203], v[16:19]
	v_mfma_f32_16x16x32_bf16 v[44:47], v[156:159], v[172:175], v[44:47]
	v_mfma_f32_16x16x32_bf16 v[40:43], v[164:167], v[172:175], v[40:43]
	v_mfma_f32_16x16x32_bf16 v[28:31], v[156:159], v[180:183], v[28:31]
	v_mfma_f32_16x16x32_bf16 v[24:27], v[164:167], v[180:183], v[24:27]
	v_mfma_f32_16x16x32_bf16 v[12:15], v[156:159], v[188:191], v[12:15]
	v_mfma_f32_16x16x32_bf16 v[8:11], v[164:167], v[188:191], v[8:11]
	v_mfma_f32_16x16x32_bf16 v[4:7], v[156:159], v[196:199], v[4:7]
	v_mfma_f32_16x16x32_bf16 v[0:3], v[164:167], v[196:199], v[0:3]
	v_mfma_f32_16x16x32_bf16 v[44:47], v[160:163], v[176:179], v[44:47]
	v_mfma_f32_16x16x32_bf16 v[40:43], v[168:171], v[176:179], v[40:43]
	v_mfma_f32_16x16x32_bf16 v[28:31], v[160:163], v[184:187], v[28:31]
	v_mfma_f32_16x16x32_bf16 v[24:27], v[168:171], v[184:187], v[24:27]
	v_mfma_f32_16x16x32_bf16 v[12:15], v[160:163], v[192:195], v[12:15]
	v_mfma_f32_16x16x32_bf16 v[8:11], v[168:171], v[192:195], v[8:11]
	v_mfma_f32_16x16x32_bf16 v[4:7], v[160:163], v[200:203], v[4:7]
	v_mfma_f32_16x16x32_bf16 v[0:3], v[168:171], v[200:203], v[0:3]
	s_barrier
	v_add_u32_e32 v150, s78, v133
	v_add_u32_e32 v155, s77, v133
	ds_read_b128 v[138:141], v150
	ds_read_b128 v[142:145], v150 offset:1024
	ds_read_b128 v[146:149], v150 offset:2048
	ds_read_b128 v[150:153], v150 offset:3072
	ds_read_b128 v[156:159], v155
	ds_read_b128 v[160:163], v155 offset:1024
	ds_read_b128 v[164:167], v155 offset:2048
	ds_read_b128 v[168:171], v155 offset:3072
	s_mov_b32 m0, s65
	v_lshl_add_u64 v[208:209], v[206:207], 0, s[6:7]
	ds_read_b128 v[172:175], v137 offset:32768
	ds_read_b128 v[176:179], v137 offset:33792
	ds_read_b128 v[180:183], v137 offset:34816
	ds_read_b128 v[184:187], v137 offset:35840
	ds_read_b128 v[188:191], v137 offset:36864
	ds_read_b128 v[192:195], v137 offset:37888
	ds_read_b128 v[196:199], v137 offset:38912
	ds_read_b128 v[200:203], v137 offset:39936
	global_load_lds_dwordx4 v[208:209], off
	v_lshl_add_u64 v[208:209], v[206:207], 0, s[12:13]
	s_mov_b32 m0, s66
	s_nop 0
	global_load_lds_dwordx4 v[208:209], off
	s_waitcnt vmcnt(8)
	s_waitcnt lgkmcnt(0)
	s_barrier
	s_waitcnt lgkmcnt(0)
	v_mfma_f32_16x16x32_bf16 v[124:127], v[138:141], v[172:175], v[124:127]
	v_mfma_f32_16x16x32_bf16 v[120:123], v[146:149], v[172:175], v[120:123]
	v_mfma_f32_16x16x32_bf16 v[116:119], v[138:141], v[180:183], v[116:119]
	v_mfma_f32_16x16x32_bf16 v[112:115], v[146:149], v[180:183], v[112:115]
	v_mfma_f32_16x16x32_bf16 v[100:103], v[138:141], v[188:191], v[100:103]
	v_mfma_f32_16x16x32_bf16 v[96:99], v[146:149], v[188:191], v[96:99]
	v_mfma_f32_16x16x32_bf16 v[84:87], v[138:141], v[196:199], v[84:87]
	v_mfma_f32_16x16x32_bf16 v[80:83], v[146:149], v[196:199], v[80:83]
	v_mfma_f32_16x16x32_bf16 v[124:127], v[142:145], v[176:179], v[124:127]
	v_mfma_f32_16x16x32_bf16 v[120:123], v[150:153], v[176:179], v[120:123]
	v_mfma_f32_16x16x32_bf16 v[116:119], v[142:145], v[184:187], v[116:119]
	v_mfma_f32_16x16x32_bf16 v[112:115], v[150:153], v[184:187], v[112:115]
	v_mfma_f32_16x16x32_bf16 v[100:103], v[142:145], v[192:195], v[100:103]
	v_mfma_f32_16x16x32_bf16 v[96:99], v[150:153], v[192:195], v[96:99]
	v_mfma_f32_16x16x32_bf16 v[84:87], v[142:145], v[200:203], v[84:87]
	v_mfma_f32_16x16x32_bf16 v[80:83], v[150:153], v[200:203], v[80:83]
	v_mfma_f32_16x16x32_bf16 v[108:111], v[156:159], v[172:175], v[108:111]
	v_mfma_f32_16x16x32_bf16 v[104:107], v[164:167], v[172:175], v[104:107]
	v_mfma_f32_16x16x32_bf16 v[92:95], v[156:159], v[180:183], v[92:95]
	v_mfma_f32_16x16x32_bf16 v[88:91], v[164:167], v[180:183], v[88:91]
	v_mfma_f32_16x16x32_bf16 v[76:79], v[156:159], v[188:191], v[76:79]
	v_mfma_f32_16x16x32_bf16 v[72:75], v[164:167], v[188:191], v[72:75]
	v_mfma_f32_16x16x32_bf16 v[68:71], v[156:159], v[196:199], v[68:71]
	v_mfma_f32_16x16x32_bf16 v[64:67], v[164:167], v[196:199], v[64:67]
	v_mfma_f32_16x16x32_bf16 v[108:111], v[160:163], v[176:179], v[108:111]
	v_mfma_f32_16x16x32_bf16 v[104:107], v[168:171], v[176:179], v[104:107]
	v_mfma_f32_16x16x32_bf16 v[92:95], v[160:163], v[184:187], v[92:95]
	v_mfma_f32_16x16x32_bf16 v[88:91], v[168:171], v[184:187], v[88:91]
	v_mfma_f32_16x16x32_bf16 v[76:79], v[160:163], v[192:195], v[76:79]
	v_mfma_f32_16x16x32_bf16 v[72:75], v[168:171], v[192:195], v[72:75]
	v_mfma_f32_16x16x32_bf16 v[68:71], v[160:163], v[200:203], v[68:71]
	v_mfma_f32_16x16x32_bf16 v[64:67], v[168:171], v[200:203], v[64:67]
	s_barrier
	s_mov_b32 m0, s76
	v_lshl_add_u64 v[208:209], v[204:205], 0, s[18:19]
	ds_read_b128 v[172:175], v137 offset:49152
	ds_read_b128 v[176:179], v137 offset:50176
	ds_read_b128 v[180:183], v137 offset:51200
	ds_read_b128 v[184:187], v137 offset:52224
	ds_read_b128 v[188:191], v137 offset:53248
	ds_read_b128 v[192:195], v137 offset:54272
	ds_read_b128 v[196:199], v137 offset:55296
	ds_read_b128 v[200:203], v137 offset:56320
	global_load_lds_dwordx4 v[208:209], off
	v_lshl_add_u64 v[208:209], v[204:205], 0, s[22:23]
	s_mov_b32 m0, s75
	s_nop 0
	global_load_lds_dwordx4 v[208:209], off
	v_lshl_add_u64 v[208:209], v[204:205], 0, s[24:25]
	s_mov_b32 m0, s61
	v_lshl_add_u64 v[204:205], v[204:205], 0, s[28:29]
	global_load_lds_dwordx4 v[208:209], off
	s_mov_b32 m0, s60
	s_nop 0
	global_load_lds_dwordx4 v[204:205], off
	v_lshl_add_u64 v[204:205], v[206:207], 0, s[18:19]
	s_mov_b32 m0, s34
	s_nop 0
	global_load_lds_dwordx4 v[204:205], off
	v_lshl_add_u64 v[204:205], v[206:207], 0, s[22:23]
	s_mov_b32 m0, s67
	s_nop 0
	global_load_lds_dwordx4 v[204:205], off
	s_waitcnt vmcnt(8)
	s_waitcnt lgkmcnt(0)
	s_barrier
	s_waitcnt lgkmcnt(0)
	v_mfma_f32_16x16x32_bf16 v[60:63], v[138:141], v[172:175], v[60:63]
	v_mfma_f32_16x16x32_bf16 v[56:59], v[146:149], v[172:175], v[56:59]
	v_mfma_f32_16x16x32_bf16 v[52:55], v[138:141], v[180:183], v[52:55]
	v_mfma_f32_16x16x32_bf16 v[48:51], v[146:149], v[180:183], v[48:51]
	v_mfma_f32_16x16x32_bf16 v[36:39], v[138:141], v[188:191], v[36:39]
	v_mfma_f32_16x16x32_bf16 v[32:35], v[146:149], v[188:191], v[32:35]
	v_mfma_f32_16x16x32_bf16 v[20:23], v[138:141], v[196:199], v[20:23]
	v_mfma_f32_16x16x32_bf16 v[16:19], v[146:149], v[196:199], v[16:19]
	v_mfma_f32_16x16x32_bf16 v[60:63], v[142:145], v[176:179], v[60:63]
	v_mfma_f32_16x16x32_bf16 v[56:59], v[150:153], v[176:179], v[56:59]
	v_mfma_f32_16x16x32_bf16 v[52:55], v[142:145], v[184:187], v[52:55]
	v_mfma_f32_16x16x32_bf16 v[48:51], v[150:153], v[184:187], v[48:51]
	v_mfma_f32_16x16x32_bf16 v[36:39], v[142:145], v[192:195], v[36:39]
	v_mfma_f32_16x16x32_bf16 v[32:35], v[150:153], v[192:195], v[32:35]
	v_mfma_f32_16x16x32_bf16 v[20:23], v[142:145], v[200:203], v[20:23]
	v_mfma_f32_16x16x32_bf16 v[16:19], v[150:153], v[200:203], v[16:19]
	v_mfma_f32_16x16x32_bf16 v[44:47], v[156:159], v[172:175], v[44:47]
	v_mfma_f32_16x16x32_bf16 v[40:43], v[164:167], v[172:175], v[40:43]
	v_mfma_f32_16x16x32_bf16 v[28:31], v[156:159], v[180:183], v[28:31]
	v_mfma_f32_16x16x32_bf16 v[24:27], v[164:167], v[180:183], v[24:27]
	v_mfma_f32_16x16x32_bf16 v[12:15], v[156:159], v[188:191], v[12:15]
	v_mfma_f32_16x16x32_bf16 v[8:11], v[164:167], v[188:191], v[8:11]
	v_mfma_f32_16x16x32_bf16 v[4:7], v[156:159], v[196:199], v[4:7]
	v_mfma_f32_16x16x32_bf16 v[0:3], v[164:167], v[196:199], v[0:3]
	v_mfma_f32_16x16x32_bf16 v[44:47], v[160:163], v[176:179], v[44:47]
	v_mfma_f32_16x16x32_bf16 v[40:43], v[168:171], v[176:179], v[40:43]
	v_mfma_f32_16x16x32_bf16 v[28:31], v[160:163], v[184:187], v[28:31]
	v_mfma_f32_16x16x32_bf16 v[24:27], v[168:171], v[184:187], v[24:27]
	v_mfma_f32_16x16x32_bf16 v[12:15], v[160:163], v[192:195], v[12:15]
	v_mfma_f32_16x16x32_bf16 v[8:11], v[168:171], v[192:195], v[8:11]
	v_mfma_f32_16x16x32_bf16 v[4:7], v[160:163], v[200:203], v[4:7]
	v_mfma_f32_16x16x32_bf16 v[0:3], v[168:171], v[200:203], v[0:3]
	s_barrier
	s_movk_i32 s60, 0x100
	s_andn2_b64 vcc, exec, s[50:51]
	s_mov_b64 s[2:3], -1
	s_mov_b64 s[50:51], 0
	s_cbranch_vccz .LBB0_614
	s_and_b64 vcc, exec, s[30:31]
	s_cbranch_vccz .LBB0_617
	s_barrier

.LBB0_629:
	s_add_u32 s54, s44, s60
	s_addc_u32 s55, s45, 0
	s_add_u32 s61, s54, 0x100
	ds_read_b128 v[138:141], v135
	ds_read_b128 v[142:145], v135 offset:1024
	ds_read_b128 v[146:149], v135 offset:2048
	ds_read_b128 v[150:153], v135 offset:3072
	ds_read_b128 v[156:159], v136
	ds_read_b128 v[160:163], v136 offset:1024
	ds_read_b128 v[164:167], v136 offset:2048
	ds_read_b128 v[168:171], v136 offset:3072
	s_addc_u32 s76, s55, 0
	s_and_b64 s[52:53], s[2:3], exec
	s_cselect_b32 s52, s74, s61
	s_cselect_b32 s53, s39, s76
	s_add_u32 s60, s48, s60
	s_addc_u32 s61, s49, 0
	s_add_u32 s60, s60, 0x100
	s_addc_u32 s61, s61, 0
	s_and_b64 s[2:3], s[2:3], exec
	s_cselect_b32 s2, s75, s60
	s_cselect_b32 s3, s37, s61
	s_add_i32 s78, 0, 0x1c000
	s_add_i32 s79, 0, 0x18000
	s_add_i32 s61, s78, s57
	s_add_i32 s83, s67, s57
	s_add_i32 s81, s68, s57
	s_add_i32 s77, s79, s57
	s_add_i32 s60, s61, 0x2000
	s_add_i32 m0, s27, 0xc000
	s_add_i32 s84, s27, 0xe000
	s_add_i32 s82, s83, 0x2000
	s_add_i32 s80, s81, 0x2000
	s_add_i32 s76, s77, 0x2000
	v_lshl_add_u64 v[204:205], s[54:55], 0, v[128:129]
	v_lshl_add_u64 v[206:207], v[204:205], 0, s[24:25]
	ds_read_b128 v[172:175], v137
	ds_read_b128 v[176:179], v137 offset:1024
	ds_read_b128 v[180:183], v137 offset:2048
	ds_read_b128 v[184:187], v137 offset:3072
	ds_read_b128 v[188:191], v137 offset:4096
	ds_read_b128 v[192:195], v137 offset:5120
	ds_read_b128 v[196:199], v137 offset:6144
	ds_read_b128 v[200:203], v137 offset:7168
	global_load_lds_dwordx4 v[206:207], off
	v_lshl_add_u64 v[204:205], v[204:205], 0, s[28:29]
	s_mov_b32 m0, s84
	s_nop 0
	global_load_lds_dwordx4 v[204:205], off
	s_waitcnt vmcnt(8)
	s_waitcnt lgkmcnt(0)
	s_barrier
	s_waitcnt lgkmcnt(0)
	v_mfma_f32_16x16x32_bf16 v[124:127], v[138:141], v[172:175], v[124:127]
	v_mfma_f32_16x16x32_bf16 v[120:123], v[146:149], v[172:175], v[120:123]
	v_mfma_f32_16x16x32_bf16 v[116:119], v[138:141], v[180:183], v[116:119]
	v_mfma_f32_16x16x32_bf16 v[112:115], v[146:149], v[180:183], v[112:115]
	v_mfma_f32_16x16x32_bf16 v[100:103], v[138:141], v[188:191], v[100:103]
	v_mfma_f32_16x16x32_bf16 v[96:99], v[146:149], v[188:191], v[96:99]
	v_mfma_f32_16x16x32_bf16 v[84:87], v[138:141], v[196:199], v[84:87]
	v_mfma_f32_16x16x32_bf16 v[80:83], v[146:149], v[196:199], v[80:83]
	v_mfma_f32_16x16x32_bf16 v[124:127], v[142:145], v[176:179], v[124:127]
	v_mfma_f32_16x16x32_bf16 v[120:123], v[150:153], v[176:179], v[120:123]
	v_mfma_f32_16x16x32_bf16 v[116:119], v[142:145], v[184:187], v[116:119]
	v_mfma_f32_16x16x32_bf16 v[112:115], v[150:153], v[184:187], v[112:115]
	v_mfma_f32_16x16x32_bf16 v[100:103], v[142:145], v[192:195], v[100:103]
	v_mfma_f32_16x16x32_bf16 v[96:99], v[150:153], v[192:195], v[96:99]
	v_mfma_f32_16x16x32_bf16 v[84:87], v[142:145], v[200:203], v[84:87]
	v_mfma_f32_16x16x32_bf16 v[80:83], v[150:153], v[200:203], v[80:83]
	v_mfma_f32_16x16x32_bf16 v[108:111], v[156:159], v[172:175], v[108:111]
	v_mfma_f32_16x16x32_bf16 v[104:107], v[164:167], v[172:175], v[104:107]
	v_mfma_f32_16x16x32_bf16 v[92:95], v[156:159], v[180:183], v[92:95]
	v_mfma_f32_16x16x32_bf16 v[88:91], v[164:167], v[180:183], v[88:91]
	v_mfma_f32_16x16x32_bf16 v[76:79], v[156:159], v[188:191], v[76:79]
	v_mfma_f32_16x16x32_bf16 v[72:75], v[164:167], v[188:191], v[72:75]
	v_mfma_f32_16x16x32_bf16 v[68:71], v[156:159], v[196:199], v[68:71]
	v_mfma_f32_16x16x32_bf16 v[64:67], v[164:167], v[196:199], v[64:67]
	v_mfma_f32_16x16x32_bf16 v[108:111], v[160:163], v[176:179], v[108:111]
	v_mfma_f32_16x16x32_bf16 v[104:107], v[168:171], v[176:179], v[104:107]
	v_mfma_f32_16x16x32_bf16 v[92:95], v[160:163], v[184:187], v[92:95]
	v_mfma_f32_16x16x32_bf16 v[88:91], v[168:171], v[184:187], v[88:91]
	v_mfma_f32_16x16x32_bf16 v[76:79], v[160:163], v[192:195], v[76:79]
	v_mfma_f32_16x16x32_bf16 v[72:75], v[168:171], v[192:195], v[72:75]
	v_mfma_f32_16x16x32_bf16 v[68:71], v[160:163], v[200:203], v[68:71]
	v_mfma_f32_16x16x32_bf16 v[64:67], v[168:171], v[200:203], v[64:67]
	s_barrier
	s_mov_b32 m0, s83
	v_lshl_add_u64 v[204:205], s[2:3], 0, v[130:131]
	ds_read_b128 v[172:175], v137 offset:16384
	ds_read_b128 v[176:179], v137 offset:17408
	ds_read_b128 v[180:183], v137 offset:18432
	ds_read_b128 v[184:187], v137 offset:19456
	ds_read_b128 v[188:191], v137 offset:20480
	ds_read_b128 v[192:195], v137 offset:21504
	ds_read_b128 v[196:199], v137 offset:22528
	ds_read_b128 v[200:203], v137 offset:23552
	global_load_lds_dwordx4 v[204:205], off
	v_lshl_add_u64 v[206:207], v[204:205], 0, s[4:5]
	s_mov_b32 m0, s82
	s_nop 0
	global_load_lds_dwordx4 v[206:207], off
	v_lshl_add_u64 v[206:207], v[204:205], 0, s[6:7]
	s_mov_b32 m0, s81
	s_nop 0
	global_load_lds_dwordx4 v[206:207], off
	v_lshl_add_u64 v[206:207], v[204:205], 0, s[12:13]
	s_mov_b32 m0, s80
	s_nop 0
	global_load_lds_dwordx4 v[206:207], off
	v_lshl_add_u64 v[206:207], s[52:53], 0, v[128:129]
	s_mov_b32 m0, s27
	v_lshl_add_u64 v[208:209], v[206:207], 0, s[4:5]
	global_load_lds_dwordx4 v[206:207], off
	s_mov_b32 m0, s58
	s_nop 0
	global_load_lds_dwordx4 v[208:209], off
	s_waitcnt vmcnt(8)
	s_waitcnt lgkmcnt(0)
	s_barrier
	s_waitcnt lgkmcnt(0)
	v_mfma_f32_16x16x32_bf16 v[60:63], v[138:141], v[172:175], v[60:63]
	v_mfma_f32_16x16x32_bf16 v[56:59], v[146:149], v[172:175], v[56:59]
	v_mfma_f32_16x16x32_bf16 v[52:55], v[138:141], v[180:183], v[52:55]
	v_mfma_f32_16x16x32_bf16 v[48:51], v[146:149], v[180:183], v[48:51]
	v_mfma_f32_16x16x32_bf16 v[36:39], v[138:141], v[188:191], v[36:39]
	v_mfma_f32_16x16x32_bf16 v[32:35], v[146:149], v[188:191], v[32:35]
	v_mfma_f32_16x16x32_bf16 v[20:23], v[138:141], v[196:199], v[20:23]
	v_mfma_f32_16x16x32_bf16 v[16:19], v[146:149], v[196:199], v[16:19]
	v_mfma_f32_16x16x32_bf16 v[60:63], v[142:145], v[176:179], v[60:63]
	v_mfma_f32_16x16x32_bf16 v[56:59], v[150:153], v[176:179], v[56:59]
	v_mfma_f32_16x16x32_bf16 v[52:55], v[142:145], v[184:187], v[52:55]
	v_mfma_f32_16x16x32_bf16 v[48:51], v[150:153], v[184:187], v[48:51]
	v_mfma_f32_16x16x32_bf16 v[36:39], v[142:145], v[192:195], v[36:39]
	v_mfma_f32_16x16x32_bf16 v[32:35], v[150:153], v[192:195], v[32:35]
	v_mfma_f32_16x16x32_bf16 v[20:23], v[142:145], v[200:203], v[20:23]
	v_mfma_f32_16x16x32_bf16 v[16:19], v[150:153], v[200:203], v[16:19]
	v_mfma_f32_16x16x32_bf16 v[44:47], v[156:159], v[172:175], v[44:47]
	v_mfma_f32_16x16x32_bf16 v[40:43], v[164:167], v[172:175], v[40:43]
	v_mfma_f32_16x16x32_bf16 v[28:31], v[156:159], v[180:183], v[28:31]
	v_mfma_f32_16x16x32_bf16 v[24:27], v[164:167], v[180:183], v[24:27]
	v_mfma_f32_16x16x32_bf16 v[12:15], v[156:159], v[188:191], v[12:15]
	v_mfma_f32_16x16x32_bf16 v[8:11], v[164:167], v[188:191], v[8:11]
	v_mfma_f32_16x16x32_bf16 v[4:7], v[156:159], v[196:199], v[4:7]
	v_mfma_f32_16x16x32_bf16 v[0:3], v[164:167], v[196:199], v[0:3]
	v_mfma_f32_16x16x32_bf16 v[44:47], v[160:163], v[176:179], v[44:47]
	v_mfma_f32_16x16x32_bf16 v[40:43], v[168:171], v[176:179], v[40:43]
	v_mfma_f32_16x16x32_bf16 v[28:31], v[160:163], v[184:187], v[28:31]
	v_mfma_f32_16x16x32_bf16 v[24:27], v[168:171], v[184:187], v[24:27]
	v_mfma_f32_16x16x32_bf16 v[12:15], v[160:163], v[192:195], v[12:15]
	v_mfma_f32_16x16x32_bf16 v[8:11], v[168:171], v[192:195], v[8:11]
	v_mfma_f32_16x16x32_bf16 v[4:7], v[160:163], v[200:203], v[4:7]
	v_mfma_f32_16x16x32_bf16 v[0:3], v[168:171], v[200:203], v[0:3]
	s_barrier
	v_add_u32_e32 v150, s79, v133
	v_add_u32_e32 v155, s78, v133
	ds_read_b128 v[138:141], v150
	ds_read_b128 v[142:145], v150 offset:1024
	ds_read_b128 v[146:149], v150 offset:2048
	ds_read_b128 v[150:153], v150 offset:3072
	ds_read_b128 v[156:159], v155
	ds_read_b128 v[160:163], v155 offset:1024
	ds_read_b128 v[164:167], v155 offset:2048
	ds_read_b128 v[168:171], v155 offset:3072
	s_mov_b32 m0, s59
	v_lshl_add_u64 v[208:209], v[206:207], 0, s[6:7]
	ds_read_b128 v[172:175], v137 offset:32768
	ds_read_b128 v[176:179], v137 offset:33792
	ds_read_b128 v[180:183], v137 offset:34816
	ds_read_b128 v[184:187], v137 offset:35840
	ds_read_b128 v[188:191], v137 offset:36864
	ds_read_b128 v[192:195], v137 offset:37888
	ds_read_b128 v[196:199], v137 offset:38912
	ds_read_b128 v[200:203], v137 offset:39936
	global_load_lds_dwordx4 v[208:209], off
	v_lshl_add_u64 v[208:209], v[206:207], 0, s[12:13]
	s_mov_b32 m0, s62
	s_nop 0
	global_load_lds_dwordx4 v[208:209], off
	s_waitcnt vmcnt(8)
	s_waitcnt lgkmcnt(0)
	s_barrier
	s_waitcnt lgkmcnt(0)
	v_mfma_f32_16x16x32_bf16 v[124:127], v[138:141], v[172:175], v[124:127]
	v_mfma_f32_16x16x32_bf16 v[120:123], v[146:149], v[172:175], v[120:123]
	v_mfma_f32_16x16x32_bf16 v[116:119], v[138:141], v[180:183], v[116:119]
	v_mfma_f32_16x16x32_bf16 v[112:115], v[146:149], v[180:183], v[112:115]
	v_mfma_f32_16x16x32_bf16 v[100:103], v[138:141], v[188:191], v[100:103]
	v_mfma_f32_16x16x32_bf16 v[96:99], v[146:149], v[188:191], v[96:99]
	v_mfma_f32_16x16x32_bf16 v[84:87], v[138:141], v[196:199], v[84:87]
	v_mfma_f32_16x16x32_bf16 v[80:83], v[146:149], v[196:199], v[80:83]
	v_mfma_f32_16x16x32_bf16 v[124:127], v[142:145], v[176:179], v[124:127]
	v_mfma_f32_16x16x32_bf16 v[120:123], v[150:153], v[176:179], v[120:123]
	v_mfma_f32_16x16x32_bf16 v[116:119], v[142:145], v[184:187], v[116:119]
	v_mfma_f32_16x16x32_bf16 v[112:115], v[150:153], v[184:187], v[112:115]
	v_mfma_f32_16x16x32_bf16 v[100:103], v[142:145], v[192:195], v[100:103]
	v_mfma_f32_16x16x32_bf16 v[96:99], v[150:153], v[192:195], v[96:99]
	v_mfma_f32_16x16x32_bf16 v[84:87], v[142:145], v[200:203], v[84:87]
	v_mfma_f32_16x16x32_bf16 v[80:83], v[150:153], v[200:203], v[80:83]
	v_mfma_f32_16x16x32_bf16 v[108:111], v[156:159], v[172:175], v[108:111]
	v_mfma_f32_16x16x32_bf16 v[104:107], v[164:167], v[172:175], v[104:107]
	v_mfma_f32_16x16x32_bf16 v[92:95], v[156:159], v[180:183], v[92:95]
	v_mfma_f32_16x16x32_bf16 v[88:91], v[164:167], v[180:183], v[88:91]
	v_mfma_f32_16x16x32_bf16 v[76:79], v[156:159], v[188:191], v[76:79]
	v_mfma_f32_16x16x32_bf16 v[72:75], v[164:167], v[188:191], v[72:75]
	v_mfma_f32_16x16x32_bf16 v[68:71], v[156:159], v[196:199], v[68:71]
	v_mfma_f32_16x16x32_bf16 v[64:67], v[164:167], v[196:199], v[64:67]
	v_mfma_f32_16x16x32_bf16 v[108:111], v[160:163], v[176:179], v[108:111]
	v_mfma_f32_16x16x32_bf16 v[104:107], v[168:171], v[176:179], v[104:107]
	v_mfma_f32_16x16x32_bf16 v[92:95], v[160:163], v[184:187], v[92:95]
	v_mfma_f32_16x16x32_bf16 v[88:91], v[168:171], v[184:187], v[88:91]
	v_mfma_f32_16x16x32_bf16 v[76:79], v[160:163], v[192:195], v[76:79]
	v_mfma_f32_16x16x32_bf16 v[72:75], v[168:171], v[192:195], v[72:75]
	v_mfma_f32_16x16x32_bf16 v[68:71], v[160:163], v[200:203], v[68:71]
	v_mfma_f32_16x16x32_bf16 v[64:67], v[168:171], v[200:203], v[64:67]
	s_barrier
	s_mov_b32 m0, s77
	v_lshl_add_u64 v[208:209], v[204:205], 0, s[18:19]
	ds_read_b128 v[172:175], v137 offset:49152
	ds_read_b128 v[176:179], v137 offset:50176
	ds_read_b128 v[180:183], v137 offset:51200
	ds_read_b128 v[184:187], v137 offset:52224
	ds_read_b128 v[188:191], v137 offset:53248
	ds_read_b128 v[192:195], v137 offset:54272
	ds_read_b128 v[196:199], v137 offset:55296
	ds_read_b128 v[200:203], v137 offset:56320
	global_load_lds_dwordx4 v[208:209], off
	v_lshl_add_u64 v[208:209], v[204:205], 0, s[22:23]
	s_mov_b32 m0, s76
	s_nop 0
	global_load_lds_dwordx4 v[208:209], off
	v_lshl_add_u64 v[208:209], v[204:205], 0, s[24:25]
	s_mov_b32 m0, s61
	v_lshl_add_u64 v[204:205], v[204:205], 0, s[28:29]
	global_load_lds_dwordx4 v[208:209], off
	s_mov_b32 m0, s60
	s_nop 0
	global_load_lds_dwordx4 v[204:205], off
	v_lshl_add_u64 v[204:205], v[206:207], 0, s[18:19]
	s_mov_b32 m0, s65
	s_nop 0
	global_load_lds_dwordx4 v[204:205], off
	v_lshl_add_u64 v[204:205], v[206:207], 0, s[22:23]
	s_mov_b32 m0, s66
	s_nop 0
	global_load_lds_dwordx4 v[204:205], off
	s_waitcnt vmcnt(8)
	s_waitcnt lgkmcnt(0)
	s_barrier
	s_waitcnt lgkmcnt(0)
	v_mfma_f32_16x16x32_bf16 v[60:63], v[138:141], v[172:175], v[60:63]
	v_mfma_f32_16x16x32_bf16 v[56:59], v[146:149], v[172:175], v[56:59]
	v_mfma_f32_16x16x32_bf16 v[52:55], v[138:141], v[180:183], v[52:55]
	v_mfma_f32_16x16x32_bf16 v[48:51], v[146:149], v[180:183], v[48:51]
	v_mfma_f32_16x16x32_bf16 v[36:39], v[138:141], v[188:191], v[36:39]
	v_mfma_f32_16x16x32_bf16 v[32:35], v[146:149], v[188:191], v[32:35]
	v_mfma_f32_16x16x32_bf16 v[20:23], v[138:141], v[196:199], v[20:23]
	v_mfma_f32_16x16x32_bf16 v[16:19], v[146:149], v[196:199], v[16:19]
	v_mfma_f32_16x16x32_bf16 v[60:63], v[142:145], v[176:179], v[60:63]
	v_mfma_f32_16x16x32_bf16 v[56:59], v[150:153], v[176:179], v[56:59]
	v_mfma_f32_16x16x32_bf16 v[52:55], v[142:145], v[184:187], v[52:55]
	v_mfma_f32_16x16x32_bf16 v[48:51], v[150:153], v[184:187], v[48:51]
	v_mfma_f32_16x16x32_bf16 v[36:39], v[142:145], v[192:195], v[36:39]
	v_mfma_f32_16x16x32_bf16 v[32:35], v[150:153], v[192:195], v[32:35]
	v_mfma_f32_16x16x32_bf16 v[20:23], v[142:145], v[200:203], v[20:23]
	v_mfma_f32_16x16x32_bf16 v[16:19], v[150:153], v[200:203], v[16:19]
	v_mfma_f32_16x16x32_bf16 v[44:47], v[156:159], v[172:175], v[44:47]
	v_mfma_f32_16x16x32_bf16 v[40:43], v[164:167], v[172:175], v[40:43]
	v_mfma_f32_16x16x32_bf16 v[28:31], v[156:159], v[180:183], v[28:31]
	v_mfma_f32_16x16x32_bf16 v[24:27], v[164:167], v[180:183], v[24:27]
	v_mfma_f32_16x16x32_bf16 v[12:15], v[156:159], v[188:191], v[12:15]
	v_mfma_f32_16x16x32_bf16 v[8:11], v[164:167], v[188:191], v[8:11]
	v_mfma_f32_16x16x32_bf16 v[4:7], v[156:159], v[196:199], v[4:7]
	v_mfma_f32_16x16x32_bf16 v[0:3], v[164:167], v[196:199], v[0:3]
	v_mfma_f32_16x16x32_bf16 v[44:47], v[160:163], v[176:179], v[44:47]
	v_mfma_f32_16x16x32_bf16 v[40:43], v[168:171], v[176:179], v[40:43]
	v_mfma_f32_16x16x32_bf16 v[28:31], v[160:163], v[184:187], v[28:31]
	v_mfma_f32_16x16x32_bf16 v[24:27], v[168:171], v[184:187], v[24:27]
	v_mfma_f32_16x16x32_bf16 v[12:15], v[160:163], v[192:195], v[12:15]
	v_mfma_f32_16x16x32_bf16 v[8:11], v[168:171], v[192:195], v[8:11]
	v_mfma_f32_16x16x32_bf16 v[4:7], v[160:163], v[200:203], v[4:7]
	v_mfma_f32_16x16x32_bf16 v[0:3], v[168:171], v[200:203], v[0:3]
	s_barrier
	s_movk_i32 s60, 0x100
	s_andn2_b64 vcc, exec, s[50:51]
	s_mov_b64 s[2:3], -1
	s_mov_b64 s[50:51], 0
	s_cbranch_vccz .LBB0_629
	s_and_b64 vcc, exec, s[30:31]
	s_cbranch_vccz .LBB0_632
	s_barrier

.LBB0_750:
	s_nop 1
	v_max_f32_e32 v65, v48, v48
	v_max_f32_e32 v66, v32, v32
	v_max_f32_e32 v65, v66, v65
	v_max3_f32 v65, v65, v33, v49
	v_max3_f32 v65, v65, v34, v50
	v_max3_f32 v65, v65, v35, v51
	v_max3_f32 v65, v65, v36, v52
	v_max3_f32 v65, v65, v37, v53
	v_max3_f32 v65, v65, v38, v54
	v_max3_f32 v65, v65, v39, v55
	v_max3_f32 v65, v65, v40, v56
	v_max3_f32 v65, v65, v41, v57
	v_max3_f32 v65, v65, v42, v58
	v_max3_f32 v65, v65, v43, v59
	v_max3_f32 v65, v65, v44, v60
	v_max3_f32 v65, v65, v45, v61
	v_max3_f32 v65, v65, v46, v62
	v_max3_f32 v65, v65, v47, v63
	v_mov_b32_e32 v66, v65
	s_nop 1
	v_permlane32_swap_b32_e32 v65, v66
	v_max_f32_e32 v66, v66, v66
	v_max_f32_e32 v65, v65, v65
	s_cmp_lg_u32 s49, 63
	v_max_f32_e32 v66, v65, v66
	s_cselect_b64 s[2:3], -1, 0
	s_cmp_eq_u32 s49, 63
	s_mov_b64 s[28:29], -1
	s_cbranch_scc1 .LBB0_753
	v_cmp_lt_f32_e32 vcc, 0x41000000, v66
	s_cbranch_vccz .LBB0_758
	v_max_f32_e32 v65, v66, v66
	v_max_f32_e32 v66, 0, v65

.LBB0_831:
	ds_read_b128 v[128:131], v202
	ds_read_b128 v[132:135], v202 offset:1024
	ds_read_b128 v[136:139], v202 offset:2048
	ds_read_b128 v[140:143], v202 offset:3072
	ds_read_b128 v[144:147], v203
	ds_read_b128 v[148:151], v203 offset:1024
	ds_read_b128 v[152:155], v203 offset:2048
	ds_read_b128 v[156:159], v203 offset:3072
	s_add_u32 s60, s54, 0xfffc0080
	s_addc_u32 s61, s55, -1
	s_cmp_eq_u32 s71, 12
	s_cselect_b32 s61, s26, s61
	s_cselect_b32 s60, s27, s60
	s_cselect_b32 s73, s43, s3
	s_cselect_b32 s72, s45, s2
	v_lshl_add_u64 v[210:211], s[54:55], 0, v[180:181]
	s_add_i32 m0, s51, 0xc000
	ds_read_b128 v[160:163], v204
	ds_read_b128 v[164:167], v204 offset:1024
	ds_read_b128 v[168:171], v204 offset:2048
	ds_read_b128 v[172:175], v204 offset:3072
	ds_read_b128 v[186:189], v204 offset:4096
	ds_read_b128 v[190:193], v204 offset:5120
	ds_read_b128 v[194:197], v204 offset:6144
	ds_read_b128 v[206:209], v204 offset:7168
	global_load_lds_dwordx4 v[210:211], off
	v_lshl_add_u64 v[210:211], v[210:211], 0, s[0:1]
	s_add_i32 m0, s51, 0xe000
	s_nop 0
	global_load_lds_dwordx4 v[210:211], off
	s_waitcnt vmcnt(8)
	s_waitcnt lgkmcnt(0)
	s_barrier
	s_waitcnt lgkmcnt(0)
	v_mfma_f32_16x16x32_bf16 v[124:127], v[128:131], v[160:163], v[124:127]
	v_mfma_f32_16x16x32_bf16 v[120:123], v[136:139], v[160:163], v[120:123]
	v_mfma_f32_16x16x32_bf16 v[108:111], v[128:131], v[168:171], v[108:111]
	v_mfma_f32_16x16x32_bf16 v[104:107], v[136:139], v[168:171], v[104:107]
	v_mfma_f32_16x16x32_bf16 v[92:95], v[128:131], v[186:189], v[92:95]
	v_mfma_f32_16x16x32_bf16 v[88:91], v[136:139], v[186:189], v[88:91]
	v_mfma_f32_16x16x32_bf16 v[76:79], v[128:131], v[194:197], v[76:79]
	v_mfma_f32_16x16x32_bf16 v[72:75], v[136:139], v[194:197], v[72:75]
	v_mfma_f32_16x16x32_bf16 v[124:127], v[132:135], v[164:167], v[124:127]
	v_mfma_f32_16x16x32_bf16 v[120:123], v[140:143], v[164:167], v[120:123]
	v_mfma_f32_16x16x32_bf16 v[108:111], v[132:135], v[172:175], v[108:111]
	v_mfma_f32_16x16x32_bf16 v[104:107], v[140:143], v[172:175], v[104:107]
	v_mfma_f32_16x16x32_bf16 v[92:95], v[132:135], v[190:193], v[92:95]
	v_mfma_f32_16x16x32_bf16 v[88:91], v[140:143], v[190:193], v[88:91]
	v_mfma_f32_16x16x32_bf16 v[76:79], v[132:135], v[206:209], v[76:79]
	v_mfma_f32_16x16x32_bf16 v[72:75], v[140:143], v[206:209], v[72:75]
	v_mfma_f32_16x16x32_bf16 v[116:119], v[144:147], v[160:163], v[116:119]
	v_mfma_f32_16x16x32_bf16 v[112:115], v[152:155], v[160:163], v[112:115]
	v_mfma_f32_16x16x32_bf16 v[100:103], v[144:147], v[168:171], v[100:103]
	v_mfma_f32_16x16x32_bf16 v[96:99], v[152:155], v[168:171], v[96:99]
	v_mfma_f32_16x16x32_bf16 v[84:87], v[144:147], v[186:189], v[84:87]
	v_mfma_f32_16x16x32_bf16 v[80:83], v[152:155], v[186:189], v[80:83]
	v_mfma_f32_16x16x32_bf16 v[68:71], v[144:147], v[194:197], v[68:71]
	v_mfma_f32_16x16x32_bf16 v[64:67], v[152:155], v[194:197], v[64:67]
	v_mfma_f32_16x16x32_bf16 v[116:119], v[148:151], v[164:167], v[116:119]
	v_mfma_f32_16x16x32_bf16 v[112:115], v[156:159], v[164:167], v[112:115]
	v_mfma_f32_16x16x32_bf16 v[100:103], v[148:151], v[172:175], v[100:103]
	v_mfma_f32_16x16x32_bf16 v[96:99], v[156:159], v[172:175], v[96:99]
	v_mfma_f32_16x16x32_bf16 v[84:87], v[148:151], v[190:193], v[84:87]
	v_mfma_f32_16x16x32_bf16 v[80:83], v[156:159], v[190:193], v[80:83]
	v_mfma_f32_16x16x32_bf16 v[68:71], v[148:151], v[206:209], v[68:71]
	v_mfma_f32_16x16x32_bf16 v[64:67], v[156:159], v[206:209], v[64:67]
	s_barrier
	v_lshl_add_u64 v[210:211], s[72:73], 0, v[178:179]
	s_add_i32 s72, s69, s59
	s_mov_b32 m0, s72
	ds_read_b128 v[160:163], v204 offset:16384
	ds_read_b128 v[164:167], v204 offset:17408
	ds_read_b128 v[168:171], v204 offset:18432
	ds_read_b128 v[172:175], v204 offset:19456
	ds_read_b128 v[186:189], v204 offset:20480
	ds_read_b128 v[190:193], v204 offset:21504
	ds_read_b128 v[194:197], v204 offset:22528
	ds_read_b128 v[206:209], v204 offset:23552
	global_load_lds_dwordx4 v[210:211], off
	v_lshl_add_u64 v[212:213], v[210:211], 0, s[0:1]
	s_add_i32 m0, s72, 0x2000
	s_add_i32 s72, s70, s59
	global_load_lds_dwordx4 v[212:213], off
	v_lshl_add_u64 v[212:213], v[210:211], 0, s[4:5]
	s_mov_b32 m0, s72
	s_nop 0
	global_load_lds_dwordx4 v[212:213], off
	v_lshl_add_u64 v[212:213], v[210:211], 0, s[12:13]
	s_add_i32 m0, s72, 0x2000
	s_nop 0
	global_load_lds_dwordx4 v[212:213], off
	v_lshl_add_u64 v[212:213], s[60:61], 0, v[176:177]
	s_mov_b32 m0, s51
	v_lshl_add_u64 v[214:215], v[212:213], 0, s[0:1]
	global_load_lds_dwordx4 v[212:213], off
	s_mov_b32 m0, s53
	s_nop 0
	global_load_lds_dwordx4 v[214:215], off
	s_waitcnt vmcnt(8)
	s_waitcnt lgkmcnt(0)
	s_barrier
	s_waitcnt lgkmcnt(0)
	v_mfma_f32_16x16x32_bf16 v[60:63], v[128:131], v[160:163], v[60:63]
	v_mfma_f32_16x16x32_bf16 v[56:59], v[136:139], v[160:163], v[56:59]
	v_mfma_f32_16x16x32_bf16 v[44:47], v[128:131], v[168:171], v[44:47]
	v_mfma_f32_16x16x32_bf16 v[40:43], v[136:139], v[168:171], v[40:43]
	v_mfma_f32_16x16x32_bf16 v[28:31], v[128:131], v[186:189], v[28:31]
	v_mfma_f32_16x16x32_bf16 v[24:27], v[136:139], v[186:189], v[24:27]
	v_mfma_f32_16x16x32_bf16 v[12:15], v[128:131], v[194:197], v[12:15]
	v_mfma_f32_16x16x32_bf16 v[8:11], v[136:139], v[194:197], v[8:11]
	v_mfma_f32_16x16x32_bf16 v[60:63], v[132:135], v[164:167], v[60:63]
	v_mfma_f32_16x16x32_bf16 v[56:59], v[140:143], v[164:167], v[56:59]
	v_mfma_f32_16x16x32_bf16 v[44:47], v[132:135], v[172:175], v[44:47]
	v_mfma_f32_16x16x32_bf16 v[40:43], v[140:143], v[172:175], v[40:43]
	v_mfma_f32_16x16x32_bf16 v[28:31], v[132:135], v[190:193], v[28:31]
	v_mfma_f32_16x16x32_bf16 v[24:27], v[140:143], v[190:193], v[24:27]
	v_mfma_f32_16x16x32_bf16 v[12:15], v[132:135], v[206:209], v[12:15]
	v_mfma_f32_16x16x32_bf16 v[8:11], v[140:143], v[206:209], v[8:11]
	v_mfma_f32_16x16x32_bf16 v[52:55], v[144:147], v[160:163], v[52:55]
	v_mfma_f32_16x16x32_bf16 v[48:51], v[152:155], v[160:163], v[48:51]
	v_mfma_f32_16x16x32_bf16 v[36:39], v[144:147], v[168:171], v[36:39]
	v_mfma_f32_16x16x32_bf16 v[32:35], v[152:155], v[168:171], v[32:35]
	v_mfma_f32_16x16x32_bf16 v[20:23], v[144:147], v[186:189], v[20:23]
	v_mfma_f32_16x16x32_bf16 v[16:19], v[152:155], v[186:189], v[16:19]
	v_mfma_f32_16x16x32_bf16 v[4:7], v[144:147], v[194:197], v[4:7]
	v_mfma_f32_16x16x32_bf16 v[0:3], v[152:155], v[194:197], v[0:3]
	v_mfma_f32_16x16x32_bf16 v[52:55], v[148:151], v[164:167], v[52:55]
	v_mfma_f32_16x16x32_bf16 v[48:51], v[156:159], v[164:167], v[48:51]
	v_mfma_f32_16x16x32_bf16 v[36:39], v[148:151], v[172:175], v[36:39]
	v_mfma_f32_16x16x32_bf16 v[32:35], v[156:159], v[172:175], v[32:35]
	v_mfma_f32_16x16x32_bf16 v[20:23], v[148:151], v[190:193], v[20:23]
	v_mfma_f32_16x16x32_bf16 v[16:19], v[156:159], v[190:193], v[16:19]
	v_mfma_f32_16x16x32_bf16 v[4:7], v[148:151], v[206:209], v[4:7]
	v_mfma_f32_16x16x32_bf16 v[0:3], v[156:159], v[206:209], v[0:3]
	s_barrier
	s_add_i32 s60, 0, 0x18000
	s_add_i32 s61, 0, 0x1c000
	v_add_u32_e32 v140, s60, v200
	v_add_u32_e32 v156, s61, v200
	ds_read_b128 v[128:131], v140
	ds_read_b128 v[132:135], v140 offset:1024
	ds_read_b128 v[136:139], v140 offset:2048
	ds_read_b128 v[140:143], v140 offset:3072
	ds_read_b128 v[144:147], v156
	ds_read_b128 v[148:151], v156 offset:1024
	ds_read_b128 v[152:155], v156 offset:2048
	ds_read_b128 v[156:159], v156 offset:3072
	s_mov_b32 m0, s62
	v_lshl_add_u64 v[214:215], v[212:213], 0, s[4:5]
	ds_read_b128 v[160:163], v204 offset:32768
	ds_read_b128 v[164:167], v204 offset:33792
	ds_read_b128 v[168:171], v204 offset:34816
	ds_read_b128 v[172:175], v204 offset:35840
	ds_read_b128 v[186:189], v204 offset:36864
	ds_read_b128 v[190:193], v204 offset:37888
	ds_read_b128 v[194:197], v204 offset:38912
	ds_read_b128 v[206:209], v204 offset:39936
	global_load_lds_dwordx4 v[214:215], off
	v_lshl_add_u64 v[214:215], v[212:213], 0, s[12:13]
	s_mov_b32 m0, s65
	s_nop 0
	global_load_lds_dwordx4 v[214:215], off
	s_waitcnt vmcnt(8)
	s_waitcnt lgkmcnt(0)
	s_barrier
	s_waitcnt lgkmcnt(0)
	v_mfma_f32_16x16x32_bf16 v[124:127], v[128:131], v[160:163], v[124:127]
	v_mfma_f32_16x16x32_bf16 v[120:123], v[136:139], v[160:163], v[120:123]
	v_mfma_f32_16x16x32_bf16 v[108:111], v[128:131], v[168:171], v[108:111]
	v_mfma_f32_16x16x32_bf16 v[104:107], v[136:139], v[168:171], v[104:107]
	v_mfma_f32_16x16x32_bf16 v[92:95], v[128:131], v[186:189], v[92:95]
	v_mfma_f32_16x16x32_bf16 v[88:91], v[136:139], v[186:189], v[88:91]
	v_mfma_f32_16x16x32_bf16 v[76:79], v[128:131], v[194:197], v[76:79]
	v_mfma_f32_16x16x32_bf16 v[72:75], v[136:139], v[194:197], v[72:75]
	v_mfma_f32_16x16x32_bf16 v[124:127], v[132:135], v[164:167], v[124:127]
	v_mfma_f32_16x16x32_bf16 v[120:123], v[140:143], v[164:167], v[120:123]
	v_mfma_f32_16x16x32_bf16 v[108:111], v[132:135], v[172:175], v[108:111]
	v_mfma_f32_16x16x32_bf16 v[104:107], v[140:143], v[172:175], v[104:107]
	v_mfma_f32_16x16x32_bf16 v[92:95], v[132:135], v[190:193], v[92:95]
	v_mfma_f32_16x16x32_bf16 v[88:91], v[140:143], v[190:193], v[88:91]
	v_mfma_f32_16x16x32_bf16 v[76:79], v[132:135], v[206:209], v[76:79]
	v_mfma_f32_16x16x32_bf16 v[72:75], v[140:143], v[206:209], v[72:75]
	v_mfma_f32_16x16x32_bf16 v[116:119], v[144:147], v[160:163], v[116:119]
	v_mfma_f32_16x16x32_bf16 v[112:115], v[152:155], v[160:163], v[112:115]
	v_mfma_f32_16x16x32_bf16 v[100:103], v[144:147], v[168:171], v[100:103]
	v_mfma_f32_16x16x32_bf16 v[96:99], v[152:155], v[168:171], v[96:99]
	v_mfma_f32_16x16x32_bf16 v[84:87], v[144:147], v[186:189], v[84:87]
	v_mfma_f32_16x16x32_bf16 v[80:83], v[152:155], v[186:189], v[80:83]
	v_mfma_f32_16x16x32_bf16 v[68:71], v[144:147], v[194:197], v[68:71]
	v_mfma_f32_16x16x32_bf16 v[64:67], v[152:155], v[194:197], v[64:67]
	v_mfma_f32_16x16x32_bf16 v[116:119], v[148:151], v[164:167], v[116:119]
	v_mfma_f32_16x16x32_bf16 v[112:115], v[156:159], v[164:167], v[112:115]
	v_mfma_f32_16x16x32_bf16 v[100:103], v[148:151], v[172:175], v[100:103]
	v_mfma_f32_16x16x32_bf16 v[96:99], v[156:159], v[172:175], v[96:99]
	v_mfma_f32_16x16x32_bf16 v[84:87], v[148:151], v[190:193], v[84:87]
	v_mfma_f32_16x16x32_bf16 v[80:83], v[156:159], v[190:193], v[80:83]
	v_mfma_f32_16x16x32_bf16 v[68:71], v[148:151], v[206:209], v[68:71]
	v_mfma_f32_16x16x32_bf16 v[64:67], v[156:159], v[206:209], v[64:67]
	s_barrier
	s_add_i32 s60, s60, s59
	v_lshl_add_u64 v[214:215], v[210:211], 0, s[30:31]
	s_mov_b32 m0, s60
	ds_read_b128 v[160:163], v204 offset:49152
	ds_read_b128 v[164:167], v204 offset:50176
	ds_read_b128 v[168:171], v204 offset:51200
	ds_read_b128 v[172:175], v204 offset:52224
	ds_read_b128 v[186:189], v204 offset:53248
	ds_read_b128 v[190:193], v204 offset:54272
	ds_read_b128 v[194:197], v204 offset:55296
	ds_read_b128 v[206:209], v204 offset:56320
	global_load_lds_dwordx4 v[214:215], off
	v_lshl_add_u64 v[214:215], v[210:211], 0, s[34:35]
	s_add_i32 m0, s60, 0x2000
	s_add_i32 s60, s61, s59
	global_load_lds_dwordx4 v[214:215], off
	v_lshl_add_u64 v[214:215], v[210:211], 0, s[36:37]
	s_mov_b32 m0, s60
	v_lshl_add_u64 v[210:211], v[210:211], 0, s[38:39]
	global_load_lds_dwordx4 v[214:215], off
	s_add_i32 m0, s60, 0x2000
	s_nop 0
	global_load_lds_dwordx4 v[210:211], off
	v_lshl_add_u64 v[210:211], v[212:213], 0, s[30:31]
	s_mov_b32 m0, s67
	s_nop 0
	global_load_lds_dwordx4 v[210:211], off
	v_lshl_add_u64 v[210:211], v[212:213], 0, s[34:35]
	s_mov_b32 m0, s68
	s_nop 0
	global_load_lds_dwordx4 v[210:211], off
	s_waitcnt vmcnt(8)
	s_waitcnt lgkmcnt(0)
	s_barrier
	s_waitcnt lgkmcnt(0)
	v_mfma_f32_16x16x32_bf16 v[60:63], v[128:131], v[160:163], v[60:63]
	v_mfma_f32_16x16x32_bf16 v[56:59], v[136:139], v[160:163], v[56:59]
	v_mfma_f32_16x16x32_bf16 v[44:47], v[128:131], v[168:171], v[44:47]
	v_mfma_f32_16x16x32_bf16 v[40:43], v[136:139], v[168:171], v[40:43]
	v_mfma_f32_16x16x32_bf16 v[28:31], v[128:131], v[186:189], v[28:31]
	v_mfma_f32_16x16x32_bf16 v[24:27], v[136:139], v[186:189], v[24:27]
	v_mfma_f32_16x16x32_bf16 v[12:15], v[128:131], v[194:197], v[12:15]
	v_mfma_f32_16x16x32_bf16 v[8:11], v[136:139], v[194:197], v[8:11]
	v_mfma_f32_16x16x32_bf16 v[60:63], v[132:135], v[164:167], v[60:63]
	v_mfma_f32_16x16x32_bf16 v[56:59], v[140:143], v[164:167], v[56:59]
	v_mfma_f32_16x16x32_bf16 v[44:47], v[132:135], v[172:175], v[44:47]
	v_mfma_f32_16x16x32_bf16 v[40:43], v[140:143], v[172:175], v[40:43]
	v_mfma_f32_16x16x32_bf16 v[28:31], v[132:135], v[190:193], v[28:31]
	v_mfma_f32_16x16x32_bf16 v[24:27], v[140:143], v[190:193], v[24:27]
	v_mfma_f32_16x16x32_bf16 v[12:15], v[132:135], v[206:209], v[12:15]
	v_mfma_f32_16x16x32_bf16 v[8:11], v[140:143], v[206:209], v[8:11]
	v_mfma_f32_16x16x32_bf16 v[52:55], v[144:147], v[160:163], v[52:55]
	v_mfma_f32_16x16x32_bf16 v[48:51], v[152:155], v[160:163], v[48:51]
	v_mfma_f32_16x16x32_bf16 v[36:39], v[144:147], v[168:171], v[36:39]
	v_mfma_f32_16x16x32_bf16 v[32:35], v[152:155], v[168:171], v[32:35]
	v_mfma_f32_16x16x32_bf16 v[20:23], v[144:147], v[186:189], v[20:23]
	v_mfma_f32_16x16x32_bf16 v[16:19], v[152:155], v[186:189], v[16:19]
	v_mfma_f32_16x16x32_bf16 v[4:7], v[144:147], v[194:197], v[4:7]
	v_mfma_f32_16x16x32_bf16 v[0:3], v[152:155], v[194:197], v[0:3]
	v_mfma_f32_16x16x32_bf16 v[52:55], v[148:151], v[164:167], v[52:55]
	v_mfma_f32_16x16x32_bf16 v[48:51], v[156:159], v[164:167], v[48:51]
	v_mfma_f32_16x16x32_bf16 v[36:39], v[148:151], v[172:175], v[36:39]
	v_mfma_f32_16x16x32_bf16 v[32:35], v[156:159], v[172:175], v[32:35]
	v_mfma_f32_16x16x32_bf16 v[20:23], v[148:151], v[190:193], v[20:23]
	v_mfma_f32_16x16x32_bf16 v[16:19], v[156:159], v[190:193], v[16:19]
	v_mfma_f32_16x16x32_bf16 v[4:7], v[148:151], v[206:209], v[4:7]
	v_mfma_f32_16x16x32_bf16 v[0:3], v[156:159], v[206:209], v[0:3]
	s_barrier
	s_add_i32 s71, s71, 2
	s_add_u32 s54, s54, 0x100
	s_addc_u32 s55, s55, 0
	s_add_u32 s2, s2, 0x100
	s_addc_u32 s3, s3, 0
	s_cmp_gt_u32 s71, 13
	s_cbranch_scc0 .LBB0_831
	s_and_b64 vcc, exec, s[40:41]
	s_cbranch_vccz .LBB0_834
	s_barrier

.LBB0_925:
	s_add_u32 s0, s10, 0xfffc0080
	s_addc_u32 s1, s11, -1
	s_add_i32 s77, 0, 0x10000
	s_cmp_eq_u32 s49, 12
	s_cselect_b32 s1, s16, s1
	s_cselect_b32 s0, s17, s0
	v_add_u32_e32 v142, s77, v146
	s_cselect_b32 vcc_hi, s33, s3
	s_cselect_b32 vcc_lo, s48, s2
	s_add_i32 s79, 0, 0x14000
	ds_read_b128 v[134:137], v142
	ds_read_b128 v[138:141], v142 offset:1024
	ds_read_b128 v[150:153], v142 offset:2048
	ds_read_b128 v[154:157], v142 offset:3072
	v_add_u32_e32 v142, s79, v146
	ds_read_b128 v[158:161], v142
	ds_read_b128 v[162:165], v142 offset:1024
	ds_read_b128 v[166:169], v142 offset:2048
	ds_read_b128 v[170:173], v142 offset:3072
	v_lshl_add_u64 v[142:143], s[10:11], 0, v[132:133]
	s_add_i32 m0, s51, 0xc000
	ds_read_b128 v[174:177], v148
	ds_read_b128 v[178:181], v148 offset:1024
	ds_read_b128 v[200:203], v148 offset:2048
	ds_read_b128 v[204:207], v148 offset:3072
	ds_read_b128 v[208:211], v148 offset:4096
	ds_read_b128 v[212:215], v148 offset:5120
	ds_read_b128 v[216:219], v148 offset:6144
	ds_read_b128 v[220:223], v148 offset:7168
	global_load_lds_dwordx4 v[142:143], off
	v_lshl_add_u64 v[142:143], v[142:143], 0, s[84:85]
	s_add_i32 m0, s51, 0xe000
	s_nop 0
	global_load_lds_dwordx4 v[142:143], off
	s_waitcnt vmcnt(8)
	s_waitcnt lgkmcnt(0)
	s_barrier
	s_waitcnt lgkmcnt(0)
	v_mfma_f32_16x16x32_bf16 v[124:127], v[134:137], v[174:177], v[124:127]
	v_mfma_f32_16x16x32_bf16 v[120:123], v[150:153], v[174:177], v[120:123]
	v_mfma_f32_16x16x32_bf16 v[108:111], v[134:137], v[200:203], v[108:111]
	v_mfma_f32_16x16x32_bf16 v[104:107], v[150:153], v[200:203], v[104:107]
	v_mfma_f32_16x16x32_bf16 v[92:95], v[134:137], v[208:211], v[92:95]
	v_mfma_f32_16x16x32_bf16 v[88:91], v[150:153], v[208:211], v[88:91]
	v_mfma_f32_16x16x32_bf16 v[76:79], v[134:137], v[216:219], v[76:79]
	v_mfma_f32_16x16x32_bf16 v[72:75], v[150:153], v[216:219], v[72:75]
	v_mfma_f32_16x16x32_bf16 v[124:127], v[138:141], v[178:181], v[124:127]
	v_mfma_f32_16x16x32_bf16 v[120:123], v[154:157], v[178:181], v[120:123]
	v_mfma_f32_16x16x32_bf16 v[108:111], v[138:141], v[204:207], v[108:111]
	v_mfma_f32_16x16x32_bf16 v[104:107], v[154:157], v[204:207], v[104:107]
	v_mfma_f32_16x16x32_bf16 v[92:95], v[138:141], v[212:215], v[92:95]
	v_mfma_f32_16x16x32_bf16 v[88:91], v[154:157], v[212:215], v[88:91]
	v_mfma_f32_16x16x32_bf16 v[76:79], v[138:141], v[220:223], v[76:79]
	v_mfma_f32_16x16x32_bf16 v[72:75], v[154:157], v[220:223], v[72:75]
	v_mfma_f32_16x16x32_bf16 v[116:119], v[158:161], v[174:177], v[116:119]
	v_mfma_f32_16x16x32_bf16 v[112:115], v[166:169], v[174:177], v[112:115]
	v_mfma_f32_16x16x32_bf16 v[100:103], v[158:161], v[200:203], v[100:103]
	v_mfma_f32_16x16x32_bf16 v[96:99], v[166:169], v[200:203], v[96:99]
	v_mfma_f32_16x16x32_bf16 v[84:87], v[158:161], v[208:211], v[84:87]
	v_mfma_f32_16x16x32_bf16 v[80:83], v[166:169], v[208:211], v[80:83]
	v_mfma_f32_16x16x32_bf16 v[68:71], v[158:161], v[216:219], v[68:71]
	v_mfma_f32_16x16x32_bf16 v[64:67], v[166:169], v[216:219], v[64:67]
	v_mfma_f32_16x16x32_bf16 v[116:119], v[162:165], v[178:181], v[116:119]
	v_mfma_f32_16x16x32_bf16 v[112:115], v[170:173], v[178:181], v[112:115]
	v_mfma_f32_16x16x32_bf16 v[100:103], v[162:165], v[204:207], v[100:103]
	v_mfma_f32_16x16x32_bf16 v[96:99], v[170:173], v[204:207], v[96:99]
	v_mfma_f32_16x16x32_bf16 v[84:87], v[162:165], v[212:215], v[84:87]
	v_mfma_f32_16x16x32_bf16 v[80:83], v[170:173], v[212:215], v[80:83]
	v_mfma_f32_16x16x32_bf16 v[68:71], v[162:165], v[220:223], v[68:71]
	v_mfma_f32_16x16x32_bf16 v[64:67], v[170:173], v[220:223], v[64:67]
	s_barrier
	s_add_i32 s77, s77, s50
	v_lshl_add_u64 v[142:143], vcc, 0, v[128:129]
	s_mov_b32 m0, s77
	ds_read_b128 v[174:177], v148 offset:16384
	ds_read_b128 v[178:181], v148 offset:17408
	ds_read_b128 v[200:203], v148 offset:18432
	ds_read_b128 v[204:207], v148 offset:19456
	ds_read_b128 v[208:211], v148 offset:20480
	ds_read_b128 v[212:215], v148 offset:21504
	ds_read_b128 v[216:219], v148 offset:22528
	ds_read_b128 v[220:223], v148 offset:23552
	global_load_lds_dwordx4 v[142:143], off
	v_lshl_add_u64 v[182:183], v[142:143], 0, s[84:85]
	s_add_i32 m0, s77, 0x2000
	s_add_i32 s77, s79, s50
	global_load_lds_dwordx4 v[182:183], off
	v_lshl_add_u64 v[182:183], v[142:143], 0, s[86:87]
	s_mov_b32 m0, s77
	s_nop 0
	global_load_lds_dwordx4 v[182:183], off
	v_lshl_add_u64 v[182:183], v[142:143], 0, s[88:89]
	s_add_i32 m0, s77, 0x2000
	s_nop 0
	global_load_lds_dwordx4 v[182:183], off
	v_lshl_add_u64 v[182:183], s[0:1], 0, v[130:131]
	s_mov_b32 m0, s51
	v_lshl_add_u64 v[224:225], v[182:183], 0, s[84:85]
	global_load_lds_dwordx4 v[182:183], off
	s_mov_b32 m0, s54
	s_nop 0
	global_load_lds_dwordx4 v[224:225], off
	s_waitcnt vmcnt(8)
	s_waitcnt lgkmcnt(0)
	s_barrier
	s_waitcnt lgkmcnt(0)
	v_mfma_f32_16x16x32_bf16 v[60:63], v[134:137], v[174:177], v[60:63]
	v_mfma_f32_16x16x32_bf16 v[56:59], v[150:153], v[174:177], v[56:59]
	v_mfma_f32_16x16x32_bf16 v[44:47], v[134:137], v[200:203], v[44:47]
	v_mfma_f32_16x16x32_bf16 v[40:43], v[150:153], v[200:203], v[40:43]
	v_mfma_f32_16x16x32_bf16 v[28:31], v[134:137], v[208:211], v[28:31]
	v_mfma_f32_16x16x32_bf16 v[24:27], v[150:153], v[208:211], v[24:27]
	v_mfma_f32_16x16x32_bf16 v[12:15], v[134:137], v[216:219], v[12:15]
	v_mfma_f32_16x16x32_bf16 v[8:11], v[150:153], v[216:219], v[8:11]
	v_mfma_f32_16x16x32_bf16 v[60:63], v[138:141], v[178:181], v[60:63]
	v_mfma_f32_16x16x32_bf16 v[56:59], v[154:157], v[178:181], v[56:59]
	v_mfma_f32_16x16x32_bf16 v[44:47], v[138:141], v[204:207], v[44:47]
	v_mfma_f32_16x16x32_bf16 v[40:43], v[154:157], v[204:207], v[40:43]
	v_mfma_f32_16x16x32_bf16 v[28:31], v[138:141], v[212:215], v[28:31]
	v_mfma_f32_16x16x32_bf16 v[24:27], v[154:157], v[212:215], v[24:27]
	v_mfma_f32_16x16x32_bf16 v[12:15], v[138:141], v[220:223], v[12:15]
	v_mfma_f32_16x16x32_bf16 v[8:11], v[154:157], v[220:223], v[8:11]
	v_mfma_f32_16x16x32_bf16 v[52:55], v[158:161], v[174:177], v[52:55]
	v_mfma_f32_16x16x32_bf16 v[48:51], v[166:169], v[174:177], v[48:51]
	v_mfma_f32_16x16x32_bf16 v[36:39], v[158:161], v[200:203], v[36:39]
	v_mfma_f32_16x16x32_bf16 v[32:35], v[166:169], v[200:203], v[32:35]
	v_mfma_f32_16x16x32_bf16 v[20:23], v[158:161], v[208:211], v[20:23]
	v_mfma_f32_16x16x32_bf16 v[16:19], v[166:169], v[208:211], v[16:19]
	v_mfma_f32_16x16x32_bf16 v[4:7], v[158:161], v[216:219], v[4:7]
	v_mfma_f32_16x16x32_bf16 v[0:3], v[166:169], v[216:219], v[0:3]
	v_mfma_f32_16x16x32_bf16 v[52:55], v[162:165], v[178:181], v[52:55]
	v_mfma_f32_16x16x32_bf16 v[48:51], v[170:173], v[178:181], v[48:51]
	v_mfma_f32_16x16x32_bf16 v[36:39], v[162:165], v[204:207], v[36:39]
	v_mfma_f32_16x16x32_bf16 v[32:35], v[170:173], v[204:207], v[32:35]
	v_mfma_f32_16x16x32_bf16 v[20:23], v[162:165], v[212:215], v[20:23]
	v_mfma_f32_16x16x32_bf16 v[16:19], v[170:173], v[212:215], v[16:19]
	v_mfma_f32_16x16x32_bf16 v[4:7], v[162:165], v[220:223], v[4:7]
	v_mfma_f32_16x16x32_bf16 v[0:3], v[170:173], v[220:223], v[0:3]
	s_barrier
	s_add_i32 s0, 0, 0x18000
	v_add_u32_e32 v149, s0, v146
	s_add_i32 s1, 0, 0x1c000
	ds_read_b128 v[134:137], v149
	ds_read_b128 v[138:141], v149 offset:1024
	ds_read_b128 v[150:153], v149 offset:2048
	ds_read_b128 v[154:157], v149 offset:3072
	v_add_u32_e32 v149, s1, v146
	ds_read_b128 v[158:161], v149
	ds_read_b128 v[162:165], v149 offset:1024
	ds_read_b128 v[166:169], v149 offset:2048
	ds_read_b128 v[170:173], v149 offset:3072
	s_mov_b32 m0, s55
	v_lshl_add_u64 v[224:225], v[182:183], 0, s[86:87]
	ds_read_b128 v[174:177], v148 offset:32768
	ds_read_b128 v[178:181], v148 offset:33792
	ds_read_b128 v[200:203], v148 offset:34816
	ds_read_b128 v[204:207], v148 offset:35840
	ds_read_b128 v[208:211], v148 offset:36864
	ds_read_b128 v[212:215], v148 offset:37888
	ds_read_b128 v[216:219], v148 offset:38912
	ds_read_b128 v[220:223], v148 offset:39936
	global_load_lds_dwordx4 v[224:225], off
	v_lshl_add_u64 v[224:225], v[182:183], 0, s[88:89]
	s_mov_b32 m0, s66
	s_nop 0
	global_load_lds_dwordx4 v[224:225], off
	s_waitcnt vmcnt(8)
	s_waitcnt lgkmcnt(0)
	s_barrier
	s_waitcnt lgkmcnt(0)
	v_mfma_f32_16x16x32_bf16 v[124:127], v[134:137], v[174:177], v[124:127]
	v_mfma_f32_16x16x32_bf16 v[120:123], v[150:153], v[174:177], v[120:123]
	v_mfma_f32_16x16x32_bf16 v[108:111], v[134:137], v[200:203], v[108:111]
	v_mfma_f32_16x16x32_bf16 v[104:107], v[150:153], v[200:203], v[104:107]
	v_mfma_f32_16x16x32_bf16 v[92:95], v[134:137], v[208:211], v[92:95]
	v_mfma_f32_16x16x32_bf16 v[88:91], v[150:153], v[208:211], v[88:91]
	v_mfma_f32_16x16x32_bf16 v[76:79], v[134:137], v[216:219], v[76:79]
	v_mfma_f32_16x16x32_bf16 v[72:75], v[150:153], v[216:219], v[72:75]
	v_mfma_f32_16x16x32_bf16 v[124:127], v[138:141], v[178:181], v[124:127]
	v_mfma_f32_16x16x32_bf16 v[120:123], v[154:157], v[178:181], v[120:123]
	v_mfma_f32_16x16x32_bf16 v[108:111], v[138:141], v[204:207], v[108:111]
	v_mfma_f32_16x16x32_bf16 v[104:107], v[154:157], v[204:207], v[104:107]
	v_mfma_f32_16x16x32_bf16 v[92:95], v[138:141], v[212:215], v[92:95]
	v_mfma_f32_16x16x32_bf16 v[88:91], v[154:157], v[212:215], v[88:91]
	v_mfma_f32_16x16x32_bf16 v[76:79], v[138:141], v[220:223], v[76:79]
	v_mfma_f32_16x16x32_bf16 v[72:75], v[154:157], v[220:223], v[72:75]
	v_mfma_f32_16x16x32_bf16 v[116:119], v[158:161], v[174:177], v[116:119]
	v_mfma_f32_16x16x32_bf16 v[112:115], v[166:169], v[174:177], v[112:115]
	v_mfma_f32_16x16x32_bf16 v[100:103], v[158:161], v[200:203], v[100:103]
	v_mfma_f32_16x16x32_bf16 v[96:99], v[166:169], v[200:203], v[96:99]
	v_mfma_f32_16x16x32_bf16 v[84:87], v[158:161], v[208:211], v[84:87]
	v_mfma_f32_16x16x32_bf16 v[80:83], v[166:169], v[208:211], v[80:83]
	v_mfma_f32_16x16x32_bf16 v[68:71], v[158:161], v[216:219], v[68:71]
	v_mfma_f32_16x16x32_bf16 v[64:67], v[166:169], v[216:219], v[64:67]
	v_mfma_f32_16x16x32_bf16 v[116:119], v[162:165], v[178:181], v[116:119]
	v_mfma_f32_16x16x32_bf16 v[112:115], v[170:173], v[178:181], v[112:115]
	v_mfma_f32_16x16x32_bf16 v[100:103], v[162:165], v[204:207], v[100:103]
	v_mfma_f32_16x16x32_bf16 v[96:99], v[170:173], v[204:207], v[96:99]
	v_mfma_f32_16x16x32_bf16 v[84:87], v[162:165], v[212:215], v[84:87]
	v_mfma_f32_16x16x32_bf16 v[80:83], v[170:173], v[212:215], v[80:83]
	v_mfma_f32_16x16x32_bf16 v[68:71], v[162:165], v[220:223], v[68:71]
	v_mfma_f32_16x16x32_bf16 v[64:67], v[170:173], v[220:223], v[64:67]
	s_barrier
	s_add_i32 s0, s0, s50
	v_lshl_add_u64 v[224:225], v[142:143], 0, s[90:91]
	s_mov_b32 m0, s0
	ds_read_b128 v[174:177], v148 offset:49152
	ds_read_b128 v[178:181], v148 offset:50176
	ds_read_b128 v[200:203], v148 offset:51200
	ds_read_b128 v[204:207], v148 offset:52224
	ds_read_b128 v[208:211], v148 offset:53248
	ds_read_b128 v[212:215], v148 offset:54272
	ds_read_b128 v[216:219], v148 offset:55296
	ds_read_b128 v[220:223], v148 offset:56320
	global_load_lds_dwordx4 v[224:225], off
	v_lshl_add_u64 v[224:225], v[142:143], 0, s[92:93]
	s_add_i32 m0, s0, 0x2000
	s_add_i32 s0, s1, s50
	global_load_lds_dwordx4 v[224:225], off
	v_lshl_add_u64 v[224:225], v[142:143], 0, s[94:95]
	s_mov_b32 m0, s0
	v_lshl_add_u64 v[142:143], v[142:143], 0, s[96:97]
	global_load_lds_dwordx4 v[224:225], off
	s_add_i32 m0, s0, 0x2000
	s_nop 0
	global_load_lds_dwordx4 v[142:143], off
	v_lshl_add_u64 v[142:143], v[182:183], 0, s[90:91]
	s_mov_b32 m0, s67
	s_nop 0
	global_load_lds_dwordx4 v[142:143], off
	v_lshl_add_u64 v[142:143], v[182:183], 0, s[92:93]
	s_mov_b32 m0, s18
	s_nop 0
	global_load_lds_dwordx4 v[142:143], off
	s_waitcnt vmcnt(8)
	s_waitcnt lgkmcnt(0)
	s_barrier
	s_waitcnt lgkmcnt(0)
	v_mfma_f32_16x16x32_bf16 v[60:63], v[134:137], v[174:177], v[60:63]
	v_mfma_f32_16x16x32_bf16 v[56:59], v[150:153], v[174:177], v[56:59]
	v_mfma_f32_16x16x32_bf16 v[44:47], v[134:137], v[200:203], v[44:47]
	v_mfma_f32_16x16x32_bf16 v[40:43], v[150:153], v[200:203], v[40:43]
	v_mfma_f32_16x16x32_bf16 v[28:31], v[134:137], v[208:211], v[28:31]
	v_mfma_f32_16x16x32_bf16 v[24:27], v[150:153], v[208:211], v[24:27]
	v_mfma_f32_16x16x32_bf16 v[12:15], v[134:137], v[216:219], v[12:15]
	v_mfma_f32_16x16x32_bf16 v[8:11], v[150:153], v[216:219], v[8:11]
	v_mfma_f32_16x16x32_bf16 v[60:63], v[138:141], v[178:181], v[60:63]
	v_mfma_f32_16x16x32_bf16 v[56:59], v[154:157], v[178:181], v[56:59]
	v_mfma_f32_16x16x32_bf16 v[44:47], v[138:141], v[204:207], v[44:47]
	v_mfma_f32_16x16x32_bf16 v[40:43], v[154:157], v[204:207], v[40:43]
	v_mfma_f32_16x16x32_bf16 v[28:31], v[138:141], v[212:215], v[28:31]
	v_mfma_f32_16x16x32_bf16 v[24:27], v[154:157], v[212:215], v[24:27]
	v_mfma_f32_16x16x32_bf16 v[12:15], v[138:141], v[220:223], v[12:15]
	v_mfma_f32_16x16x32_bf16 v[8:11], v[154:157], v[220:223], v[8:11]
	v_mfma_f32_16x16x32_bf16 v[52:55], v[158:161], v[174:177], v[52:55]
	v_mfma_f32_16x16x32_bf16 v[48:51], v[166:169], v[174:177], v[48:51]
	v_mfma_f32_16x16x32_bf16 v[36:39], v[158:161], v[200:203], v[36:39]
	v_mfma_f32_16x16x32_bf16 v[32:35], v[166:169], v[200:203], v[32:35]
	v_mfma_f32_16x16x32_bf16 v[20:23], v[158:161], v[208:211], v[20:23]
	v_mfma_f32_16x16x32_bf16 v[16:19], v[166:169], v[208:211], v[16:19]
	v_mfma_f32_16x16x32_bf16 v[4:7], v[158:161], v[216:219], v[4:7]
	v_mfma_f32_16x16x32_bf16 v[0:3], v[166:169], v[216:219], v[0:3]
	v_mfma_f32_16x16x32_bf16 v[52:55], v[162:165], v[178:181], v[52:55]
	v_mfma_f32_16x16x32_bf16 v[48:51], v[170:173], v[178:181], v[48:51]
	v_mfma_f32_16x16x32_bf16 v[36:39], v[162:165], v[204:207], v[36:39]
	v_mfma_f32_16x16x32_bf16 v[32:35], v[170:173], v[204:207], v[32:35]
	v_mfma_f32_16x16x32_bf16 v[20:23], v[162:165], v[212:215], v[20:23]
	v_mfma_f32_16x16x32_bf16 v[16:19], v[170:173], v[212:215], v[16:19]
	v_mfma_f32_16x16x32_bf16 v[4:7], v[162:165], v[220:223], v[4:7]
	v_mfma_f32_16x16x32_bf16 v[0:3], v[170:173], v[220:223], v[0:3]
	s_barrier
	s_add_i32 s49, s49, 2
	s_add_u32 s10, s10, 0x100
	s_addc_u32 s11, s11, 0
	s_add_u32 s2, s2, 0x100
	s_addc_u32 s3, s3, 0
	s_cmp_gt_u32 s49, 13
	s_cbranch_scc0 .LBB0_925
	s_and_b64 vcc, exec, s[72:73]
	s_cbranch_vccz .LBB0_928
	s_barrier

.LBB0_1130:
	s_add_u32 s2, s10, s77
	s_addc_u32 s3, s11, 0
	s_add_u32 s12, s2, 0x100
	s_addc_u32 s13, s3, 0
	s_and_b64 s[6:7], s[18:19], exec
	s_cselect_b32 vcc_lo, s0, s12
	s_cselect_b32 vcc_hi, s1, s13
	s_add_u32 s6, s80, s77
	s_addc_u32 s7, s81, 0
	s_add_u32 s12, s6, 0x100
	s_addc_u32 s13, s7, 0
	s_add_i32 s17, 0, 0x10000
	s_and_b64 s[6:7], s[18:19], exec
	s_cselect_b32 s18, s49, s12
	s_cselect_b32 s19, s23, s13
	s_add_i32 s6, 0, 0x14000
	v_add_u32_e32 v40, s17, v209
	v_add_u32_e32 v128, s6, v209
	ds_read_b128 v[24:27], v40
	ds_read_b128 v[32:35], v40 offset:1024
	ds_read_b128 v[36:39], v40 offset:2048
	ds_read_b128 v[40:43], v40 offset:3072
	ds_read_b128 v[48:51], v128
	ds_read_b128 v[52:55], v128 offset:1024
	ds_read_b128 v[108:111], v128 offset:2048
	ds_read_b128 v[128:131], v128 offset:3072
	s_add_i32 s79, 0, 0x18000
	s_add_i32 s78, 0, 0x1c000
	s_add_i32 s16, s79, s26
	s_add_i32 s73, s17, s26
	s_add_i32 s12, s6, s26
	s_add_i32 s77, s16, 0x2000
	s_add_i32 s7, s78, s26
	s_add_i32 m0, s22, 0xc000
	s_add_i32 s27, s22, 0xe000
	s_add_i32 s72, s73, 0x2000
	s_add_i32 s13, s12, 0x2000
	s_add_i32 s6, s7, 0x2000
	v_lshl_add_u64 v[182:183], s[2:3], 0, v[168:169]
	v_lshl_add_u64 v[216:217], v[182:183], 0, s[94:95]
	ds_read_b128 v[148:151], v211
	ds_read_b128 v[160:163], v211 offset:1024
	ds_read_b128 v[170:173], v211 offset:2048
	ds_read_b128 v[174:177], v211 offset:3072
	ds_read_b128 v[178:181], v211 offset:4096
	ds_read_b128 v[200:203], v211 offset:5120
	ds_read_b128 v[204:207], v211 offset:6144
	ds_read_b128 v[212:215], v211 offset:7168
	global_load_lds_dwordx4 v[216:217], off
	v_lshl_add_u64 v[182:183], v[182:183], 0, s[96:97]
	s_mov_b32 m0, s27
	s_nop 0
	global_load_lds_dwordx4 v[182:183], off
	s_waitcnt vmcnt(8)
	s_waitcnt lgkmcnt(0)
	s_barrier
	s_waitcnt lgkmcnt(0)
	v_mfma_f32_16x16x32_bf16 v[164:167], v[24:27], v[148:151], v[164:167]
	v_mfma_f32_16x16x32_bf16 v[156:159], v[36:39], v[148:151], v[156:159]
	v_mfma_f32_16x16x32_bf16 v[140:143], v[24:27], v[170:173], v[140:143]
	v_mfma_f32_16x16x32_bf16 v[136:139], v[36:39], v[170:173], v[136:139]
	v_mfma_f32_16x16x32_bf16 v[120:123], v[24:27], v[178:181], v[120:123]
	v_mfma_f32_16x16x32_bf16 v[116:119], v[36:39], v[178:181], v[116:119]
	v_mfma_f32_16x16x32_bf16 v[100:103], v[24:27], v[204:207], v[100:103]
	v_mfma_f32_16x16x32_bf16 v[96:99], v[36:39], v[204:207], v[96:99]
	v_mfma_f32_16x16x32_bf16 v[164:167], v[32:35], v[160:163], v[164:167]
	v_mfma_f32_16x16x32_bf16 v[156:159], v[40:43], v[160:163], v[156:159]
	v_mfma_f32_16x16x32_bf16 v[140:143], v[32:35], v[174:177], v[140:143]
	v_mfma_f32_16x16x32_bf16 v[136:139], v[40:43], v[174:177], v[136:139]
	v_mfma_f32_16x16x32_bf16 v[120:123], v[32:35], v[200:203], v[120:123]
	v_mfma_f32_16x16x32_bf16 v[116:119], v[40:43], v[200:203], v[116:119]
	v_mfma_f32_16x16x32_bf16 v[100:103], v[32:35], v[212:215], v[100:103]
	v_mfma_f32_16x16x32_bf16 v[96:99], v[40:43], v[212:215], v[96:99]
	v_mfma_f32_16x16x32_bf16 v[152:155], v[48:51], v[148:151], v[152:155]
	v_mfma_f32_16x16x32_bf16 v[144:147], v[108:111], v[148:151], v[144:147]
	v_mfma_f32_16x16x32_bf16 v[124:127], v[48:51], v[170:173], v[124:127]
	v_mfma_f32_16x16x32_bf16 v[132:135], v[108:111], v[170:173], v[132:135]
	v_mfma_f32_16x16x32_bf16 v[104:107], v[48:51], v[178:181], v[104:107]
	v_mfma_f32_16x16x32_bf16 v[112:115], v[108:111], v[178:181], v[112:115]
	v_mfma_f32_16x16x32_bf16 v[88:91], v[48:51], v[204:207], v[88:91]
	v_mfma_f32_16x16x32_bf16 v[92:95], v[108:111], v[204:207], v[92:95]
	v_mfma_f32_16x16x32_bf16 v[152:155], v[52:55], v[160:163], v[152:155]
	v_mfma_f32_16x16x32_bf16 v[144:147], v[128:131], v[160:163], v[144:147]
	v_mfma_f32_16x16x32_bf16 v[124:127], v[52:55], v[174:177], v[124:127]
	v_mfma_f32_16x16x32_bf16 v[132:135], v[128:131], v[174:177], v[132:135]
	v_mfma_f32_16x16x32_bf16 v[104:107], v[52:55], v[200:203], v[104:107]
	v_mfma_f32_16x16x32_bf16 v[112:115], v[128:131], v[200:203], v[112:115]
	v_mfma_f32_16x16x32_bf16 v[88:91], v[52:55], v[212:215], v[88:91]
	v_mfma_f32_16x16x32_bf16 v[92:95], v[128:131], v[212:215], v[92:95]
	s_barrier
	s_mov_b32 m0, s73
	v_lshl_add_u64 v[182:183], s[18:19], 0, v[184:185]
	ds_read_b128 v[148:151], v211 offset:16384
	ds_read_b128 v[160:163], v211 offset:17408
	ds_read_b128 v[170:173], v211 offset:18432
	ds_read_b128 v[174:177], v211 offset:19456
	ds_read_b128 v[178:181], v211 offset:20480
	ds_read_b128 v[200:203], v211 offset:21504
	ds_read_b128 v[204:207], v211 offset:22528
	ds_read_b128 v[212:215], v211 offset:23552
	global_load_lds_dwordx4 v[182:183], off
	v_lshl_add_u64 v[216:217], v[182:183], 0, s[64:65]
	s_mov_b32 m0, s72
	v_lshl_add_u64 v[220:221], vcc, 0, v[168:169]
	global_load_lds_dwordx4 v[216:217], off
	v_lshl_add_u64 v[216:217], v[182:183], 0, s[20:21]
	s_mov_b32 m0, s12
	s_nop 0
	global_load_lds_dwordx4 v[216:217], off
	v_lshl_add_u64 v[216:217], v[182:183], 0, s[68:69]
	s_mov_b32 m0, s13
	s_nop 0
	global_load_lds_dwordx4 v[216:217], off
	s_mov_b32 m0, s22
	v_lshl_add_u64 v[216:217], v[220:221], 0, s[84:85]
	global_load_lds_dwordx4 v[220:221], off
	s_mov_b32 m0, s50
	s_nop 0
	global_load_lds_dwordx4 v[216:217], off
	s_waitcnt vmcnt(8)
	s_waitcnt lgkmcnt(0)
	s_barrier
	s_waitcnt lgkmcnt(0)
	v_mfma_f32_16x16x32_bf16 v[84:87], v[24:27], v[148:151], v[84:87]
	v_mfma_f32_16x16x32_bf16 v[80:83], v[36:39], v[148:151], v[80:83]
	v_mfma_f32_16x16x32_bf16 v[68:71], v[24:27], v[170:173], v[68:71]
	v_mfma_f32_16x16x32_bf16 v[64:67], v[36:39], v[170:173], v[64:67]
	v_mfma_f32_16x16x32_bf16 v[44:47], v[24:27], v[178:181], v[44:47]
	v_mfma_f32_16x16x32_bf16 v[28:31], v[36:39], v[178:181], v[28:31]
	v_mfma_f32_16x16x32_bf16 v[12:15], v[24:27], v[204:207], v[12:15]
	v_mfma_f32_16x16x32_bf16 v[8:11], v[36:39], v[204:207], v[8:11]
	v_mfma_f32_16x16x32_bf16 v[84:87], v[32:35], v[160:163], v[84:87]
	v_mfma_f32_16x16x32_bf16 v[80:83], v[40:43], v[160:163], v[80:83]
	v_mfma_f32_16x16x32_bf16 v[68:71], v[32:35], v[174:177], v[68:71]
	v_mfma_f32_16x16x32_bf16 v[64:67], v[40:43], v[174:177], v[64:67]
	v_mfma_f32_16x16x32_bf16 v[44:47], v[32:35], v[200:203], v[44:47]
	v_mfma_f32_16x16x32_bf16 v[28:31], v[40:43], v[200:203], v[28:31]
	v_mfma_f32_16x16x32_bf16 v[12:15], v[32:35], v[212:215], v[12:15]
	v_mfma_f32_16x16x32_bf16 v[8:11], v[40:43], v[212:215], v[8:11]
	v_mfma_f32_16x16x32_bf16 v[16:19], v[48:51], v[178:181], v[16:19]
	v_mfma_f32_16x16x32_bf16 v[20:23], v[108:111], v[178:181], v[20:23]
	v_mfma_f32_16x16x32_bf16 v[0:3], v[48:51], v[204:207], v[0:3]
	v_mfma_f32_16x16x32_bf16 v[4:7], v[108:111], v[204:207], v[4:7]
	v_mfma_f32_16x16x32_bf16 v[24:27], v[48:51], v[148:151], v[72:75]
	v_mfma_f32_16x16x32_bf16 v[32:35], v[108:111], v[148:151], v[76:79]
	v_mfma_f32_16x16x32_bf16 v[36:39], v[48:51], v[170:173], v[56:59]
	v_mfma_f32_16x16x32_bf16 v[40:43], v[108:111], v[170:173], v[60:63]
	v_mfma_f32_16x16x32_bf16 v[16:19], v[52:55], v[200:203], v[16:19]
	v_mfma_f32_16x16x32_bf16 v[20:23], v[128:131], v[200:203], v[20:23]
	v_mfma_f32_16x16x32_bf16 v[0:3], v[52:55], v[212:215], v[0:3]
	v_mfma_f32_16x16x32_bf16 v[4:7], v[128:131], v[212:215], v[4:7]
	v_mfma_f32_16x16x32_bf16 v[24:27], v[52:55], v[160:163], v[24:27]
	v_mfma_f32_16x16x32_bf16 v[32:35], v[128:131], v[160:163], v[32:35]
	v_mfma_f32_16x16x32_bf16 v[36:39], v[52:55], v[174:177], v[36:39]
	v_mfma_f32_16x16x32_bf16 v[40:43], v[128:131], v[174:177], v[40:43]
	s_barrier
	v_add_u32_e32 v60, s79, v209
	v_add_u32_e32 v72, s78, v209
	ds_read_b128 v[48:51], v60
	ds_read_b128 v[52:55], v60 offset:1024
	ds_read_b128 v[56:59], v60 offset:2048
	ds_read_b128 v[60:63], v60 offset:3072
	ds_read_b128 v[108:111], v72
	ds_read_b128 v[128:131], v72 offset:1024
	ds_read_b128 v[148:151], v72 offset:2048
	ds_read_b128 v[160:163], v72 offset:3072
	s_mov_b32 m0, s51
	v_lshl_add_u64 v[216:217], v[220:221], 0, s[86:87]
	ds_read_b128 v[72:75], v211 offset:32768
	ds_read_b128 v[76:79], v211 offset:33792
	ds_read_b128 v[170:173], v211 offset:34816
	ds_read_b128 v[174:177], v211 offset:35840
	ds_read_b128 v[178:181], v211 offset:36864
	ds_read_b128 v[200:203], v211 offset:37888
	ds_read_b128 v[204:207], v211 offset:38912
	ds_read_b128 v[212:215], v211 offset:39936
	global_load_lds_dwordx4 v[216:217], off
	v_lshl_add_u64 v[216:217], v[220:221], 0, s[88:89]
	s_mov_b32 m0, s66
	s_nop 0
	global_load_lds_dwordx4 v[216:217], off
	s_waitcnt vmcnt(8)
	s_waitcnt lgkmcnt(0)
	s_barrier
	s_waitcnt lgkmcnt(0)
	v_mfma_f32_16x16x32_bf16 v[164:167], v[48:51], v[72:75], v[164:167]
	v_mfma_f32_16x16x32_bf16 v[156:159], v[56:59], v[72:75], v[156:159]
	v_mfma_f32_16x16x32_bf16 v[140:143], v[48:51], v[170:173], v[140:143]
	v_mfma_f32_16x16x32_bf16 v[136:139], v[56:59], v[170:173], v[136:139]
	v_mfma_f32_16x16x32_bf16 v[120:123], v[48:51], v[178:181], v[120:123]
	v_mfma_f32_16x16x32_bf16 v[116:119], v[56:59], v[178:181], v[116:119]
	v_mfma_f32_16x16x32_bf16 v[100:103], v[48:51], v[204:207], v[100:103]
	v_mfma_f32_16x16x32_bf16 v[96:99], v[56:59], v[204:207], v[96:99]
	v_mfma_f32_16x16x32_bf16 v[164:167], v[52:55], v[76:79], v[164:167]
	v_mfma_f32_16x16x32_bf16 v[156:159], v[60:63], v[76:79], v[156:159]
	v_mfma_f32_16x16x32_bf16 v[140:143], v[52:55], v[174:177], v[140:143]
	v_mfma_f32_16x16x32_bf16 v[136:139], v[60:63], v[174:177], v[136:139]
	v_mfma_f32_16x16x32_bf16 v[120:123], v[52:55], v[200:203], v[120:123]
	v_mfma_f32_16x16x32_bf16 v[116:119], v[60:63], v[200:203], v[116:119]
	v_mfma_f32_16x16x32_bf16 v[100:103], v[52:55], v[212:215], v[100:103]
	v_mfma_f32_16x16x32_bf16 v[96:99], v[60:63], v[212:215], v[96:99]
	v_mfma_f32_16x16x32_bf16 v[152:155], v[108:111], v[72:75], v[152:155]
	v_mfma_f32_16x16x32_bf16 v[72:75], v[148:151], v[72:75], v[144:147]
	v_mfma_f32_16x16x32_bf16 v[144:147], v[160:163], v[76:79], v[72:75]
	v_mfma_f32_16x16x32_bf16 v[72:75], v[108:111], v[170:173], v[124:127]
	v_mfma_f32_16x16x32_bf16 v[124:127], v[128:131], v[174:177], v[72:75]
	v_mfma_f32_16x16x32_bf16 v[72:75], v[148:151], v[170:173], v[132:135]
	v_mfma_f32_16x16x32_bf16 v[132:135], v[160:163], v[174:177], v[72:75]
	v_mfma_f32_16x16x32_bf16 v[72:75], v[108:111], v[178:181], v[104:107]
	v_mfma_f32_16x16x32_bf16 v[104:107], v[128:131], v[200:203], v[72:75]
	v_mfma_f32_16x16x32_bf16 v[72:75], v[148:151], v[178:181], v[112:115]
	v_mfma_f32_16x16x32_bf16 v[112:115], v[160:163], v[200:203], v[72:75]
	v_mfma_f32_16x16x32_bf16 v[72:75], v[108:111], v[204:207], v[88:91]
	v_mfma_f32_16x16x32_bf16 v[88:91], v[128:131], v[212:215], v[72:75]
	v_mfma_f32_16x16x32_bf16 v[72:75], v[148:151], v[204:207], v[92:95]
	v_mfma_f32_16x16x32_bf16 v[152:155], v[128:131], v[76:79], v[152:155]
	v_mfma_f32_16x16x32_bf16 v[92:95], v[160:163], v[212:215], v[72:75]
	s_barrier
	s_mov_b32 m0, s16
	s_nop 2
	v_lshl_add_u64 v[72:73], v[182:183], 0, s[90:91]
	ds_read_b128 v[76:79], v211 offset:49152
	ds_read_b128 v[170:173], v211 offset:50176
	ds_read_b128 v[174:177], v211 offset:51200
	ds_read_b128 v[178:181], v211 offset:52224
	ds_read_b128 v[200:203], v211 offset:53248
	ds_read_b128 v[204:207], v211 offset:54272
	ds_read_b128 v[212:215], v211 offset:55296
	ds_read_b128 v[216:219], v211 offset:56320
	global_load_lds_dwordx4 v[72:73], off
	v_lshl_add_u64 v[72:73], v[182:183], 0, s[70:71]
	s_mov_b32 m0, s77
	s_nop 0
	global_load_lds_dwordx4 v[72:73], off
	v_lshl_add_u64 v[72:73], v[182:183], 0, s[74:75]
	s_mov_b32 m0, s7
	s_nop 0
	global_load_lds_dwordx4 v[72:73], off
	v_lshl_add_u64 v[72:73], v[182:183], 0, s[60:61]
	s_mov_b32 m0, s6
	s_nop 0
	global_load_lds_dwordx4 v[72:73], off
	v_lshl_add_u64 v[72:73], v[220:221], 0, s[90:91]
	s_mov_b32 m0, s67
	s_nop 0
	global_load_lds_dwordx4 v[72:73], off
	v_lshl_add_u64 v[72:73], v[220:221], 0, s[92:93]
	s_mov_b32 m0, s36
	s_nop 0
	global_load_lds_dwordx4 v[72:73], off
	s_waitcnt vmcnt(8)
	s_waitcnt lgkmcnt(0)
	s_barrier
	s_waitcnt lgkmcnt(0)
	v_mfma_f32_16x16x32_bf16 v[72:75], v[48:51], v[76:79], v[84:87]
	v_mfma_f32_16x16x32_bf16 v[84:87], v[52:55], v[170:173], v[72:75]
	v_mfma_f32_16x16x32_bf16 v[72:75], v[56:59], v[76:79], v[80:83]
	v_mfma_f32_16x16x32_bf16 v[68:71], v[48:51], v[174:177], v[68:71]
	v_mfma_f32_16x16x32_bf16 v[64:67], v[56:59], v[174:177], v[64:67]
	v_mfma_f32_16x16x32_bf16 v[44:47], v[48:51], v[200:203], v[44:47]
	v_mfma_f32_16x16x32_bf16 v[28:31], v[56:59], v[200:203], v[28:31]
	v_mfma_f32_16x16x32_bf16 v[12:15], v[48:51], v[212:215], v[12:15]
	v_mfma_f32_16x16x32_bf16 v[8:11], v[56:59], v[212:215], v[8:11]
	v_mfma_f32_16x16x32_bf16 v[80:83], v[60:63], v[170:173], v[72:75]
	v_mfma_f32_16x16x32_bf16 v[68:71], v[52:55], v[178:181], v[68:71]
	v_mfma_f32_16x16x32_bf16 v[64:67], v[60:63], v[178:181], v[64:67]
	v_mfma_f32_16x16x32_bf16 v[44:47], v[52:55], v[204:207], v[44:47]
	v_mfma_f32_16x16x32_bf16 v[28:31], v[60:63], v[204:207], v[28:31]
	v_mfma_f32_16x16x32_bf16 v[12:15], v[52:55], v[216:219], v[12:15]
	v_mfma_f32_16x16x32_bf16 v[8:11], v[60:63], v[216:219], v[8:11]
	v_mfma_f32_16x16x32_bf16 v[24:27], v[108:111], v[76:79], v[24:27]
	v_mfma_f32_16x16x32_bf16 v[72:75], v[128:131], v[170:173], v[24:27]
	v_mfma_f32_16x16x32_bf16 v[24:27], v[148:151], v[76:79], v[32:35]
	v_mfma_f32_16x16x32_bf16 v[76:79], v[160:163], v[170:173], v[24:27]
	v_mfma_f32_16x16x32_bf16 v[24:27], v[108:111], v[174:177], v[36:39]
	v_mfma_f32_16x16x32_bf16 v[56:59], v[128:131], v[178:181], v[24:27]
	v_mfma_f32_16x16x32_bf16 v[24:27], v[148:151], v[174:177], v[40:43]
	v_mfma_f32_16x16x32_bf16 v[16:19], v[108:111], v[200:203], v[16:19]
	v_mfma_f32_16x16x32_bf16 v[20:23], v[148:151], v[200:203], v[20:23]
	v_mfma_f32_16x16x32_bf16 v[0:3], v[108:111], v[212:215], v[0:3]
	v_mfma_f32_16x16x32_bf16 v[4:7], v[148:151], v[212:215], v[4:7]
	v_mfma_f32_16x16x32_bf16 v[60:63], v[160:163], v[178:181], v[24:27]
	v_mfma_f32_16x16x32_bf16 v[16:19], v[128:131], v[204:207], v[16:19]
	v_mfma_f32_16x16x32_bf16 v[20:23], v[160:163], v[204:207], v[20:23]
	v_mfma_f32_16x16x32_bf16 v[0:3], v[128:131], v[216:219], v[0:3]
	v_mfma_f32_16x16x32_bf16 v[4:7], v[160:163], v[216:219], v[4:7]
	s_barrier
	s_movk_i32 s77, 0x100
	s_andn2_b64 vcc, exec, s[8:9]
	s_mov_b64 s[18:19], -1
	s_mov_b64 s[8:9], 0
	s_cbranch_vccz .LBB0_1130
	v_readlane_b32 s2, v255, 47
	v_readlane_b32 s3, v255, 48
	s_and_b64 vcc, exec, s[2:3]
	s_cbranch_vccz .LBB0_1133
	s_barrier

.LBB0_1597:
	s_add_u32 s2, s54, 0xfffc0080
	s_addc_u32 s3, s55, -1
	s_add_i32 s66, 0, 0x10000
	s_cmp_eq_u32 vcc_hi, 12
	s_cselect_b32 s3, s1, s3
	s_cselect_b32 s2, s26, s2
	s_cselect_b32 s51, s25, vcc_lo
	s_cselect_b32 s50, s27, s37
	s_add_i32 s67, 0, 0x14000
	v_add_u32_e32 v140, s66, v214
	v_add_u32_e32 v156, s67, v214
	ds_read_b128 v[128:131], v140
	ds_read_b128 v[132:135], v140 offset:1024
	ds_read_b128 v[136:139], v140 offset:2048
	ds_read_b128 v[140:143], v140 offset:3072
	ds_read_b128 v[144:147], v156
	ds_read_b128 v[148:151], v156 offset:1024
	ds_read_b128 v[152:155], v156 offset:2048
	ds_read_b128 v[156:159], v156 offset:3072
	v_lshl_add_u64 v[212:213], s[54:55], 0, v[178:179]
	s_add_i32 m0, s79, 0xc000
	ds_read_b128 v[160:163], v216
	ds_read_b128 v[164:167], v216 offset:1024
	ds_read_b128 v[168:171], v216 offset:2048
	ds_read_b128 v[172:175], v216 offset:3072
	ds_read_b128 v[180:183], v216 offset:4096
	ds_read_b128 v[200:203], v216 offset:5120
	ds_read_b128 v[204:207], v216 offset:6144
	ds_read_b128 v[208:211], v216 offset:7168
	global_load_lds_dwordx4 v[212:213], off
	v_lshl_add_u64 v[212:213], v[212:213], 0, s[84:85]
	s_add_i32 m0, s79, 0xe000
	s_nop 0
	global_load_lds_dwordx4 v[212:213], off
	s_waitcnt vmcnt(8)
	s_waitcnt lgkmcnt(0)
	s_barrier
	s_waitcnt lgkmcnt(0)
	v_mfma_f32_16x16x32_bf16 v[124:127], v[128:131], v[160:163], v[124:127]
	v_mfma_f32_16x16x32_bf16 v[120:123], v[136:139], v[160:163], v[120:123]
	v_mfma_f32_16x16x32_bf16 v[108:111], v[128:131], v[168:171], v[108:111]
	v_mfma_f32_16x16x32_bf16 v[104:107], v[136:139], v[168:171], v[104:107]
	v_mfma_f32_16x16x32_bf16 v[92:95], v[128:131], v[180:183], v[92:95]
	v_mfma_f32_16x16x32_bf16 v[88:91], v[136:139], v[180:183], v[88:91]
	v_mfma_f32_16x16x32_bf16 v[76:79], v[128:131], v[204:207], v[76:79]
	v_mfma_f32_16x16x32_bf16 v[72:75], v[136:139], v[204:207], v[72:75]
	v_mfma_f32_16x16x32_bf16 v[124:127], v[132:135], v[164:167], v[124:127]
	v_mfma_f32_16x16x32_bf16 v[120:123], v[140:143], v[164:167], v[120:123]
	v_mfma_f32_16x16x32_bf16 v[108:111], v[132:135], v[172:175], v[108:111]
	v_mfma_f32_16x16x32_bf16 v[104:107], v[140:143], v[172:175], v[104:107]
	v_mfma_f32_16x16x32_bf16 v[92:95], v[132:135], v[200:203], v[92:95]
	v_mfma_f32_16x16x32_bf16 v[88:91], v[140:143], v[200:203], v[88:91]
	v_mfma_f32_16x16x32_bf16 v[76:79], v[132:135], v[208:211], v[76:79]
	v_mfma_f32_16x16x32_bf16 v[72:75], v[140:143], v[208:211], v[72:75]
	v_mfma_f32_16x16x32_bf16 v[116:119], v[144:147], v[160:163], v[116:119]
	v_mfma_f32_16x16x32_bf16 v[112:115], v[152:155], v[160:163], v[112:115]
	v_mfma_f32_16x16x32_bf16 v[100:103], v[144:147], v[168:171], v[100:103]
	v_mfma_f32_16x16x32_bf16 v[96:99], v[152:155], v[168:171], v[96:99]
	v_mfma_f32_16x16x32_bf16 v[84:87], v[144:147], v[180:183], v[84:87]
	v_mfma_f32_16x16x32_bf16 v[80:83], v[152:155], v[180:183], v[80:83]
	v_mfma_f32_16x16x32_bf16 v[68:71], v[144:147], v[204:207], v[68:71]
	v_mfma_f32_16x16x32_bf16 v[64:67], v[152:155], v[204:207], v[64:67]
	v_mfma_f32_16x16x32_bf16 v[116:119], v[148:151], v[164:167], v[116:119]
	v_mfma_f32_16x16x32_bf16 v[112:115], v[156:159], v[164:167], v[112:115]
	v_mfma_f32_16x16x32_bf16 v[100:103], v[148:151], v[172:175], v[100:103]
	v_mfma_f32_16x16x32_bf16 v[96:99], v[156:159], v[172:175], v[96:99]
	v_mfma_f32_16x16x32_bf16 v[84:87], v[148:151], v[200:203], v[84:87]
	v_mfma_f32_16x16x32_bf16 v[80:83], v[156:159], v[200:203], v[80:83]
	v_mfma_f32_16x16x32_bf16 v[68:71], v[148:151], v[208:211], v[68:71]
	v_mfma_f32_16x16x32_bf16 v[64:67], v[156:159], v[208:211], v[64:67]
	s_barrier
	v_lshl_add_u64 v[212:213], s[50:51], 0, v[184:185]
	s_add_i32 s50, s66, s78
	s_mov_b32 m0, s50
	ds_read_b128 v[160:163], v216 offset:16384
	ds_read_b128 v[164:167], v216 offset:17408
	ds_read_b128 v[168:171], v216 offset:18432
	ds_read_b128 v[172:175], v216 offset:19456
	ds_read_b128 v[180:183], v216 offset:20480
	ds_read_b128 v[200:203], v216 offset:21504
	ds_read_b128 v[204:207], v216 offset:22528
	ds_read_b128 v[208:211], v216 offset:23552
	global_load_lds_dwordx4 v[212:213], off
	v_lshl_add_u64 v[218:219], v[212:213], 0, s[84:85]
	s_add_i32 m0, s50, 0x2000
	s_add_i32 s50, s67, s78
	global_load_lds_dwordx4 v[218:219], off
	v_lshl_add_u64 v[218:219], v[212:213], 0, s[86:87]
	s_mov_b32 m0, s50
	s_nop 0
	global_load_lds_dwordx4 v[218:219], off
	v_lshl_add_u64 v[218:219], v[212:213], 0, s[88:89]
	s_add_i32 m0, s50, 0x2000
	s_nop 0
	global_load_lds_dwordx4 v[218:219], off
	v_lshl_add_u64 v[218:219], s[2:3], 0, v[176:177]
	s_mov_b32 m0, s79
	v_lshl_add_u64 v[220:221], v[218:219], 0, s[84:85]
	global_load_lds_dwordx4 v[218:219], off
	s_mov_b32 m0, s80
	s_nop 0
	global_load_lds_dwordx4 v[220:221], off
	s_waitcnt vmcnt(8)
	s_waitcnt lgkmcnt(0)
	s_barrier
	s_waitcnt lgkmcnt(0)
	v_mfma_f32_16x16x32_bf16 v[60:63], v[128:131], v[160:163], v[60:63]
	v_mfma_f32_16x16x32_bf16 v[56:59], v[136:139], v[160:163], v[56:59]
	v_mfma_f32_16x16x32_bf16 v[44:47], v[128:131], v[168:171], v[44:47]
	v_mfma_f32_16x16x32_bf16 v[40:43], v[136:139], v[168:171], v[40:43]
	v_mfma_f32_16x16x32_bf16 v[28:31], v[128:131], v[180:183], v[28:31]
	v_mfma_f32_16x16x32_bf16 v[24:27], v[136:139], v[180:183], v[24:27]
	v_mfma_f32_16x16x32_bf16 v[12:15], v[128:131], v[204:207], v[12:15]
	v_mfma_f32_16x16x32_bf16 v[8:11], v[136:139], v[204:207], v[8:11]
	v_mfma_f32_16x16x32_bf16 v[60:63], v[132:135], v[164:167], v[60:63]
	v_mfma_f32_16x16x32_bf16 v[56:59], v[140:143], v[164:167], v[56:59]
	v_mfma_f32_16x16x32_bf16 v[44:47], v[132:135], v[172:175], v[44:47]
	v_mfma_f32_16x16x32_bf16 v[40:43], v[140:143], v[172:175], v[40:43]
	v_mfma_f32_16x16x32_bf16 v[28:31], v[132:135], v[200:203], v[28:31]
	v_mfma_f32_16x16x32_bf16 v[24:27], v[140:143], v[200:203], v[24:27]
	v_mfma_f32_16x16x32_bf16 v[12:15], v[132:135], v[208:211], v[12:15]
	v_mfma_f32_16x16x32_bf16 v[8:11], v[140:143], v[208:211], v[8:11]
	v_mfma_f32_16x16x32_bf16 v[52:55], v[144:147], v[160:163], v[52:55]
	v_mfma_f32_16x16x32_bf16 v[48:51], v[152:155], v[160:163], v[48:51]
	v_mfma_f32_16x16x32_bf16 v[36:39], v[144:147], v[168:171], v[36:39]
	v_mfma_f32_16x16x32_bf16 v[32:35], v[152:155], v[168:171], v[32:35]
	v_mfma_f32_16x16x32_bf16 v[20:23], v[144:147], v[180:183], v[20:23]
	v_mfma_f32_16x16x32_bf16 v[16:19], v[152:155], v[180:183], v[16:19]
	v_mfma_f32_16x16x32_bf16 v[4:7], v[144:147], v[204:207], v[4:7]
	v_mfma_f32_16x16x32_bf16 v[0:3], v[152:155], v[204:207], v[0:3]
	v_mfma_f32_16x16x32_bf16 v[52:55], v[148:151], v[164:167], v[52:55]
	v_mfma_f32_16x16x32_bf16 v[48:51], v[156:159], v[164:167], v[48:51]
	v_mfma_f32_16x16x32_bf16 v[36:39], v[148:151], v[172:175], v[36:39]
	v_mfma_f32_16x16x32_bf16 v[32:35], v[156:159], v[172:175], v[32:35]
	v_mfma_f32_16x16x32_bf16 v[20:23], v[148:151], v[200:203], v[20:23]
	v_mfma_f32_16x16x32_bf16 v[16:19], v[156:159], v[200:203], v[16:19]
	v_mfma_f32_16x16x32_bf16 v[4:7], v[148:151], v[208:211], v[4:7]
	v_mfma_f32_16x16x32_bf16 v[0:3], v[156:159], v[208:211], v[0:3]
	s_barrier
	s_add_i32 s2, 0, 0x18000
	s_add_i32 s3, 0, 0x1c000
	v_add_u32_e32 v140, s2, v214
	v_add_u32_e32 v156, s3, v214
	ds_read_b128 v[128:131], v140
	ds_read_b128 v[132:135], v140 offset:1024
	ds_read_b128 v[136:139], v140 offset:2048
	ds_read_b128 v[140:143], v140 offset:3072
	ds_read_b128 v[144:147], v156
	ds_read_b128 v[148:151], v156 offset:1024
	ds_read_b128 v[152:155], v156 offset:2048
	ds_read_b128 v[156:159], v156 offset:3072
	s_mov_b32 m0, s81
	v_lshl_add_u64 v[220:221], v[218:219], 0, s[86:87]
	ds_read_b128 v[160:163], v216 offset:32768
	ds_read_b128 v[164:167], v216 offset:33792
	ds_read_b128 v[168:171], v216 offset:34816
	ds_read_b128 v[172:175], v216 offset:35840
	ds_read_b128 v[180:183], v216 offset:36864
	ds_read_b128 v[200:203], v216 offset:37888
	ds_read_b128 v[204:207], v216 offset:38912
	ds_read_b128 v[208:211], v216 offset:39936
	global_load_lds_dwordx4 v[220:221], off
	v_lshl_add_u64 v[220:221], v[218:219], 0, s[88:89]
	s_mov_b32 m0, s82
	s_nop 0
	global_load_lds_dwordx4 v[220:221], off
	s_waitcnt vmcnt(8)
	s_waitcnt lgkmcnt(0)
	s_barrier
	s_waitcnt lgkmcnt(0)
	v_mfma_f32_16x16x32_bf16 v[124:127], v[128:131], v[160:163], v[124:127]
	v_mfma_f32_16x16x32_bf16 v[120:123], v[136:139], v[160:163], v[120:123]
	v_mfma_f32_16x16x32_bf16 v[108:111], v[128:131], v[168:171], v[108:111]
	v_mfma_f32_16x16x32_bf16 v[104:107], v[136:139], v[168:171], v[104:107]
	v_mfma_f32_16x16x32_bf16 v[92:95], v[128:131], v[180:183], v[92:95]
	v_mfma_f32_16x16x32_bf16 v[88:91], v[136:139], v[180:183], v[88:91]
	v_mfma_f32_16x16x32_bf16 v[76:79], v[128:131], v[204:207], v[76:79]
	v_mfma_f32_16x16x32_bf16 v[72:75], v[136:139], v[204:207], v[72:75]
	v_mfma_f32_16x16x32_bf16 v[124:127], v[132:135], v[164:167], v[124:127]
	v_mfma_f32_16x16x32_bf16 v[120:123], v[140:143], v[164:167], v[120:123]
	v_mfma_f32_16x16x32_bf16 v[108:111], v[132:135], v[172:175], v[108:111]
	v_mfma_f32_16x16x32_bf16 v[104:107], v[140:143], v[172:175], v[104:107]
	v_mfma_f32_16x16x32_bf16 v[92:95], v[132:135], v[200:203], v[92:95]
	v_mfma_f32_16x16x32_bf16 v[88:91], v[140:143], v[200:203], v[88:91]
	v_mfma_f32_16x16x32_bf16 v[76:79], v[132:135], v[208:211], v[76:79]
	v_mfma_f32_16x16x32_bf16 v[72:75], v[140:143], v[208:211], v[72:75]
	v_mfma_f32_16x16x32_bf16 v[116:119], v[144:147], v[160:163], v[116:119]
	v_mfma_f32_16x16x32_bf16 v[112:115], v[152:155], v[160:163], v[112:115]
	v_mfma_f32_16x16x32_bf16 v[100:103], v[144:147], v[168:171], v[100:103]
	v_mfma_f32_16x16x32_bf16 v[96:99], v[152:155], v[168:171], v[96:99]
	v_mfma_f32_16x16x32_bf16 v[84:87], v[144:147], v[180:183], v[84:87]
	v_mfma_f32_16x16x32_bf16 v[80:83], v[152:155], v[180:183], v[80:83]
	v_mfma_f32_16x16x32_bf16 v[68:71], v[144:147], v[204:207], v[68:71]
	v_mfma_f32_16x16x32_bf16 v[64:67], v[152:155], v[204:207], v[64:67]
	v_mfma_f32_16x16x32_bf16 v[116:119], v[148:151], v[164:167], v[116:119]
	v_mfma_f32_16x16x32_bf16 v[112:115], v[156:159], v[164:167], v[112:115]
	v_mfma_f32_16x16x32_bf16 v[100:103], v[148:151], v[172:175], v[100:103]
	v_mfma_f32_16x16x32_bf16 v[96:99], v[156:159], v[172:175], v[96:99]
	v_mfma_f32_16x16x32_bf16 v[84:87], v[148:151], v[200:203], v[84:87]
	v_mfma_f32_16x16x32_bf16 v[80:83], v[156:159], v[200:203], v[80:83]
	v_mfma_f32_16x16x32_bf16 v[68:71], v[148:151], v[208:211], v[68:71]
	v_mfma_f32_16x16x32_bf16 v[64:67], v[156:159], v[208:211], v[64:67]
	s_barrier
	s_add_i32 s2, s2, s78
	v_lshl_add_u64 v[220:221], v[212:213], 0, s[90:91]
	s_mov_b32 m0, s2
	ds_read_b128 v[160:163], v216 offset:49152
	ds_read_b128 v[164:167], v216 offset:50176
	ds_read_b128 v[168:171], v216 offset:51200
	ds_read_b128 v[172:175], v216 offset:52224
	ds_read_b128 v[180:183], v216 offset:53248
	ds_read_b128 v[200:203], v216 offset:54272
	ds_read_b128 v[204:207], v216 offset:55296
	ds_read_b128 v[208:211], v216 offset:56320
	global_load_lds_dwordx4 v[220:221], off
	v_lshl_add_u64 v[220:221], v[212:213], 0, s[92:93]
	s_add_i32 m0, s2, 0x2000
	s_add_i32 s2, s3, s78
	global_load_lds_dwordx4 v[220:221], off
	v_lshl_add_u64 v[220:221], v[212:213], 0, s[94:95]
	s_mov_b32 m0, s2
	v_lshl_add_u64 v[212:213], v[212:213], 0, s[96:97]
	global_load_lds_dwordx4 v[220:221], off
	s_add_i32 m0, s2, 0x2000
	s_nop 0
	global_load_lds_dwordx4 v[212:213], off
	v_lshl_add_u64 v[212:213], v[218:219], 0, s[90:91]
	s_mov_b32 m0, s48
	s_nop 0
	global_load_lds_dwordx4 v[212:213], off
	v_lshl_add_u64 v[212:213], v[218:219], 0, s[92:93]
	s_mov_b32 m0, s49
	s_nop 0
	global_load_lds_dwordx4 v[212:213], off
	s_waitcnt vmcnt(8)
	s_waitcnt lgkmcnt(0)
	s_barrier
	s_waitcnt lgkmcnt(0)
	v_mfma_f32_16x16x32_bf16 v[60:63], v[128:131], v[160:163], v[60:63]
	v_mfma_f32_16x16x32_bf16 v[56:59], v[136:139], v[160:163], v[56:59]
	v_mfma_f32_16x16x32_bf16 v[44:47], v[128:131], v[168:171], v[44:47]
	v_mfma_f32_16x16x32_bf16 v[40:43], v[136:139], v[168:171], v[40:43]
	v_mfma_f32_16x16x32_bf16 v[28:31], v[128:131], v[180:183], v[28:31]
	v_mfma_f32_16x16x32_bf16 v[24:27], v[136:139], v[180:183], v[24:27]
	v_mfma_f32_16x16x32_bf16 v[12:15], v[128:131], v[204:207], v[12:15]
	v_mfma_f32_16x16x32_bf16 v[8:11], v[136:139], v[204:207], v[8:11]
	v_mfma_f32_16x16x32_bf16 v[60:63], v[132:135], v[164:167], v[60:63]
	v_mfma_f32_16x16x32_bf16 v[56:59], v[140:143], v[164:167], v[56:59]
	v_mfma_f32_16x16x32_bf16 v[44:47], v[132:135], v[172:175], v[44:47]
	v_mfma_f32_16x16x32_bf16 v[40:43], v[140:143], v[172:175], v[40:43]
	v_mfma_f32_16x16x32_bf16 v[28:31], v[132:135], v[200:203], v[28:31]
	v_mfma_f32_16x16x32_bf16 v[24:27], v[140:143], v[200:203], v[24:27]
	v_mfma_f32_16x16x32_bf16 v[12:15], v[132:135], v[208:211], v[12:15]
	v_mfma_f32_16x16x32_bf16 v[8:11], v[140:143], v[208:211], v[8:11]
	v_mfma_f32_16x16x32_bf16 v[52:55], v[144:147], v[160:163], v[52:55]
	v_mfma_f32_16x16x32_bf16 v[48:51], v[152:155], v[160:163], v[48:51]
	v_mfma_f32_16x16x32_bf16 v[36:39], v[144:147], v[168:171], v[36:39]
	v_mfma_f32_16x16x32_bf16 v[32:35], v[152:155], v[168:171], v[32:35]
	v_mfma_f32_16x16x32_bf16 v[20:23], v[144:147], v[180:183], v[20:23]
	v_mfma_f32_16x16x32_bf16 v[16:19], v[152:155], v[180:183], v[16:19]
	v_mfma_f32_16x16x32_bf16 v[4:7], v[144:147], v[204:207], v[4:7]
	v_mfma_f32_16x16x32_bf16 v[0:3], v[152:155], v[204:207], v[0:3]
	v_mfma_f32_16x16x32_bf16 v[52:55], v[148:151], v[164:167], v[52:55]
	v_mfma_f32_16x16x32_bf16 v[48:51], v[156:159], v[164:167], v[48:51]
	v_mfma_f32_16x16x32_bf16 v[36:39], v[148:151], v[172:175], v[36:39]
	v_mfma_f32_16x16x32_bf16 v[32:35], v[156:159], v[172:175], v[32:35]
	v_mfma_f32_16x16x32_bf16 v[20:23], v[148:151], v[200:203], v[20:23]
	v_mfma_f32_16x16x32_bf16 v[16:19], v[156:159], v[200:203], v[16:19]
	v_mfma_f32_16x16x32_bf16 v[4:7], v[148:151], v[208:211], v[4:7]
	v_mfma_f32_16x16x32_bf16 v[0:3], v[156:159], v[208:211], v[0:3]
	s_barrier
	s_add_i32 vcc_hi, vcc_hi, 2
	s_add_u32 s54, s54, 0x100
	s_addc_u32 s55, s55, 0
	s_add_u32 s37, s37, 0x100
	s_addc_u32 vcc_lo, vcc_lo, 0
	s_cmp_gt_u32 vcc_hi, 13
	s_cbranch_scc0 .LBB0_1597
	s_and_b64 vcc, exec, s[22:23]
	s_cbranch_vccz .LBB0_1600
	s_barrier

.LBB0_1692:
	s_add_u32 s2, s10, 0xfffc0080
	s_addc_u32 s3, s11, -1
	s_add_i32 s73, 0, 0x10000
	s_cmp_eq_u32 s55, 12
	s_cselect_b32 s3, s0, s3
	s_cselect_b32 s2, s1, s2
	s_cselect_b32 vcc_hi, s79, s54
	s_cselect_b32 vcc_lo, s78, s49
	s_add_i32 s77, 0, 0x14000
	v_add_u32_e32 v144, s73, v206
	v_add_u32_e32 v160, s77, v206
	ds_read_b128 v[132:135], v144
	ds_read_b128 v[136:139], v144 offset:1024
	ds_read_b128 v[140:143], v144 offset:2048
	ds_read_b128 v[144:147], v144 offset:3072
	ds_read_b128 v[148:151], v160
	ds_read_b128 v[152:155], v160 offset:1024
	ds_read_b128 v[156:159], v160 offset:2048
	ds_read_b128 v[160:163], v160 offset:3072
	v_lshl_add_u64 v[204:205], s[10:11], 0, v[130:131]
	s_add_i32 m0, s51, 0xc000
	ds_read_b128 v[164:167], v240
	ds_read_b128 v[168:171], v240 offset:1024
	ds_read_b128 v[172:175], v240 offset:2048
	ds_read_b128 v[176:179], v240 offset:3072
	ds_read_b128 v[180:183], v240 offset:4096
	ds_read_b128 v[200:203], v240 offset:5120
	ds_read_b128 v[242:245], v240 offset:6144
	ds_read_b128 v[246:249], v240 offset:7168
	global_load_lds_dwordx4 v[204:205], off
	v_lshl_add_u64 v[204:205], v[204:205], 0, s[84:85]
	s_add_i32 m0, s51, 0xe000
	s_nop 0
	global_load_lds_dwordx4 v[204:205], off
	s_waitcnt vmcnt(8)
	s_waitcnt lgkmcnt(0)
	s_barrier
	s_waitcnt lgkmcnt(0)
	v_mfma_f32_16x16x32_bf16 v[124:127], v[132:135], v[164:167], v[124:127]
	v_mfma_f32_16x16x32_bf16 v[120:123], v[140:143], v[164:167], v[120:123]
	v_mfma_f32_16x16x32_bf16 v[108:111], v[132:135], v[172:175], v[108:111]
	v_mfma_f32_16x16x32_bf16 v[104:107], v[140:143], v[172:175], v[104:107]
	v_mfma_f32_16x16x32_bf16 v[92:95], v[132:135], v[180:183], v[92:95]
	v_mfma_f32_16x16x32_bf16 v[88:91], v[140:143], v[180:183], v[88:91]
	v_mfma_f32_16x16x32_bf16 v[76:79], v[132:135], v[242:245], v[76:79]
	v_mfma_f32_16x16x32_bf16 v[72:75], v[140:143], v[242:245], v[72:75]
	v_mfma_f32_16x16x32_bf16 v[124:127], v[136:139], v[168:171], v[124:127]
	v_mfma_f32_16x16x32_bf16 v[120:123], v[144:147], v[168:171], v[120:123]
	v_mfma_f32_16x16x32_bf16 v[108:111], v[136:139], v[176:179], v[108:111]
	v_mfma_f32_16x16x32_bf16 v[104:107], v[144:147], v[176:179], v[104:107]
	v_mfma_f32_16x16x32_bf16 v[92:95], v[136:139], v[200:203], v[92:95]
	v_mfma_f32_16x16x32_bf16 v[88:91], v[144:147], v[200:203], v[88:91]
	v_mfma_f32_16x16x32_bf16 v[76:79], v[136:139], v[246:249], v[76:79]
	v_mfma_f32_16x16x32_bf16 v[72:75], v[144:147], v[246:249], v[72:75]
	v_mfma_f32_16x16x32_bf16 v[116:119], v[148:151], v[164:167], v[116:119]
	v_mfma_f32_16x16x32_bf16 v[112:115], v[156:159], v[164:167], v[112:115]
	v_mfma_f32_16x16x32_bf16 v[100:103], v[148:151], v[172:175], v[100:103]
	v_mfma_f32_16x16x32_bf16 v[96:99], v[156:159], v[172:175], v[96:99]
	v_mfma_f32_16x16x32_bf16 v[84:87], v[148:151], v[180:183], v[84:87]
	v_mfma_f32_16x16x32_bf16 v[80:83], v[156:159], v[180:183], v[80:83]
	v_mfma_f32_16x16x32_bf16 v[68:71], v[148:151], v[242:245], v[68:71]
	v_mfma_f32_16x16x32_bf16 v[64:67], v[156:159], v[242:245], v[64:67]
	v_mfma_f32_16x16x32_bf16 v[116:119], v[152:155], v[168:171], v[116:119]
	v_mfma_f32_16x16x32_bf16 v[112:115], v[160:163], v[168:171], v[112:115]
	v_mfma_f32_16x16x32_bf16 v[100:103], v[152:155], v[176:179], v[100:103]
	v_mfma_f32_16x16x32_bf16 v[96:99], v[160:163], v[176:179], v[96:99]
	v_mfma_f32_16x16x32_bf16 v[84:87], v[152:155], v[200:203], v[84:87]
	v_mfma_f32_16x16x32_bf16 v[80:83], v[160:163], v[200:203], v[80:83]
	v_mfma_f32_16x16x32_bf16 v[68:71], v[152:155], v[246:249], v[68:71]
	v_mfma_f32_16x16x32_bf16 v[64:67], v[160:163], v[246:249], v[64:67]
	s_barrier
	s_add_i32 s73, s73, s50
	v_lshl_add_u64 v[204:205], vcc, 0, v[184:185]
	s_mov_b32 m0, s73
	ds_read_b128 v[164:167], v240 offset:16384
	ds_read_b128 v[168:171], v240 offset:17408
	ds_read_b128 v[172:175], v240 offset:18432
	ds_read_b128 v[176:179], v240 offset:19456
	ds_read_b128 v[180:183], v240 offset:20480
	ds_read_b128 v[200:203], v240 offset:21504
	ds_read_b128 v[242:245], v240 offset:22528
	ds_read_b128 v[246:249], v240 offset:23552
	global_load_lds_dwordx4 v[204:205], off
	v_lshl_add_u64 v[250:251], v[204:205], 0, s[84:85]
	s_add_i32 m0, s73, 0x2000
	s_add_i32 s73, s77, s50
	global_load_lds_dwordx4 v[250:251], off
	v_lshl_add_u64 v[250:251], v[204:205], 0, s[86:87]
	s_mov_b32 m0, s73
	s_nop 0
	global_load_lds_dwordx4 v[250:251], off
	v_lshl_add_u64 v[250:251], v[204:205], 0, s[88:89]
	s_add_i32 m0, s73, 0x2000
	s_nop 0
	global_load_lds_dwordx4 v[250:251], off
	v_lshl_add_u64 v[250:251], s[2:3], 0, v[128:129]
	s_mov_b32 m0, s51
	v_lshl_add_u64 v[252:253], v[250:251], 0, s[84:85]
	global_load_lds_dwordx4 v[250:251], off
	s_mov_b32 m0, s66
	s_nop 0
	global_load_lds_dwordx4 v[252:253], off
	s_waitcnt vmcnt(8)
	s_waitcnt lgkmcnt(0)
	s_barrier
	s_waitcnt lgkmcnt(0)
	v_mfma_f32_16x16x32_bf16 v[60:63], v[132:135], v[164:167], v[60:63]
	v_mfma_f32_16x16x32_bf16 v[56:59], v[140:143], v[164:167], v[56:59]
	v_mfma_f32_16x16x32_bf16 v[44:47], v[132:135], v[172:175], v[44:47]
	v_mfma_f32_16x16x32_bf16 v[40:43], v[140:143], v[172:175], v[40:43]
	v_mfma_f32_16x16x32_bf16 v[28:31], v[132:135], v[180:183], v[28:31]
	v_mfma_f32_16x16x32_bf16 v[24:27], v[140:143], v[180:183], v[24:27]
	v_mfma_f32_16x16x32_bf16 v[12:15], v[132:135], v[242:245], v[12:15]
	v_mfma_f32_16x16x32_bf16 v[8:11], v[140:143], v[242:245], v[8:11]
	v_mfma_f32_16x16x32_bf16 v[60:63], v[136:139], v[168:171], v[60:63]
	v_mfma_f32_16x16x32_bf16 v[56:59], v[144:147], v[168:171], v[56:59]
	v_mfma_f32_16x16x32_bf16 v[44:47], v[136:139], v[176:179], v[44:47]
	v_mfma_f32_16x16x32_bf16 v[40:43], v[144:147], v[176:179], v[40:43]
	v_mfma_f32_16x16x32_bf16 v[28:31], v[136:139], v[200:203], v[28:31]
	v_mfma_f32_16x16x32_bf16 v[24:27], v[144:147], v[200:203], v[24:27]
	v_mfma_f32_16x16x32_bf16 v[12:15], v[136:139], v[246:249], v[12:15]
	v_mfma_f32_16x16x32_bf16 v[8:11], v[144:147], v[246:249], v[8:11]
	v_mfma_f32_16x16x32_bf16 v[52:55], v[148:151], v[164:167], v[52:55]
	v_mfma_f32_16x16x32_bf16 v[48:51], v[156:159], v[164:167], v[48:51]
	v_mfma_f32_16x16x32_bf16 v[36:39], v[148:151], v[172:175], v[36:39]
	v_mfma_f32_16x16x32_bf16 v[32:35], v[156:159], v[172:175], v[32:35]
	v_mfma_f32_16x16x32_bf16 v[20:23], v[148:151], v[180:183], v[20:23]
	v_mfma_f32_16x16x32_bf16 v[16:19], v[156:159], v[180:183], v[16:19]
	v_mfma_f32_16x16x32_bf16 v[4:7], v[148:151], v[242:245], v[4:7]
	v_mfma_f32_16x16x32_bf16 v[0:3], v[156:159], v[242:245], v[0:3]
	v_mfma_f32_16x16x32_bf16 v[52:55], v[152:155], v[168:171], v[52:55]
	v_mfma_f32_16x16x32_bf16 v[48:51], v[160:163], v[168:171], v[48:51]
	v_mfma_f32_16x16x32_bf16 v[36:39], v[152:155], v[176:179], v[36:39]
	v_mfma_f32_16x16x32_bf16 v[32:35], v[160:163], v[176:179], v[32:35]
	v_mfma_f32_16x16x32_bf16 v[20:23], v[152:155], v[200:203], v[20:23]
	v_mfma_f32_16x16x32_bf16 v[16:19], v[160:163], v[200:203], v[16:19]
	v_mfma_f32_16x16x32_bf16 v[4:7], v[152:155], v[246:249], v[4:7]
	v_mfma_f32_16x16x32_bf16 v[0:3], v[160:163], v[246:249], v[0:3]
	s_barrier
	s_add_i32 s2, 0, 0x18000
	s_add_i32 s3, 0, 0x1c000
	v_add_u32_e32 v144, s2, v206
	v_add_u32_e32 v160, s3, v206
	ds_read_b128 v[132:135], v144
	ds_read_b128 v[136:139], v144 offset:1024
	ds_read_b128 v[140:143], v144 offset:2048
	ds_read_b128 v[144:147], v144 offset:3072
	ds_read_b128 v[148:151], v160
	ds_read_b128 v[152:155], v160 offset:1024
	ds_read_b128 v[156:159], v160 offset:2048
	ds_read_b128 v[160:163], v160 offset:3072
	s_mov_b32 m0, s67
	v_lshl_add_u64 v[252:253], v[250:251], 0, s[86:87]
	ds_read_b128 v[164:167], v240 offset:32768
	ds_read_b128 v[168:171], v240 offset:33792
	ds_read_b128 v[172:175], v240 offset:34816
	ds_read_b128 v[176:179], v240 offset:35840
	ds_read_b128 v[180:183], v240 offset:36864
	ds_read_b128 v[200:203], v240 offset:37888
	ds_read_b128 v[242:245], v240 offset:38912
	ds_read_b128 v[246:249], v240 offset:39936
	global_load_lds_dwordx4 v[252:253], off
	v_lshl_add_u64 v[252:253], v[250:251], 0, s[88:89]
	s_mov_b32 m0, s82
	s_nop 0
	global_load_lds_dwordx4 v[252:253], off
	s_waitcnt vmcnt(8)
	s_waitcnt lgkmcnt(0)
	s_barrier
	s_waitcnt lgkmcnt(0)
	v_mfma_f32_16x16x32_bf16 v[124:127], v[132:135], v[164:167], v[124:127]
	v_mfma_f32_16x16x32_bf16 v[120:123], v[140:143], v[164:167], v[120:123]
	v_mfma_f32_16x16x32_bf16 v[108:111], v[132:135], v[172:175], v[108:111]
	v_mfma_f32_16x16x32_bf16 v[104:107], v[140:143], v[172:175], v[104:107]
	v_mfma_f32_16x16x32_bf16 v[92:95], v[132:135], v[180:183], v[92:95]
	v_mfma_f32_16x16x32_bf16 v[88:91], v[140:143], v[180:183], v[88:91]
	v_mfma_f32_16x16x32_bf16 v[76:79], v[132:135], v[242:245], v[76:79]
	v_mfma_f32_16x16x32_bf16 v[72:75], v[140:143], v[242:245], v[72:75]
	v_mfma_f32_16x16x32_bf16 v[124:127], v[136:139], v[168:171], v[124:127]
	v_mfma_f32_16x16x32_bf16 v[120:123], v[144:147], v[168:171], v[120:123]
	v_mfma_f32_16x16x32_bf16 v[108:111], v[136:139], v[176:179], v[108:111]
	v_mfma_f32_16x16x32_bf16 v[104:107], v[144:147], v[176:179], v[104:107]
	v_mfma_f32_16x16x32_bf16 v[92:95], v[136:139], v[200:203], v[92:95]
	v_mfma_f32_16x16x32_bf16 v[88:91], v[144:147], v[200:203], v[88:91]
	v_mfma_f32_16x16x32_bf16 v[76:79], v[136:139], v[246:249], v[76:79]
	v_mfma_f32_16x16x32_bf16 v[72:75], v[144:147], v[246:249], v[72:75]
	v_mfma_f32_16x16x32_bf16 v[116:119], v[148:151], v[164:167], v[116:119]
	v_mfma_f32_16x16x32_bf16 v[112:115], v[156:159], v[164:167], v[112:115]
	v_mfma_f32_16x16x32_bf16 v[100:103], v[148:151], v[172:175], v[100:103]
	v_mfma_f32_16x16x32_bf16 v[96:99], v[156:159], v[172:175], v[96:99]
	v_mfma_f32_16x16x32_bf16 v[84:87], v[148:151], v[180:183], v[84:87]
	v_mfma_f32_16x16x32_bf16 v[80:83], v[156:159], v[180:183], v[80:83]
	v_mfma_f32_16x16x32_bf16 v[68:71], v[148:151], v[242:245], v[68:71]
	v_mfma_f32_16x16x32_bf16 v[64:67], v[156:159], v[242:245], v[64:67]
	v_mfma_f32_16x16x32_bf16 v[116:119], v[152:155], v[168:171], v[116:119]
	v_mfma_f32_16x16x32_bf16 v[112:115], v[160:163], v[168:171], v[112:115]
	v_mfma_f32_16x16x32_bf16 v[100:103], v[152:155], v[176:179], v[100:103]
	v_mfma_f32_16x16x32_bf16 v[96:99], v[160:163], v[176:179], v[96:99]
	v_mfma_f32_16x16x32_bf16 v[84:87], v[152:155], v[200:203], v[84:87]
	v_mfma_f32_16x16x32_bf16 v[80:83], v[160:163], v[200:203], v[80:83]
	v_mfma_f32_16x16x32_bf16 v[68:71], v[152:155], v[246:249], v[68:71]
	v_mfma_f32_16x16x32_bf16 v[64:67], v[160:163], v[246:249], v[64:67]
	s_barrier
	s_add_i32 s2, s2, s50
	v_lshl_add_u64 v[252:253], v[204:205], 0, s[90:91]
	s_mov_b32 m0, s2
	ds_read_b128 v[164:167], v240 offset:49152
	ds_read_b128 v[168:171], v240 offset:50176
	ds_read_b128 v[172:175], v240 offset:51200
	ds_read_b128 v[176:179], v240 offset:52224
	ds_read_b128 v[180:183], v240 offset:53248
	ds_read_b128 v[200:203], v240 offset:54272
	ds_read_b128 v[242:245], v240 offset:55296
	ds_read_b128 v[246:249], v240 offset:56320
	global_load_lds_dwordx4 v[252:253], off
	v_lshl_add_u64 v[252:253], v[204:205], 0, s[92:93]
	s_add_i32 m0, s2, 0x2000
	s_add_i32 s2, s3, s50
	global_load_lds_dwordx4 v[252:253], off
	v_lshl_add_u64 v[252:253], v[204:205], 0, s[94:95]
	s_mov_b32 m0, s2
	v_lshl_add_u64 v[204:205], v[204:205], 0, s[96:97]
	global_load_lds_dwordx4 v[252:253], off
	s_add_i32 m0, s2, 0x2000
	s_nop 0
	global_load_lds_dwordx4 v[204:205], off
	v_lshl_add_u64 v[204:205], v[250:251], 0, s[90:91]
	s_mov_b32 m0, s83
	s_nop 0
	global_load_lds_dwordx4 v[204:205], off
	v_lshl_add_u64 v[204:205], v[250:251], 0, s[92:93]
	s_mov_b32 m0, s16
	s_nop 0
	global_load_lds_dwordx4 v[204:205], off
	s_waitcnt vmcnt(8)
	s_waitcnt lgkmcnt(0)
	s_barrier
	s_waitcnt lgkmcnt(0)
	v_mfma_f32_16x16x32_bf16 v[60:63], v[132:135], v[164:167], v[60:63]
	v_mfma_f32_16x16x32_bf16 v[56:59], v[140:143], v[164:167], v[56:59]
	v_mfma_f32_16x16x32_bf16 v[44:47], v[132:135], v[172:175], v[44:47]
	v_mfma_f32_16x16x32_bf16 v[40:43], v[140:143], v[172:175], v[40:43]
	v_mfma_f32_16x16x32_bf16 v[28:31], v[132:135], v[180:183], v[28:31]
	v_mfma_f32_16x16x32_bf16 v[24:27], v[140:143], v[180:183], v[24:27]
	v_mfma_f32_16x16x32_bf16 v[12:15], v[132:135], v[242:245], v[12:15]
	v_mfma_f32_16x16x32_bf16 v[8:11], v[140:143], v[242:245], v[8:11]
	v_mfma_f32_16x16x32_bf16 v[60:63], v[136:139], v[168:171], v[60:63]
	v_mfma_f32_16x16x32_bf16 v[56:59], v[144:147], v[168:171], v[56:59]
	v_mfma_f32_16x16x32_bf16 v[44:47], v[136:139], v[176:179], v[44:47]
	v_mfma_f32_16x16x32_bf16 v[40:43], v[144:147], v[176:179], v[40:43]
	v_mfma_f32_16x16x32_bf16 v[28:31], v[136:139], v[200:203], v[28:31]
	v_mfma_f32_16x16x32_bf16 v[24:27], v[144:147], v[200:203], v[24:27]
	v_mfma_f32_16x16x32_bf16 v[12:15], v[136:139], v[246:249], v[12:15]
	v_mfma_f32_16x16x32_bf16 v[8:11], v[144:147], v[246:249], v[8:11]
	v_mfma_f32_16x16x32_bf16 v[52:55], v[148:151], v[164:167], v[52:55]
	v_mfma_f32_16x16x32_bf16 v[48:51], v[156:159], v[164:167], v[48:51]
	v_mfma_f32_16x16x32_bf16 v[36:39], v[148:151], v[172:175], v[36:39]
	v_mfma_f32_16x16x32_bf16 v[32:35], v[156:159], v[172:175], v[32:35]
	v_mfma_f32_16x16x32_bf16 v[20:23], v[148:151], v[180:183], v[20:23]
	v_mfma_f32_16x16x32_bf16 v[16:19], v[156:159], v[180:183], v[16:19]
	v_mfma_f32_16x16x32_bf16 v[4:7], v[148:151], v[242:245], v[4:7]
	v_mfma_f32_16x16x32_bf16 v[0:3], v[156:159], v[242:245], v[0:3]
	v_mfma_f32_16x16x32_bf16 v[52:55], v[152:155], v[168:171], v[52:55]
	v_mfma_f32_16x16x32_bf16 v[48:51], v[160:163], v[168:171], v[48:51]
	v_mfma_f32_16x16x32_bf16 v[36:39], v[152:155], v[176:179], v[36:39]
	v_mfma_f32_16x16x32_bf16 v[32:35], v[160:163], v[176:179], v[32:35]
	v_mfma_f32_16x16x32_bf16 v[20:23], v[152:155], v[200:203], v[20:23]
	v_mfma_f32_16x16x32_bf16 v[16:19], v[160:163], v[200:203], v[16:19]
	v_mfma_f32_16x16x32_bf16 v[4:7], v[152:155], v[246:249], v[4:7]
	v_mfma_f32_16x16x32_bf16 v[0:3], v[160:163], v[246:249], v[0:3]
	s_barrier
	s_add_i32 s55, s55, 2
	s_add_u32 s10, s10, 0x100
	s_addc_u32 s11, s11, 0
	s_add_u32 s49, s49, 0x100
	s_addc_u32 s54, s54, 0
	s_cmp_gt_u32 s55, 13
	s_cbranch_scc0 .LBB0_1692
	s_and_b64 vcc, exec, s[24:25]
	s_cbranch_vccz .LBB0_1695
	s_barrier

.LBB0_1827:
	s_add_u32 s2, s10, 0xfffc0080
	s_addc_u32 s3, s11, -1
	s_add_i32 s26, 0, 0x10000
	s_cmp_eq_u32 s77, 12
	s_cselect_b32 s3, s1, s3
	s_cselect_b32 s2, s73, s2
	s_cselect_b32 vcc_hi, s79, s55
	s_cselect_b32 vcc_lo, s78, s54
	s_add_i32 s27, 0, 0x14000
	v_add_u32_e32 v140, s26, v214
	v_add_u32_e32 v156, s27, v214
	ds_read_b128 v[128:131], v140
	ds_read_b128 v[132:135], v140 offset:1024
	ds_read_b128 v[136:139], v140 offset:2048
	ds_read_b128 v[140:143], v140 offset:3072
	ds_read_b128 v[144:147], v156
	ds_read_b128 v[148:151], v156 offset:1024
	ds_read_b128 v[152:155], v156 offset:2048
	ds_read_b128 v[156:159], v156 offset:3072
	v_lshl_add_u64 v[212:213], s[10:11], 0, v[178:179]
	s_add_i32 m0, s51, 0xc000
	ds_read_b128 v[160:163], v216
	ds_read_b128 v[164:167], v216 offset:1024
	ds_read_b128 v[168:171], v216 offset:2048
	ds_read_b128 v[172:175], v216 offset:3072
	ds_read_b128 v[180:183], v216 offset:4096
	ds_read_b128 v[200:203], v216 offset:5120
	ds_read_b128 v[204:207], v216 offset:6144
	ds_read_b128 v[208:211], v216 offset:7168
	global_load_lds_dwordx4 v[212:213], off
	v_lshl_add_u64 v[212:213], v[212:213], 0, s[84:85]
	s_add_i32 m0, s51, 0xe000
	s_nop 0
	global_load_lds_dwordx4 v[212:213], off
	s_waitcnt vmcnt(8)
	s_waitcnt lgkmcnt(0)
	s_barrier
	s_waitcnt lgkmcnt(0)
	v_mfma_f32_16x16x32_bf16 v[124:127], v[128:131], v[160:163], v[124:127]
	v_mfma_f32_16x16x32_bf16 v[120:123], v[136:139], v[160:163], v[120:123]
	v_mfma_f32_16x16x32_bf16 v[108:111], v[128:131], v[168:171], v[108:111]
	v_mfma_f32_16x16x32_bf16 v[104:107], v[136:139], v[168:171], v[104:107]
	v_mfma_f32_16x16x32_bf16 v[92:95], v[128:131], v[180:183], v[92:95]
	v_mfma_f32_16x16x32_bf16 v[88:91], v[136:139], v[180:183], v[88:91]
	v_mfma_f32_16x16x32_bf16 v[76:79], v[128:131], v[204:207], v[76:79]
	v_mfma_f32_16x16x32_bf16 v[72:75], v[136:139], v[204:207], v[72:75]
	v_mfma_f32_16x16x32_bf16 v[124:127], v[132:135], v[164:167], v[124:127]
	v_mfma_f32_16x16x32_bf16 v[120:123], v[140:143], v[164:167], v[120:123]
	v_mfma_f32_16x16x32_bf16 v[108:111], v[132:135], v[172:175], v[108:111]
	v_mfma_f32_16x16x32_bf16 v[104:107], v[140:143], v[172:175], v[104:107]
	v_mfma_f32_16x16x32_bf16 v[92:95], v[132:135], v[200:203], v[92:95]
	v_mfma_f32_16x16x32_bf16 v[88:91], v[140:143], v[200:203], v[88:91]
	v_mfma_f32_16x16x32_bf16 v[76:79], v[132:135], v[208:211], v[76:79]
	v_mfma_f32_16x16x32_bf16 v[72:75], v[140:143], v[208:211], v[72:75]
	v_mfma_f32_16x16x32_bf16 v[116:119], v[144:147], v[160:163], v[116:119]
	v_mfma_f32_16x16x32_bf16 v[112:115], v[152:155], v[160:163], v[112:115]
	v_mfma_f32_16x16x32_bf16 v[100:103], v[144:147], v[168:171], v[100:103]
	v_mfma_f32_16x16x32_bf16 v[96:99], v[152:155], v[168:171], v[96:99]
	v_mfma_f32_16x16x32_bf16 v[84:87], v[144:147], v[180:183], v[84:87]
	v_mfma_f32_16x16x32_bf16 v[80:83], v[152:155], v[180:183], v[80:83]
	v_mfma_f32_16x16x32_bf16 v[68:71], v[144:147], v[204:207], v[68:71]
	v_mfma_f32_16x16x32_bf16 v[64:67], v[152:155], v[204:207], v[64:67]
	v_mfma_f32_16x16x32_bf16 v[116:119], v[148:151], v[164:167], v[116:119]
	v_mfma_f32_16x16x32_bf16 v[112:115], v[156:159], v[164:167], v[112:115]
	v_mfma_f32_16x16x32_bf16 v[100:103], v[148:151], v[172:175], v[100:103]
	v_mfma_f32_16x16x32_bf16 v[96:99], v[156:159], v[172:175], v[96:99]
	v_mfma_f32_16x16x32_bf16 v[84:87], v[148:151], v[200:203], v[84:87]
	v_mfma_f32_16x16x32_bf16 v[80:83], v[156:159], v[200:203], v[80:83]
	v_mfma_f32_16x16x32_bf16 v[68:71], v[148:151], v[208:211], v[68:71]
	v_mfma_f32_16x16x32_bf16 v[64:67], v[156:159], v[208:211], v[64:67]
	s_barrier
	s_add_i32 s26, s26, s50
	v_lshl_add_u64 v[212:213], vcc, 0, v[184:185]
	s_mov_b32 m0, s26
	ds_read_b128 v[160:163], v216 offset:16384
	ds_read_b128 v[164:167], v216 offset:17408
	ds_read_b128 v[168:171], v216 offset:18432
	ds_read_b128 v[172:175], v216 offset:19456
	ds_read_b128 v[180:183], v216 offset:20480
	ds_read_b128 v[200:203], v216 offset:21504
	ds_read_b128 v[204:207], v216 offset:22528
	ds_read_b128 v[208:211], v216 offset:23552
	global_load_lds_dwordx4 v[212:213], off
	v_lshl_add_u64 v[218:219], v[212:213], 0, s[84:85]
	s_add_i32 m0, s26, 0x2000
	s_add_i32 s26, s27, s50
	global_load_lds_dwordx4 v[218:219], off
	v_lshl_add_u64 v[218:219], v[212:213], 0, s[86:87]
	s_mov_b32 m0, s26
	s_nop 0
	global_load_lds_dwordx4 v[218:219], off
	v_lshl_add_u64 v[218:219], v[212:213], 0, s[88:89]
	s_add_i32 m0, s26, 0x2000
	s_nop 0
	global_load_lds_dwordx4 v[218:219], off
	v_lshl_add_u64 v[218:219], s[2:3], 0, v[176:177]
	s_mov_b32 m0, s51
	v_lshl_add_u64 v[220:221], v[218:219], 0, s[84:85]
	global_load_lds_dwordx4 v[218:219], off
	s_mov_b32 m0, s66
	s_nop 0
	global_load_lds_dwordx4 v[220:221], off
	s_waitcnt vmcnt(8)
	s_waitcnt lgkmcnt(0)
	s_barrier
	s_waitcnt lgkmcnt(0)
	v_mfma_f32_16x16x32_bf16 v[60:63], v[128:131], v[160:163], v[60:63]
	v_mfma_f32_16x16x32_bf16 v[56:59], v[136:139], v[160:163], v[56:59]
	v_mfma_f32_16x16x32_bf16 v[44:47], v[128:131], v[168:171], v[44:47]
	v_mfma_f32_16x16x32_bf16 v[40:43], v[136:139], v[168:171], v[40:43]
	v_mfma_f32_16x16x32_bf16 v[28:31], v[128:131], v[180:183], v[28:31]
	v_mfma_f32_16x16x32_bf16 v[24:27], v[136:139], v[180:183], v[24:27]
	v_mfma_f32_16x16x32_bf16 v[12:15], v[128:131], v[204:207], v[12:15]
	v_mfma_f32_16x16x32_bf16 v[8:11], v[136:139], v[204:207], v[8:11]
	v_mfma_f32_16x16x32_bf16 v[60:63], v[132:135], v[164:167], v[60:63]
	v_mfma_f32_16x16x32_bf16 v[56:59], v[140:143], v[164:167], v[56:59]
	v_mfma_f32_16x16x32_bf16 v[44:47], v[132:135], v[172:175], v[44:47]
	v_mfma_f32_16x16x32_bf16 v[40:43], v[140:143], v[172:175], v[40:43]
	v_mfma_f32_16x16x32_bf16 v[28:31], v[132:135], v[200:203], v[28:31]
	v_mfma_f32_16x16x32_bf16 v[24:27], v[140:143], v[200:203], v[24:27]
	v_mfma_f32_16x16x32_bf16 v[12:15], v[132:135], v[208:211], v[12:15]
	v_mfma_f32_16x16x32_bf16 v[8:11], v[140:143], v[208:211], v[8:11]
	v_mfma_f32_16x16x32_bf16 v[52:55], v[144:147], v[160:163], v[52:55]
	v_mfma_f32_16x16x32_bf16 v[48:51], v[152:155], v[160:163], v[48:51]
	v_mfma_f32_16x16x32_bf16 v[36:39], v[144:147], v[168:171], v[36:39]
	v_mfma_f32_16x16x32_bf16 v[32:35], v[152:155], v[168:171], v[32:35]
	v_mfma_f32_16x16x32_bf16 v[20:23], v[144:147], v[180:183], v[20:23]
	v_mfma_f32_16x16x32_bf16 v[16:19], v[152:155], v[180:183], v[16:19]
	v_mfma_f32_16x16x32_bf16 v[4:7], v[144:147], v[204:207], v[4:7]
	v_mfma_f32_16x16x32_bf16 v[0:3], v[152:155], v[204:207], v[0:3]
	v_mfma_f32_16x16x32_bf16 v[52:55], v[148:151], v[164:167], v[52:55]
	v_mfma_f32_16x16x32_bf16 v[48:51], v[156:159], v[164:167], v[48:51]
	v_mfma_f32_16x16x32_bf16 v[36:39], v[148:151], v[172:175], v[36:39]
	v_mfma_f32_16x16x32_bf16 v[32:35], v[156:159], v[172:175], v[32:35]
	v_mfma_f32_16x16x32_bf16 v[20:23], v[148:151], v[200:203], v[20:23]
	v_mfma_f32_16x16x32_bf16 v[16:19], v[156:159], v[200:203], v[16:19]
	v_mfma_f32_16x16x32_bf16 v[4:7], v[148:151], v[208:211], v[4:7]
	v_mfma_f32_16x16x32_bf16 v[0:3], v[156:159], v[208:211], v[0:3]
	s_barrier
	s_add_i32 s2, 0, 0x18000
	s_add_i32 s3, 0, 0x1c000
	v_add_u32_e32 v140, s2, v214
	v_add_u32_e32 v156, s3, v214
	ds_read_b128 v[128:131], v140
	ds_read_b128 v[132:135], v140 offset:1024
	ds_read_b128 v[136:139], v140 offset:2048
	ds_read_b128 v[140:143], v140 offset:3072
	ds_read_b128 v[144:147], v156
	ds_read_b128 v[148:151], v156 offset:1024
	ds_read_b128 v[152:155], v156 offset:2048
	ds_read_b128 v[156:159], v156 offset:3072
	s_mov_b32 m0, s67
	v_lshl_add_u64 v[220:221], v[218:219], 0, s[86:87]
	ds_read_b128 v[160:163], v216 offset:32768
	ds_read_b128 v[164:167], v216 offset:33792
	ds_read_b128 v[168:171], v216 offset:34816
	ds_read_b128 v[172:175], v216 offset:35840
	ds_read_b128 v[180:183], v216 offset:36864
	ds_read_b128 v[200:203], v216 offset:37888
	ds_read_b128 v[204:207], v216 offset:38912
	ds_read_b128 v[208:211], v216 offset:39936
	global_load_lds_dwordx4 v[220:221], off
	v_lshl_add_u64 v[220:221], v[218:219], 0, s[88:89]
	s_mov_b32 m0, s82
	s_nop 0
	global_load_lds_dwordx4 v[220:221], off
	s_waitcnt vmcnt(8)
	s_waitcnt lgkmcnt(0)
	s_barrier
	s_waitcnt lgkmcnt(0)
	v_mfma_f32_16x16x32_bf16 v[124:127], v[128:131], v[160:163], v[124:127]
	v_mfma_f32_16x16x32_bf16 v[120:123], v[136:139], v[160:163], v[120:123]
	v_mfma_f32_16x16x32_bf16 v[108:111], v[128:131], v[168:171], v[108:111]
	v_mfma_f32_16x16x32_bf16 v[104:107], v[136:139], v[168:171], v[104:107]
	v_mfma_f32_16x16x32_bf16 v[92:95], v[128:131], v[180:183], v[92:95]
	v_mfma_f32_16x16x32_bf16 v[88:91], v[136:139], v[180:183], v[88:91]
	v_mfma_f32_16x16x32_bf16 v[76:79], v[128:131], v[204:207], v[76:79]
	v_mfma_f32_16x16x32_bf16 v[72:75], v[136:139], v[204:207], v[72:75]
	v_mfma_f32_16x16x32_bf16 v[124:127], v[132:135], v[164:167], v[124:127]
	v_mfma_f32_16x16x32_bf16 v[120:123], v[140:143], v[164:167], v[120:123]
	v_mfma_f32_16x16x32_bf16 v[108:111], v[132:135], v[172:175], v[108:111]
	v_mfma_f32_16x16x32_bf16 v[104:107], v[140:143], v[172:175], v[104:107]
	v_mfma_f32_16x16x32_bf16 v[92:95], v[132:135], v[200:203], v[92:95]
	v_mfma_f32_16x16x32_bf16 v[88:91], v[140:143], v[200:203], v[88:91]
	v_mfma_f32_16x16x32_bf16 v[76:79], v[132:135], v[208:211], v[76:79]
	v_mfma_f32_16x16x32_bf16 v[72:75], v[140:143], v[208:211], v[72:75]
	v_mfma_f32_16x16x32_bf16 v[116:119], v[144:147], v[160:163], v[116:119]
	v_mfma_f32_16x16x32_bf16 v[112:115], v[152:155], v[160:163], v[112:115]
	v_mfma_f32_16x16x32_bf16 v[100:103], v[144:147], v[168:171], v[100:103]
	v_mfma_f32_16x16x32_bf16 v[96:99], v[152:155], v[168:171], v[96:99]
	v_mfma_f32_16x16x32_bf16 v[84:87], v[144:147], v[180:183], v[84:87]
	v_mfma_f32_16x16x32_bf16 v[80:83], v[152:155], v[180:183], v[80:83]
	v_mfma_f32_16x16x32_bf16 v[68:71], v[144:147], v[204:207], v[68:71]
	v_mfma_f32_16x16x32_bf16 v[64:67], v[152:155], v[204:207], v[64:67]
	v_mfma_f32_16x16x32_bf16 v[116:119], v[148:151], v[164:167], v[116:119]
	v_mfma_f32_16x16x32_bf16 v[112:115], v[156:159], v[164:167], v[112:115]
	v_mfma_f32_16x16x32_bf16 v[100:103], v[148:151], v[172:175], v[100:103]
	v_mfma_f32_16x16x32_bf16 v[96:99], v[156:159], v[172:175], v[96:99]
	v_mfma_f32_16x16x32_bf16 v[84:87], v[148:151], v[200:203], v[84:87]
	v_mfma_f32_16x16x32_bf16 v[80:83], v[156:159], v[200:203], v[80:83]
	v_mfma_f32_16x16x32_bf16 v[68:71], v[148:151], v[208:211], v[68:71]
	v_mfma_f32_16x16x32_bf16 v[64:67], v[156:159], v[208:211], v[64:67]
	s_barrier
	s_add_i32 s2, s2, s50
	v_lshl_add_u64 v[220:221], v[212:213], 0, s[90:91]
	s_mov_b32 m0, s2
	ds_read_b128 v[160:163], v216 offset:49152
	ds_read_b128 v[164:167], v216 offset:50176
	ds_read_b128 v[168:171], v216 offset:51200
	ds_read_b128 v[172:175], v216 offset:52224
	ds_read_b128 v[180:183], v216 offset:53248
	ds_read_b128 v[200:203], v216 offset:54272
	ds_read_b128 v[204:207], v216 offset:55296
	ds_read_b128 v[208:211], v216 offset:56320
	global_load_lds_dwordx4 v[220:221], off
	v_lshl_add_u64 v[220:221], v[212:213], 0, s[92:93]
	s_add_i32 m0, s2, 0x2000
	s_add_i32 s2, s3, s50
	global_load_lds_dwordx4 v[220:221], off
	v_lshl_add_u64 v[220:221], v[212:213], 0, s[94:95]
	s_mov_b32 m0, s2
	v_lshl_add_u64 v[212:213], v[212:213], 0, s[96:97]
	global_load_lds_dwordx4 v[220:221], off
	s_add_i32 m0, s2, 0x2000
	s_nop 0
	global_load_lds_dwordx4 v[212:213], off
	v_lshl_add_u64 v[212:213], v[218:219], 0, s[90:91]
	s_mov_b32 m0, s83
	s_nop 0
	global_load_lds_dwordx4 v[212:213], off
	v_lshl_add_u64 v[212:213], v[218:219], 0, s[92:93]
	s_mov_b32 m0, s48
	s_nop 0
	global_load_lds_dwordx4 v[212:213], off
	s_waitcnt vmcnt(8)
	s_waitcnt lgkmcnt(0)
	s_barrier
	s_waitcnt lgkmcnt(0)
	v_mfma_f32_16x16x32_bf16 v[60:63], v[128:131], v[160:163], v[60:63]
	v_mfma_f32_16x16x32_bf16 v[56:59], v[136:139], v[160:163], v[56:59]
	v_mfma_f32_16x16x32_bf16 v[44:47], v[128:131], v[168:171], v[44:47]
	v_mfma_f32_16x16x32_bf16 v[40:43], v[136:139], v[168:171], v[40:43]
	v_mfma_f32_16x16x32_bf16 v[28:31], v[128:131], v[180:183], v[28:31]
	v_mfma_f32_16x16x32_bf16 v[24:27], v[136:139], v[180:183], v[24:27]
	v_mfma_f32_16x16x32_bf16 v[12:15], v[128:131], v[204:207], v[12:15]
	v_mfma_f32_16x16x32_bf16 v[8:11], v[136:139], v[204:207], v[8:11]
	v_mfma_f32_16x16x32_bf16 v[60:63], v[132:135], v[164:167], v[60:63]
	v_mfma_f32_16x16x32_bf16 v[56:59], v[140:143], v[164:167], v[56:59]
	v_mfma_f32_16x16x32_bf16 v[44:47], v[132:135], v[172:175], v[44:47]
	v_mfma_f32_16x16x32_bf16 v[40:43], v[140:143], v[172:175], v[40:43]
	v_mfma_f32_16x16x32_bf16 v[28:31], v[132:135], v[200:203], v[28:31]
	v_mfma_f32_16x16x32_bf16 v[24:27], v[140:143], v[200:203], v[24:27]
	v_mfma_f32_16x16x32_bf16 v[12:15], v[132:135], v[208:211], v[12:15]
	v_mfma_f32_16x16x32_bf16 v[8:11], v[140:143], v[208:211], v[8:11]
	v_mfma_f32_16x16x32_bf16 v[52:55], v[144:147], v[160:163], v[52:55]
	v_mfma_f32_16x16x32_bf16 v[48:51], v[152:155], v[160:163], v[48:51]
	v_mfma_f32_16x16x32_bf16 v[36:39], v[144:147], v[168:171], v[36:39]
	v_mfma_f32_16x16x32_bf16 v[32:35], v[152:155], v[168:171], v[32:35]
	v_mfma_f32_16x16x32_bf16 v[20:23], v[144:147], v[180:183], v[20:23]
	v_mfma_f32_16x16x32_bf16 v[16:19], v[152:155], v[180:183], v[16:19]
	v_mfma_f32_16x16x32_bf16 v[4:7], v[144:147], v[204:207], v[4:7]
	v_mfma_f32_16x16x32_bf16 v[0:3], v[152:155], v[204:207], v[0:3]
	v_mfma_f32_16x16x32_bf16 v[52:55], v[148:151], v[164:167], v[52:55]
	v_mfma_f32_16x16x32_bf16 v[48:51], v[156:159], v[164:167], v[48:51]
	v_mfma_f32_16x16x32_bf16 v[36:39], v[148:151], v[172:175], v[36:39]
	v_mfma_f32_16x16x32_bf16 v[32:35], v[156:159], v[172:175], v[32:35]
	v_mfma_f32_16x16x32_bf16 v[20:23], v[148:151], v[200:203], v[20:23]
	v_mfma_f32_16x16x32_bf16 v[16:19], v[156:159], v[200:203], v[16:19]
	v_mfma_f32_16x16x32_bf16 v[4:7], v[148:151], v[208:211], v[4:7]
	v_mfma_f32_16x16x32_bf16 v[0:3], v[156:159], v[208:211], v[0:3]
	s_barrier
	s_add_i32 s77, s77, 2
	s_add_u32 s10, s10, 0x100
	s_addc_u32 s11, s11, 0
	s_add_u32 s54, s54, 0x100
	s_addc_u32 s55, s55, 0
	s_cmp_gt_u32 s77, 13
	s_cbranch_scc0 .LBB0_1827
	s_and_b64 vcc, exec, s[36:37]
	s_cbranch_vccz .LBB0_1830
	s_barrier

.LBB0_1916:
	s_add_u32 s2, s54, 0xfffc0080
	s_addc_u32 s3, s55, -1
	s_add_i32 vcc_lo, 0, 0x10000
	s_cmp_eq_u32 s81, 12
	s_cselect_b32 s3, s0, s3
	s_cselect_b32 s2, s1, s2
	v_add_u32_e32 v136, vcc_lo, v140
	s_cselect_b32 s83, s23, s80
	s_cselect_b32 s82, s25, s49
	s_add_i32 vcc_hi, 0, 0x14000
	ds_read_b128 v[132:135], v136
	ds_read_b128 v[144:147], v136 offset:1024
	ds_read_b128 v[148:151], v136 offset:2048
	ds_read_b128 v[152:155], v136 offset:3072
	v_add_u32_e32 v136, vcc_hi, v140
	ds_read_b128 v[156:159], v136
	ds_read_b128 v[160:163], v136 offset:1024
	ds_read_b128 v[164:167], v136 offset:2048
	ds_read_b128 v[168:171], v136 offset:3072
	v_lshl_add_u64 v[136:137], s[54:55], 0, v[130:131]
	s_add_i32 m0, s51, 0xc000
	ds_read_b128 v[172:175], v142
	ds_read_b128 v[176:179], v142 offset:1024
	ds_read_b128 v[180:183], v142 offset:2048
	ds_read_b128 v[200:203], v142 offset:3072
	ds_read_b128 v[204:207], v142 offset:4096
	ds_read_b128 v[208:211], v142 offset:5120
	ds_read_b128 v[212:215], v142 offset:6144
	ds_read_b128 v[216:219], v142 offset:7168
	global_load_lds_dwordx4 v[136:137], off
	v_lshl_add_u64 v[136:137], v[136:137], 0, s[84:85]
	s_add_i32 m0, s51, 0xe000
	s_nop 0
	global_load_lds_dwordx4 v[136:137], off
	s_waitcnt vmcnt(8)
	s_waitcnt lgkmcnt(0)
	s_barrier
	s_waitcnt lgkmcnt(0)
	v_mfma_f32_16x16x32_bf16 v[124:127], v[132:135], v[172:175], v[124:127]
	v_mfma_f32_16x16x32_bf16 v[120:123], v[148:151], v[172:175], v[120:123]
	v_mfma_f32_16x16x32_bf16 v[108:111], v[132:135], v[180:183], v[108:111]
	v_mfma_f32_16x16x32_bf16 v[104:107], v[148:151], v[180:183], v[104:107]
	v_mfma_f32_16x16x32_bf16 v[92:95], v[132:135], v[204:207], v[92:95]
	v_mfma_f32_16x16x32_bf16 v[88:91], v[148:151], v[204:207], v[88:91]
	v_mfma_f32_16x16x32_bf16 v[76:79], v[132:135], v[212:215], v[76:79]
	v_mfma_f32_16x16x32_bf16 v[72:75], v[148:151], v[212:215], v[72:75]
	v_mfma_f32_16x16x32_bf16 v[124:127], v[144:147], v[176:179], v[124:127]
	v_mfma_f32_16x16x32_bf16 v[120:123], v[152:155], v[176:179], v[120:123]
	v_mfma_f32_16x16x32_bf16 v[108:111], v[144:147], v[200:203], v[108:111]
	v_mfma_f32_16x16x32_bf16 v[104:107], v[152:155], v[200:203], v[104:107]
	v_mfma_f32_16x16x32_bf16 v[92:95], v[144:147], v[208:211], v[92:95]
	v_mfma_f32_16x16x32_bf16 v[88:91], v[152:155], v[208:211], v[88:91]
	v_mfma_f32_16x16x32_bf16 v[76:79], v[144:147], v[216:219], v[76:79]
	v_mfma_f32_16x16x32_bf16 v[72:75], v[152:155], v[216:219], v[72:75]
	v_mfma_f32_16x16x32_bf16 v[116:119], v[156:159], v[172:175], v[116:119]
	v_mfma_f32_16x16x32_bf16 v[112:115], v[164:167], v[172:175], v[112:115]
	v_mfma_f32_16x16x32_bf16 v[100:103], v[156:159], v[180:183], v[100:103]
	v_mfma_f32_16x16x32_bf16 v[96:99], v[164:167], v[180:183], v[96:99]
	v_mfma_f32_16x16x32_bf16 v[84:87], v[156:159], v[204:207], v[84:87]
	v_mfma_f32_16x16x32_bf16 v[80:83], v[164:167], v[204:207], v[80:83]
	v_mfma_f32_16x16x32_bf16 v[68:71], v[156:159], v[212:215], v[68:71]
	v_mfma_f32_16x16x32_bf16 v[64:67], v[164:167], v[212:215], v[64:67]
	v_mfma_f32_16x16x32_bf16 v[116:119], v[160:163], v[176:179], v[116:119]
	v_mfma_f32_16x16x32_bf16 v[112:115], v[168:171], v[176:179], v[112:115]
	v_mfma_f32_16x16x32_bf16 v[100:103], v[160:163], v[200:203], v[100:103]
	v_mfma_f32_16x16x32_bf16 v[96:99], v[168:171], v[200:203], v[96:99]
	v_mfma_f32_16x16x32_bf16 v[84:87], v[160:163], v[208:211], v[84:87]
	v_mfma_f32_16x16x32_bf16 v[80:83], v[168:171], v[208:211], v[80:83]
	v_mfma_f32_16x16x32_bf16 v[68:71], v[160:163], v[216:219], v[68:71]
	v_mfma_f32_16x16x32_bf16 v[64:67], v[168:171], v[216:219], v[64:67]
	s_barrier
	v_lshl_add_u64 v[136:137], s[82:83], 0, v[184:185]
	s_add_i32 s82, vcc_lo, s50
	s_mov_b32 m0, s82
	ds_read_b128 v[172:175], v142 offset:16384
	ds_read_b128 v[176:179], v142 offset:17408
	ds_read_b128 v[180:183], v142 offset:18432
	ds_read_b128 v[200:203], v142 offset:19456
	ds_read_b128 v[204:207], v142 offset:20480
	ds_read_b128 v[208:211], v142 offset:21504
	ds_read_b128 v[212:215], v142 offset:22528
	ds_read_b128 v[216:219], v142 offset:23552
	global_load_lds_dwordx4 v[136:137], off
	v_lshl_add_u64 v[220:221], v[136:137], 0, s[84:85]
	s_add_i32 m0, s82, 0x2000
	s_add_i32 s82, vcc_hi, s50
	global_load_lds_dwordx4 v[220:221], off
	v_lshl_add_u64 v[220:221], v[136:137], 0, s[86:87]
	s_mov_b32 m0, s82
	s_nop 0
	global_load_lds_dwordx4 v[220:221], off
	v_lshl_add_u64 v[220:221], v[136:137], 0, s[88:89]
	s_add_i32 m0, s82, 0x2000
	s_nop 0
	global_load_lds_dwordx4 v[220:221], off
	v_lshl_add_u64 v[220:221], s[2:3], 0, v[128:129]
	s_mov_b32 m0, s51
	v_lshl_add_u64 v[222:223], v[220:221], 0, s[84:85]
	global_load_lds_dwordx4 v[220:221], off
	s_mov_b32 m0, s66
	s_nop 0
	global_load_lds_dwordx4 v[222:223], off
	s_waitcnt vmcnt(8)
	s_waitcnt lgkmcnt(0)
	s_barrier
	s_waitcnt lgkmcnt(0)
	v_mfma_f32_16x16x32_bf16 v[60:63], v[132:135], v[172:175], v[60:63]
	v_mfma_f32_16x16x32_bf16 v[56:59], v[148:151], v[172:175], v[56:59]
	v_mfma_f32_16x16x32_bf16 v[44:47], v[132:135], v[180:183], v[44:47]
	v_mfma_f32_16x16x32_bf16 v[40:43], v[148:151], v[180:183], v[40:43]
	v_mfma_f32_16x16x32_bf16 v[28:31], v[132:135], v[204:207], v[28:31]
	v_mfma_f32_16x16x32_bf16 v[24:27], v[148:151], v[204:207], v[24:27]
	v_mfma_f32_16x16x32_bf16 v[12:15], v[132:135], v[212:215], v[12:15]
	v_mfma_f32_16x16x32_bf16 v[8:11], v[148:151], v[212:215], v[8:11]
	v_mfma_f32_16x16x32_bf16 v[60:63], v[144:147], v[176:179], v[60:63]
	v_mfma_f32_16x16x32_bf16 v[56:59], v[152:155], v[176:179], v[56:59]
	v_mfma_f32_16x16x32_bf16 v[44:47], v[144:147], v[200:203], v[44:47]
	v_mfma_f32_16x16x32_bf16 v[40:43], v[152:155], v[200:203], v[40:43]
	v_mfma_f32_16x16x32_bf16 v[28:31], v[144:147], v[208:211], v[28:31]
	v_mfma_f32_16x16x32_bf16 v[24:27], v[152:155], v[208:211], v[24:27]
	v_mfma_f32_16x16x32_bf16 v[12:15], v[144:147], v[216:219], v[12:15]
	v_mfma_f32_16x16x32_bf16 v[8:11], v[152:155], v[216:219], v[8:11]
	v_mfma_f32_16x16x32_bf16 v[52:55], v[156:159], v[172:175], v[52:55]
	v_mfma_f32_16x16x32_bf16 v[48:51], v[164:167], v[172:175], v[48:51]
	v_mfma_f32_16x16x32_bf16 v[36:39], v[156:159], v[180:183], v[36:39]
	v_mfma_f32_16x16x32_bf16 v[32:35], v[164:167], v[180:183], v[32:35]
	v_mfma_f32_16x16x32_bf16 v[20:23], v[156:159], v[204:207], v[20:23]
	v_mfma_f32_16x16x32_bf16 v[16:19], v[164:167], v[204:207], v[16:19]
	v_mfma_f32_16x16x32_bf16 v[4:7], v[156:159], v[212:215], v[4:7]
	v_mfma_f32_16x16x32_bf16 v[0:3], v[164:167], v[212:215], v[0:3]
	v_mfma_f32_16x16x32_bf16 v[52:55], v[160:163], v[176:179], v[52:55]
	v_mfma_f32_16x16x32_bf16 v[48:51], v[168:171], v[176:179], v[48:51]
	v_mfma_f32_16x16x32_bf16 v[36:39], v[160:163], v[200:203], v[36:39]
	v_mfma_f32_16x16x32_bf16 v[32:35], v[168:171], v[200:203], v[32:35]
	v_mfma_f32_16x16x32_bf16 v[20:23], v[160:163], v[208:211], v[20:23]
	v_mfma_f32_16x16x32_bf16 v[16:19], v[168:171], v[208:211], v[16:19]
	v_mfma_f32_16x16x32_bf16 v[4:7], v[160:163], v[216:219], v[4:7]
	v_mfma_f32_16x16x32_bf16 v[0:3], v[168:171], v[216:219], v[0:3]
	s_barrier
	s_add_i32 s2, 0, 0x18000
	v_add_u32_e32 v143, s2, v140
	s_add_i32 s3, 0, 0x1c000
	ds_read_b128 v[132:135], v143
	ds_read_b128 v[144:147], v143 offset:1024
	ds_read_b128 v[148:151], v143 offset:2048
	ds_read_b128 v[152:155], v143 offset:3072
	v_add_u32_e32 v143, s3, v140
	ds_read_b128 v[156:159], v143
	ds_read_b128 v[160:163], v143 offset:1024
	ds_read_b128 v[164:167], v143 offset:2048
	ds_read_b128 v[168:171], v143 offset:3072
	s_mov_b32 m0, s67
	v_lshl_add_u64 v[222:223], v[220:221], 0, s[86:87]
	ds_read_b128 v[172:175], v142 offset:32768
	ds_read_b128 v[176:179], v142 offset:33792
	ds_read_b128 v[180:183], v142 offset:34816
	ds_read_b128 v[200:203], v142 offset:35840
	ds_read_b128 v[204:207], v142 offset:36864
	ds_read_b128 v[208:211], v142 offset:37888
	ds_read_b128 v[212:215], v142 offset:38912
	ds_read_b128 v[216:219], v142 offset:39936
	global_load_lds_dwordx4 v[222:223], off
	v_lshl_add_u64 v[222:223], v[220:221], 0, s[88:89]
	s_mov_b32 m0, s76
	s_nop 0
	global_load_lds_dwordx4 v[222:223], off
	s_waitcnt vmcnt(8)
	s_waitcnt lgkmcnt(0)
	s_barrier
	s_waitcnt lgkmcnt(0)
	v_mfma_f32_16x16x32_bf16 v[124:127], v[132:135], v[172:175], v[124:127]
	v_mfma_f32_16x16x32_bf16 v[120:123], v[148:151], v[172:175], v[120:123]
	v_mfma_f32_16x16x32_bf16 v[108:111], v[132:135], v[180:183], v[108:111]
	v_mfma_f32_16x16x32_bf16 v[104:107], v[148:151], v[180:183], v[104:107]
	v_mfma_f32_16x16x32_bf16 v[92:95], v[132:135], v[204:207], v[92:95]
	v_mfma_f32_16x16x32_bf16 v[88:91], v[148:151], v[204:207], v[88:91]
	v_mfma_f32_16x16x32_bf16 v[76:79], v[132:135], v[212:215], v[76:79]
	v_mfma_f32_16x16x32_bf16 v[72:75], v[148:151], v[212:215], v[72:75]
	v_mfma_f32_16x16x32_bf16 v[124:127], v[144:147], v[176:179], v[124:127]
	v_mfma_f32_16x16x32_bf16 v[120:123], v[152:155], v[176:179], v[120:123]
	v_mfma_f32_16x16x32_bf16 v[108:111], v[144:147], v[200:203], v[108:111]
	v_mfma_f32_16x16x32_bf16 v[104:107], v[152:155], v[200:203], v[104:107]
	v_mfma_f32_16x16x32_bf16 v[92:95], v[144:147], v[208:211], v[92:95]
	v_mfma_f32_16x16x32_bf16 v[88:91], v[152:155], v[208:211], v[88:91]
	v_mfma_f32_16x16x32_bf16 v[76:79], v[144:147], v[216:219], v[76:79]
	v_mfma_f32_16x16x32_bf16 v[72:75], v[152:155], v[216:219], v[72:75]
	v_mfma_f32_16x16x32_bf16 v[116:119], v[156:159], v[172:175], v[116:119]
	v_mfma_f32_16x16x32_bf16 v[112:115], v[164:167], v[172:175], v[112:115]
	v_mfma_f32_16x16x32_bf16 v[100:103], v[156:159], v[180:183], v[100:103]
	v_mfma_f32_16x16x32_bf16 v[96:99], v[164:167], v[180:183], v[96:99]
	v_mfma_f32_16x16x32_bf16 v[84:87], v[156:159], v[204:207], v[84:87]
	v_mfma_f32_16x16x32_bf16 v[80:83], v[164:167], v[204:207], v[80:83]
	v_mfma_f32_16x16x32_bf16 v[68:71], v[156:159], v[212:215], v[68:71]
	v_mfma_f32_16x16x32_bf16 v[64:67], v[164:167], v[212:215], v[64:67]
	v_mfma_f32_16x16x32_bf16 v[116:119], v[160:163], v[176:179], v[116:119]
	v_mfma_f32_16x16x32_bf16 v[112:115], v[168:171], v[176:179], v[112:115]
	v_mfma_f32_16x16x32_bf16 v[100:103], v[160:163], v[200:203], v[100:103]
	v_mfma_f32_16x16x32_bf16 v[96:99], v[168:171], v[200:203], v[96:99]
	v_mfma_f32_16x16x32_bf16 v[84:87], v[160:163], v[208:211], v[84:87]
	v_mfma_f32_16x16x32_bf16 v[80:83], v[168:171], v[208:211], v[80:83]
	v_mfma_f32_16x16x32_bf16 v[68:71], v[160:163], v[216:219], v[68:71]
	v_mfma_f32_16x16x32_bf16 v[64:67], v[168:171], v[216:219], v[64:67]
	s_barrier
	s_add_i32 s2, s2, s50
	v_lshl_add_u64 v[222:223], v[136:137], 0, s[90:91]
	s_mov_b32 m0, s2
	ds_read_b128 v[172:175], v142 offset:49152
	ds_read_b128 v[176:179], v142 offset:50176
	ds_read_b128 v[180:183], v142 offset:51200
	ds_read_b128 v[200:203], v142 offset:52224
	ds_read_b128 v[204:207], v142 offset:53248
	ds_read_b128 v[208:211], v142 offset:54272
	ds_read_b128 v[212:215], v142 offset:55296
	ds_read_b128 v[216:219], v142 offset:56320
	global_load_lds_dwordx4 v[222:223], off
	v_lshl_add_u64 v[222:223], v[136:137], 0, s[92:93]
	s_add_i32 m0, s2, 0x2000
	s_add_i32 s2, s3, s50
	global_load_lds_dwordx4 v[222:223], off
	v_lshl_add_u64 v[222:223], v[136:137], 0, s[94:95]
	s_mov_b32 m0, s2
	v_lshl_add_u64 v[136:137], v[136:137], 0, s[96:97]
	global_load_lds_dwordx4 v[222:223], off
	s_add_i32 m0, s2, 0x2000
	s_nop 0
	global_load_lds_dwordx4 v[136:137], off
	v_lshl_add_u64 v[136:137], v[220:221], 0, s[90:91]
	s_mov_b32 m0, s77
	s_nop 0
	global_load_lds_dwordx4 v[136:137], off
	v_lshl_add_u64 v[136:137], v[220:221], 0, s[92:93]
	s_mov_b32 m0, s78
	s_nop 0
	global_load_lds_dwordx4 v[136:137], off
	s_waitcnt vmcnt(8)
	s_waitcnt lgkmcnt(0)
	s_barrier
	s_waitcnt lgkmcnt(0)
	v_mfma_f32_16x16x32_bf16 v[60:63], v[132:135], v[172:175], v[60:63]
	v_mfma_f32_16x16x32_bf16 v[56:59], v[148:151], v[172:175], v[56:59]
	v_mfma_f32_16x16x32_bf16 v[44:47], v[132:135], v[180:183], v[44:47]
	v_mfma_f32_16x16x32_bf16 v[40:43], v[148:151], v[180:183], v[40:43]
	v_mfma_f32_16x16x32_bf16 v[28:31], v[132:135], v[204:207], v[28:31]
	v_mfma_f32_16x16x32_bf16 v[24:27], v[148:151], v[204:207], v[24:27]
	v_mfma_f32_16x16x32_bf16 v[12:15], v[132:135], v[212:215], v[12:15]
	v_mfma_f32_16x16x32_bf16 v[8:11], v[148:151], v[212:215], v[8:11]
	v_mfma_f32_16x16x32_bf16 v[60:63], v[144:147], v[176:179], v[60:63]
	v_mfma_f32_16x16x32_bf16 v[56:59], v[152:155], v[176:179], v[56:59]
	v_mfma_f32_16x16x32_bf16 v[44:47], v[144:147], v[200:203], v[44:47]
	v_mfma_f32_16x16x32_bf16 v[40:43], v[152:155], v[200:203], v[40:43]
	v_mfma_f32_16x16x32_bf16 v[28:31], v[144:147], v[208:211], v[28:31]
	v_mfma_f32_16x16x32_bf16 v[24:27], v[152:155], v[208:211], v[24:27]
	v_mfma_f32_16x16x32_bf16 v[12:15], v[144:147], v[216:219], v[12:15]
	v_mfma_f32_16x16x32_bf16 v[8:11], v[152:155], v[216:219], v[8:11]
	v_mfma_f32_16x16x32_bf16 v[52:55], v[156:159], v[172:175], v[52:55]
	v_mfma_f32_16x16x32_bf16 v[48:51], v[164:167], v[172:175], v[48:51]
	v_mfma_f32_16x16x32_bf16 v[36:39], v[156:159], v[180:183], v[36:39]
	v_mfma_f32_16x16x32_bf16 v[32:35], v[164:167], v[180:183], v[32:35]
	v_mfma_f32_16x16x32_bf16 v[20:23], v[156:159], v[204:207], v[20:23]
	v_mfma_f32_16x16x32_bf16 v[16:19], v[164:167], v[204:207], v[16:19]
	v_mfma_f32_16x16x32_bf16 v[4:7], v[156:159], v[212:215], v[4:7]
	v_mfma_f32_16x16x32_bf16 v[0:3], v[164:167], v[212:215], v[0:3]
	v_mfma_f32_16x16x32_bf16 v[52:55], v[160:163], v[176:179], v[52:55]
	v_mfma_f32_16x16x32_bf16 v[48:51], v[168:171], v[176:179], v[48:51]
	v_mfma_f32_16x16x32_bf16 v[36:39], v[160:163], v[200:203], v[36:39]
	v_mfma_f32_16x16x32_bf16 v[32:35], v[168:171], v[200:203], v[32:35]
	v_mfma_f32_16x16x32_bf16 v[20:23], v[160:163], v[208:211], v[20:23]
	v_mfma_f32_16x16x32_bf16 v[16:19], v[168:171], v[208:211], v[16:19]
	v_mfma_f32_16x16x32_bf16 v[4:7], v[160:163], v[216:219], v[4:7]
	v_mfma_f32_16x16x32_bf16 v[0:3], v[168:171], v[216:219], v[0:3]
	s_barrier
	s_add_i32 s81, s81, 2
	s_add_u32 s54, s54, 0x100
	s_addc_u32 s55, s55, 0
	s_add_u32 s49, s49, 0x100
	s_addc_u32 s80, s80, 0
	s_cmp_gt_u32 s81, 13
	s_cbranch_scc0 .LBB0_1916
	s_and_b64 vcc, exec, s[18:19]
	s_cbranch_vccz .LBB0_1919
	s_barrier
.LBB0_1919:
	v_lshl_add_u32 v132, s48, 8, v139
	v_ashrrev_i32_e32 v133, 31, v132
	v_lshl_add_u64 v[134:135], v[132:133], 2, s[16:17]
	global_load_dword v160, v[134:135], off
	global_load_dword v161, v[134:135], off offset:64
	global_load_dword v162, v[134:135], off offset:128
	global_load_dword v163, v[134:135], off offset:192
	global_load_dword v164, v[134:135], off offset:512
	global_load_dword v165, v[134:135], off offset:576
	global_load_dword v166, v[134:135], off offset:640
	global_load_dword v167, v[134:135], off offset:704
	s_mov_b32 s2, 0x800000
	v_lshl_or_b32 v136, s33, 7, v141
	v_ashrrev_i32_e32 v137, 31, v136
	s_movk_i32 s3, 0x1600
	s_mov_b64 s[54:55], -1
	s_mov_b64 s[80:81], 0x1000
	s_waitcnt vmcnt(0)
	v_fmamk_f32 v133, v160, 0x3a800000, v227
	v_cmp_gt_f32_e32 vcc, s2, v133
	v_mul_f32_e32 v143, 0x4b800000, v133
	s_nop 0
	v_cndmask_b32_e32 v133, v133, v143, vcc
	v_rsq_f32_e32 v133, v133
	s_nop 0
	v_mul_f32_e32 v143, 0x45800000, v133
	v_cndmask_b32_e32 v144, v133, v143, vcc
	v_pk_mul_f32 v[124:125], v[124:125], v[144:145] op_sel_hi:[1,0]
	v_pk_mul_f32 v[116:117], v[116:117], v[144:145] op_sel_hi:[1,0]
	v_mul_f32_e32 v133, 0xbfb8aa3b, v124
	v_exp_f32_e32 v133, v133
	v_pk_mul_f32 v[118:119], v[118:119], v[144:145] op_sel_hi:[1,0]
	v_pk_mul_f32 v[120:121], v[120:121], v[144:145] op_sel_hi:[1,0]
	v_pk_mul_f32 v[112:113], v[112:113], v[144:145] op_sel_hi:[1,0]
	v_add_f32_e32 v133, 1.0, v133
	v_rcp_f32_e32 v146, v133
	v_mul_f32_e32 v133, 0xbfb8aa3b, v125
	v_exp_f32_e32 v133, v133
	v_pk_mul_f32 v[114:115], v[114:115], v[144:145] op_sel_hi:[1,0]
	v_add_f32_e32 v133, 1.0, v133
	v_rcp_f32_e32 v147, v133
	s_nop 0
	v_pk_mul_f32 v[124:125], v[124:125], v[146:147]
	s_nop 0
	v_pk_mul_f32 v[116:117], v[116:117], v[124:125]
	v_pk_mul_f32 v[124:125], v[126:127], v[144:145] op_sel_hi:[1,0]
	v_cvt_pk_bf16_f32 v116, v116, v117
	v_mul_f32_e32 v126, 0xbfb8aa3b, v124
	v_mul_f32_e32 v127, 0xbfb8aa3b, v125
	v_exp_f32_e32 v126, v126
	v_exp_f32_e32 v127, v127
	v_add_f32_e32 v126, 1.0, v126
	v_add_f32_e32 v127, 1.0, v127
	v_rcp_f32_e32 v126, v126
	v_rcp_f32_e32 v127, v127
	s_nop 0
	v_pk_mul_f32 v[124:125], v[124:125], v[126:127]
	s_nop 0
	v_pk_mul_f32 v[118:119], v[118:119], v[124:125]
	v_mul_f32_e32 v124, 0xbfb8aa3b, v120
	v_mul_f32_e32 v125, 0xbfb8aa3b, v121
	v_exp_f32_e32 v124, v124
	v_exp_f32_e32 v125, v125
	v_cvt_pk_bf16_f32 v117, v118, v119
	v_add_f32_e32 v124, 1.0, v124
	v_add_f32_e32 v125, 1.0, v125
	v_rcp_f32_e32 v124, v124
	v_rcp_f32_e32 v125, v125
	s_nop 0
	v_pk_mul_f32 v[120:121], v[120:121], v[124:125]
	s_nop 0
	v_pk_mul_f32 v[120:121], v[112:113], v[120:121]
	v_pk_mul_f32 v[112:113], v[122:123], v[144:145] op_sel_hi:[1,0]
	v_cvt_pk_bf16_f32 v118, v120, v121
	v_mul_f32_e32 v122, 0xbfb8aa3b, v112
	v_mul_f32_e32 v123, 0xbfb8aa3b, v113
	v_exp_f32_e32 v122, v122
	v_exp_f32_e32 v123, v123
	v_add_f32_e32 v122, 1.0, v122
	v_add_f32_e32 v123, 1.0, v123
	v_rcp_f32_e32 v122, v122
	v_rcp_f32_e32 v123, v123
	s_nop 0
	v_pk_mul_f32 v[112:113], v[112:113], v[122:123]
	s_nop 0
	v_pk_mul_f32 v[122:123], v[114:115], v[112:113]
	v_mov_b64_e32 v[112:113], s[10:11]
	v_mad_i64_i32 v[124:125], s[0:1], v132, s3, v[112:113]
	v_lshlrev_b64 v[114:115], 1, v[136:137]
	v_lshl_add_u64 v[124:125], v[124:125], 0, v[114:115]
	v_cvt_pk_bf16_f32 v119, v122, v123
	global_store_dwordx4 v[124:125], v[116:119], off nt
	s_nop 1
	v_or_b32_e32 v116, 16, v132
	v_ashrrev_i32_e32 v117, 31, v116
	v_lshl_add_u64 v[118:119], v[116:117], 2, s[16:17]
	v_fmamk_f32 v117, v161, 0x3a800000, v227
	v_cmp_gt_f32_e32 vcc, s2, v117
	v_mul_f32_e32 v118, 0x4b800000, v117
	s_nop 0
	v_cndmask_b32_e32 v117, v117, v118, vcc
	v_rsq_f32_e32 v117, v117
	s_nop 0
	v_mul_f32_e32 v118, 0x45800000, v117
	v_cndmask_b32_e32 v118, v117, v118, vcc
	v_pk_mul_f32 v[108:109], v[108:109], v[118:119] op_sel_hi:[1,0]
	v_pk_mul_f32 v[100:101], v[100:101], v[118:119] op_sel_hi:[1,0]
	v_mul_f32_e32 v117, 0xbfb8aa3b, v108
	v_exp_f32_e32 v117, v117
	v_pk_mul_f32 v[102:103], v[102:103], v[118:119] op_sel_hi:[1,0]
	v_pk_mul_f32 v[104:105], v[104:105], v[118:119] op_sel_hi:[1,0]
	v_pk_mul_f32 v[96:97], v[96:97], v[118:119] op_sel_hi:[1,0]
	v_add_f32_e32 v117, 1.0, v117
	v_rcp_f32_e32 v120, v117
	v_mul_f32_e32 v117, 0xbfb8aa3b, v109
	v_exp_f32_e32 v117, v117
	v_pk_mul_f32 v[98:99], v[98:99], v[118:119] op_sel_hi:[1,0]
	v_add_f32_e32 v117, 1.0, v117
	v_rcp_f32_e32 v121, v117
	s_nop 0
	v_pk_mul_f32 v[108:109], v[108:109], v[120:121]
	s_nop 0
	v_pk_mul_f32 v[100:101], v[100:101], v[108:109]
	v_pk_mul_f32 v[108:109], v[110:111], v[118:119] op_sel_hi:[1,0]
	s_nop 0
	v_mul_f32_e32 v110, 0xbfb8aa3b, v108
	v_mul_f32_e32 v111, 0xbfb8aa3b, v109
	v_exp_f32_e32 v110, v110
	v_exp_f32_e32 v111, v111
	v_add_f32_e32 v110, 1.0, v110
	v_add_f32_e32 v111, 1.0, v111
	v_rcp_f32_e32 v110, v110
	v_rcp_f32_e32 v111, v111
	s_nop 0
	v_pk_mul_f32 v[108:109], v[108:109], v[110:111]
	s_nop 0
	v_pk_mul_f32 v[102:103], v[102:103], v[108:109]
	v_mul_f32_e32 v108, 0xbfb8aa3b, v104
	v_mul_f32_e32 v109, 0xbfb8aa3b, v105
	v_exp_f32_e32 v108, v108
	v_exp_f32_e32 v109, v109
	v_add_f32_e32 v108, 1.0, v108
	v_add_f32_e32 v109, 1.0, v109
	v_rcp_f32_e32 v108, v108
	v_rcp_f32_e32 v109, v109
	s_nop 0
	v_pk_mul_f32 v[104:105], v[104:105], v[108:109]
	s_nop 0
	v_pk_mul_f32 v[104:105], v[96:97], v[104:105]
	v_pk_mul_f32 v[96:97], v[106:107], v[118:119] op_sel_hi:[1,0]
	s_nop 0
	v_mul_f32_e32 v106, 0xbfb8aa3b, v96
	v_mul_f32_e32 v107, 0xbfb8aa3b, v97
	v_exp_f32_e32 v106, v106
	v_exp_f32_e32 v107, v107
	v_add_f32_e32 v106, 1.0, v106
	v_add_f32_e32 v107, 1.0, v107
	v_rcp_f32_e32 v106, v106
	v_rcp_f32_e32 v107, v107
	s_nop 0
	v_pk_mul_f32 v[96:97], v[96:97], v[106:107]
	s_nop 0
	v_pk_mul_f32 v[106:107], v[98:99], v[96:97]
	v_mad_i64_i32 v[96:97], s[0:1], v116, s3, v[112:113]
	v_lshl_add_u64 v[108:109], v[96:97], 0, v[114:115]
	v_cvt_pk_bf16_f32 v96, v100, v101
	v_cvt_pk_bf16_f32 v97, v102, v103
	v_cvt_pk_bf16_f32 v98, v104, v105
	v_cvt_pk_bf16_f32 v99, v106, v107
	global_store_dwordx4 v[108:109], v[96:99], off nt
	s_nop 1
	v_or_b32_e32 v96, 32, v132
	v_ashrrev_i32_e32 v97, 31, v96
	v_lshl_add_u64 v[98:99], v[96:97], 2, s[16:17]
	v_fmamk_f32 v97, v162, 0x3a800000, v227
	v_cmp_gt_f32_e32 vcc, s2, v97
	v_mul_f32_e32 v98, 0x4b800000, v97
	s_nop 0
	v_cndmask_b32_e32 v97, v97, v98, vcc
	v_rsq_f32_e32 v97, v97
	s_nop 0
	v_mul_f32_e32 v98, 0x45800000, v97
	v_cndmask_b32_e32 v98, v97, v98, vcc
	v_pk_mul_f32 v[92:93], v[92:93], v[98:99] op_sel_hi:[1,0]
	v_pk_mul_f32 v[84:85], v[84:85], v[98:99] op_sel_hi:[1,0]
	v_mul_f32_e32 v97, 0xbfb8aa3b, v92
	v_exp_f32_e32 v97, v97
	v_pk_mul_f32 v[86:87], v[86:87], v[98:99] op_sel_hi:[1,0]
	v_pk_mul_f32 v[88:89], v[88:89], v[98:99] op_sel_hi:[1,0]
	v_pk_mul_f32 v[80:81], v[80:81], v[98:99] op_sel_hi:[1,0]
	v_add_f32_e32 v97, 1.0, v97
	v_rcp_f32_e32 v100, v97
	v_mul_f32_e32 v97, 0xbfb8aa3b, v93
	v_exp_f32_e32 v97, v97
	v_pk_mul_f32 v[82:83], v[82:83], v[98:99] op_sel_hi:[1,0]
	v_add_f32_e32 v97, 1.0, v97
	v_rcp_f32_e32 v101, v97
	s_nop 0
	v_pk_mul_f32 v[92:93], v[92:93], v[100:101]
	s_nop 0
	v_pk_mul_f32 v[84:85], v[84:85], v[92:93]
	v_pk_mul_f32 v[92:93], v[94:95], v[98:99] op_sel_hi:[1,0]
	s_nop 0
	v_mul_f32_e32 v94, 0xbfb8aa3b, v92
	v_mul_f32_e32 v95, 0xbfb8aa3b, v93
	v_exp_f32_e32 v94, v94
	v_exp_f32_e32 v95, v95
	v_add_f32_e32 v94, 1.0, v94
	v_add_f32_e32 v95, 1.0, v95
	v_rcp_f32_e32 v94, v94
	v_rcp_f32_e32 v95, v95
	s_nop 0
	v_pk_mul_f32 v[92:93], v[92:93], v[94:95]
	s_nop 0
	v_pk_mul_f32 v[86:87], v[86:87], v[92:93]
	v_mul_f32_e32 v92, 0xbfb8aa3b, v88
	v_mul_f32_e32 v93, 0xbfb8aa3b, v89
	v_exp_f32_e32 v92, v92
	v_exp_f32_e32 v93, v93
	v_add_f32_e32 v92, 1.0, v92
	v_add_f32_e32 v93, 1.0, v93
	v_rcp_f32_e32 v92, v92
	v_rcp_f32_e32 v93, v93
	s_nop 0
	v_pk_mul_f32 v[88:89], v[88:89], v[92:93]
	s_nop 0
	v_pk_mul_f32 v[88:89], v[80:81], v[88:89]
	v_pk_mul_f32 v[80:81], v[90:91], v[98:99] op_sel_hi:[1,0]
	s_nop 0
	v_mul_f32_e32 v90, 0xbfb8aa3b, v80
	v_mul_f32_e32 v91, 0xbfb8aa3b, v81
	v_exp_f32_e32 v90, v90
	v_exp_f32_e32 v91, v91
	v_add_f32_e32 v90, 1.0, v90
	v_add_f32_e32 v91, 1.0, v91
	v_rcp_f32_e32 v90, v90
	v_rcp_f32_e32 v91, v91
	s_nop 0
	v_pk_mul_f32 v[80:81], v[80:81], v[90:91]
	s_nop 0
	v_pk_mul_f32 v[90:91], v[82:83], v[80:81]
	v_mad_i64_i32 v[80:81], s[0:1], v96, s3, v[112:113]
	v_lshl_add_u64 v[92:93], v[80:81], 0, v[114:115]
	v_cvt_pk_bf16_f32 v80, v84, v85
	v_cvt_pk_bf16_f32 v81, v86, v87
	v_cvt_pk_bf16_f32 v82, v88, v89
	v_cvt_pk_bf16_f32 v83, v90, v91
	global_store_dwordx4 v[92:93], v[80:83], off nt
	s_nop 1
	v_or_b32_e32 v80, 48, v132
	v_ashrrev_i32_e32 v81, 31, v80
	v_lshl_add_u64 v[82:83], v[80:81], 2, s[16:17]
	v_fmamk_f32 v81, v163, 0x3a800000, v227
	v_cmp_gt_f32_e32 vcc, s2, v81
	v_mul_f32_e32 v82, 0x4b800000, v81
	s_nop 0
	v_cndmask_b32_e32 v81, v81, v82, vcc
	v_rsq_f32_e32 v81, v81
	s_nop 0
	v_mul_f32_e32 v82, 0x45800000, v81
	v_cndmask_b32_e32 v82, v81, v82, vcc
	v_pk_mul_f32 v[76:77], v[76:77], v[82:83] op_sel_hi:[1,0]
	v_pk_mul_f32 v[68:69], v[68:69], v[82:83] op_sel_hi:[1,0]
	v_mul_f32_e32 v81, 0xbfb8aa3b, v76
	v_exp_f32_e32 v81, v81
	v_pk_mul_f32 v[70:71], v[70:71], v[82:83] op_sel_hi:[1,0]
	v_pk_mul_f32 v[72:73], v[72:73], v[82:83] op_sel_hi:[1,0]
	v_pk_mul_f32 v[64:65], v[64:65], v[82:83] op_sel_hi:[1,0]
	v_add_f32_e32 v81, 1.0, v81
	v_rcp_f32_e32 v84, v81
	v_mul_f32_e32 v81, 0xbfb8aa3b, v77
	v_exp_f32_e32 v81, v81
	v_pk_mul_f32 v[66:67], v[66:67], v[82:83] op_sel_hi:[1,0]
	v_add_f32_e32 v81, 1.0, v81
	v_rcp_f32_e32 v85, v81
	s_nop 0
	v_pk_mul_f32 v[76:77], v[76:77], v[84:85]
	s_nop 0
	v_pk_mul_f32 v[68:69], v[68:69], v[76:77]
	v_pk_mul_f32 v[76:77], v[78:79], v[82:83] op_sel_hi:[1,0]
	v_cvt_pk_bf16_f32 v68, v68, v69
	v_mul_f32_e32 v78, 0xbfb8aa3b, v76
	v_mul_f32_e32 v79, 0xbfb8aa3b, v77
	v_exp_f32_e32 v78, v78
	v_exp_f32_e32 v79, v79
	v_add_f32_e32 v78, 1.0, v78
	v_add_f32_e32 v79, 1.0, v79
	v_rcp_f32_e32 v78, v78
	v_rcp_f32_e32 v79, v79
	s_nop 0
	v_pk_mul_f32 v[76:77], v[76:77], v[78:79]
	s_nop 0
	v_pk_mul_f32 v[70:71], v[70:71], v[76:77]
	v_mul_f32_e32 v76, 0xbfb8aa3b, v72
	v_mul_f32_e32 v77, 0xbfb8aa3b, v73
	v_exp_f32_e32 v76, v76
	v_exp_f32_e32 v77, v77
	v_cvt_pk_bf16_f32 v69, v70, v71
	v_add_f32_e32 v76, 1.0, v76
	v_add_f32_e32 v77, 1.0, v77
	v_rcp_f32_e32 v76, v76
	v_rcp_f32_e32 v77, v77
	s_nop 0
	v_pk_mul_f32 v[72:73], v[72:73], v[76:77]
	s_nop 0
	v_pk_mul_f32 v[64:65], v[64:65], v[72:73]
	v_pk_mul_f32 v[72:73], v[74:75], v[82:83] op_sel_hi:[1,0]
	v_cvt_pk_bf16_f32 v70, v64, v65
	v_mul_f32_e32 v74, 0xbfb8aa3b, v72
	v_mul_f32_e32 v75, 0xbfb8aa3b, v73
	v_exp_f32_e32 v74, v74
	v_exp_f32_e32 v75, v75
	v_add_u32_e32 v65, 0x80, v132
	v_add_f32_e32 v74, 1.0, v74
	v_add_f32_e32 v75, 1.0, v75
	v_rcp_f32_e32 v74, v74
	v_rcp_f32_e32 v75, v75
	s_nop 0
	v_pk_mul_f32 v[72:73], v[72:73], v[74:75]
	s_nop 0
	v_pk_mul_f32 v[66:67], v[66:67], v[72:73]
	v_mad_i64_i32 v[72:73], s[0:1], v80, s3, v[112:113]
	v_lshl_add_u64 v[72:73], v[72:73], 0, v[114:115]
	v_cvt_pk_bf16_f32 v71, v66, v67
	global_store_dwordx4 v[72:73], v[68:71], off nt
	v_fmamk_f32 v64, v164, 0x3a800000, v227
	v_cmp_gt_f32_e32 vcc, s2, v64
	v_mul_f32_e32 v66, 0x4b800000, v64
	s_nop 0
	v_cndmask_b32_e32 v64, v64, v66, vcc
	v_rsq_f32_e32 v64, v64
	s_nop 0
	v_mul_f32_e32 v66, 0x45800000, v64
	v_cndmask_b32_e32 v64, v64, v66, vcc
	v_pk_mul_f32 v[60:61], v[60:61], v[64:65] op_sel_hi:[1,0]
	v_pk_mul_f32 v[52:53], v[52:53], v[64:65] op_sel_hi:[1,0]
	v_mul_f32_e32 v66, 0xbfb8aa3b, v60
	v_mul_f32_e32 v67, 0xbfb8aa3b, v61
	v_exp_f32_e32 v66, v66
	v_exp_f32_e32 v67, v67
	v_pk_mul_f32 v[54:55], v[54:55], v[64:65] op_sel_hi:[1,0]
	v_pk_mul_f32 v[56:57], v[56:57], v[64:65] op_sel_hi:[1,0]
	v_add_f32_e32 v66, 1.0, v66
	v_add_f32_e32 v67, 1.0, v67
	v_rcp_f32_e32 v66, v66
	v_rcp_f32_e32 v67, v67
	v_pk_mul_f32 v[48:49], v[48:49], v[64:65] op_sel_hi:[1,0]
	v_pk_mul_f32 v[50:51], v[50:51], v[64:65] op_sel_hi:[1,0]
	v_pk_mul_f32 v[60:61], v[60:61], v[66:67]
	s_nop 0
	v_pk_mul_f32 v[52:53], v[52:53], v[60:61]
	v_pk_mul_f32 v[60:61], v[62:63], v[64:65] op_sel_hi:[1,0]
	v_cvt_pk_bf16_f32 v52, v52, v53
	v_mul_f32_e32 v62, 0xbfb8aa3b, v60
	v_mul_f32_e32 v63, 0xbfb8aa3b, v61
	v_exp_f32_e32 v62, v62
	v_exp_f32_e32 v63, v63
	v_add_f32_e32 v62, 1.0, v62
	v_add_f32_e32 v63, 1.0, v63
	v_rcp_f32_e32 v62, v62
	v_rcp_f32_e32 v63, v63
	s_nop 0
	v_pk_mul_f32 v[60:61], v[60:61], v[62:63]
	s_nop 0
	v_pk_mul_f32 v[54:55], v[54:55], v[60:61]
	v_mul_f32_e32 v60, 0xbfb8aa3b, v56
	v_mul_f32_e32 v61, 0xbfb8aa3b, v57
	v_exp_f32_e32 v60, v60
	v_exp_f32_e32 v61, v61
	v_cvt_pk_bf16_f32 v53, v54, v55
	v_add_f32_e32 v60, 1.0, v60
	v_add_f32_e32 v61, 1.0, v61
	v_rcp_f32_e32 v60, v60
	v_rcp_f32_e32 v61, v61
	s_nop 0
	v_pk_mul_f32 v[56:57], v[56:57], v[60:61]
	s_nop 0
	v_pk_mul_f32 v[48:49], v[48:49], v[56:57]
	v_pk_mul_f32 v[56:57], v[58:59], v[64:65] op_sel_hi:[1,0]
	v_cvt_pk_bf16_f32 v54, v48, v49
	v_mul_f32_e32 v58, 0xbfb8aa3b, v56
	v_mul_f32_e32 v59, 0xbfb8aa3b, v57
	v_exp_f32_e32 v58, v58
	v_exp_f32_e32 v59, v59
	v_add_u32_e32 v49, 0x90, v132
	v_add_f32_e32 v58, 1.0, v58
	v_add_f32_e32 v59, 1.0, v59
	v_rcp_f32_e32 v58, v58
	v_rcp_f32_e32 v59, v59
	s_nop 0
	v_pk_mul_f32 v[56:57], v[56:57], v[58:59]
	s_nop 0
	v_pk_mul_f32 v[50:51], v[50:51], v[56:57]
	v_mad_i64_i32 v[56:57], s[0:1], v65, s3, v[112:113]
	v_lshl_add_u64 v[56:57], v[56:57], 0, v[114:115]
	v_cvt_pk_bf16_f32 v55, v50, v51
	global_store_dwordx4 v[56:57], v[52:55], off nt
	v_fmamk_f32 v48, v165, 0x3a800000, v227
	v_cmp_gt_f32_e32 vcc, s2, v48
	v_mul_f32_e32 v50, 0x4b800000, v48
	s_nop 0
	v_cndmask_b32_e32 v48, v48, v50, vcc
	v_rsq_f32_e32 v48, v48
	s_nop 0
	v_mul_f32_e32 v50, 0x45800000, v48
	v_cndmask_b32_e32 v48, v48, v50, vcc
	v_pk_mul_f32 v[44:45], v[44:45], v[48:49] op_sel_hi:[1,0]
	v_pk_mul_f32 v[36:37], v[36:37], v[48:49] op_sel_hi:[1,0]
	v_mul_f32_e32 v50, 0xbfb8aa3b, v44
	v_mul_f32_e32 v51, 0xbfb8aa3b, v45
	v_exp_f32_e32 v50, v50
	v_exp_f32_e32 v51, v51
	v_pk_mul_f32 v[38:39], v[38:39], v[48:49] op_sel_hi:[1,0]
	v_pk_mul_f32 v[40:41], v[40:41], v[48:49] op_sel_hi:[1,0]
	v_add_f32_e32 v50, 1.0, v50
	v_add_f32_e32 v51, 1.0, v51
	v_rcp_f32_e32 v50, v50
	v_rcp_f32_e32 v51, v51
	v_pk_mul_f32 v[32:33], v[32:33], v[48:49] op_sel_hi:[1,0]
	v_pk_mul_f32 v[34:35], v[34:35], v[48:49] op_sel_hi:[1,0]
	v_pk_mul_f32 v[44:45], v[44:45], v[50:51]
	s_nop 0
	v_pk_mul_f32 v[36:37], v[36:37], v[44:45]
	v_pk_mul_f32 v[44:45], v[46:47], v[48:49] op_sel_hi:[1,0]
	v_cvt_pk_bf16_f32 v36, v36, v37
	v_mul_f32_e32 v46, 0xbfb8aa3b, v44
	v_mul_f32_e32 v47, 0xbfb8aa3b, v45
	v_exp_f32_e32 v46, v46
	v_exp_f32_e32 v47, v47
	v_add_f32_e32 v46, 1.0, v46
	v_add_f32_e32 v47, 1.0, v47
	v_rcp_f32_e32 v46, v46
	v_rcp_f32_e32 v47, v47
	s_nop 0
	v_pk_mul_f32 v[44:45], v[44:45], v[46:47]
	s_nop 0
	v_pk_mul_f32 v[38:39], v[38:39], v[44:45]
	v_mul_f32_e32 v44, 0xbfb8aa3b, v40
	v_mul_f32_e32 v45, 0xbfb8aa3b, v41
	v_exp_f32_e32 v44, v44
	v_exp_f32_e32 v45, v45
	v_cvt_pk_bf16_f32 v37, v38, v39
	v_add_f32_e32 v44, 1.0, v44
	v_add_f32_e32 v45, 1.0, v45
	v_rcp_f32_e32 v44, v44
	v_rcp_f32_e32 v45, v45
	s_nop 0
	v_pk_mul_f32 v[40:41], v[40:41], v[44:45]
	s_nop 0
	v_pk_mul_f32 v[32:33], v[32:33], v[40:41]
	v_pk_mul_f32 v[40:41], v[42:43], v[48:49] op_sel_hi:[1,0]
	v_cvt_pk_bf16_f32 v38, v32, v33
	v_mul_f32_e32 v42, 0xbfb8aa3b, v40
	v_mul_f32_e32 v43, 0xbfb8aa3b, v41
	v_exp_f32_e32 v42, v42
	v_exp_f32_e32 v43, v43
	v_add_u32_e32 v33, 0xa0, v132
	v_add_f32_e32 v42, 1.0, v42
	v_add_f32_e32 v43, 1.0, v43
	v_rcp_f32_e32 v42, v42
	v_rcp_f32_e32 v43, v43
	s_nop 0
	v_pk_mul_f32 v[40:41], v[40:41], v[42:43]
	s_nop 0
	v_pk_mul_f32 v[34:35], v[34:35], v[40:41]
	v_mad_i64_i32 v[40:41], s[0:1], v49, s3, v[112:113]
	v_lshl_add_u64 v[40:41], v[40:41], 0, v[114:115]
	v_cvt_pk_bf16_f32 v39, v34, v35
	global_store_dwordx4 v[40:41], v[36:39], off nt
	v_fmamk_f32 v32, v166, 0x3a800000, v227
	v_cmp_gt_f32_e32 vcc, s2, v32
	v_mul_f32_e32 v34, 0x4b800000, v32
	s_nop 0
	v_cndmask_b32_e32 v32, v32, v34, vcc
	v_rsq_f32_e32 v32, v32
	s_nop 0
	v_mul_f32_e32 v34, 0x45800000, v32
	v_cndmask_b32_e32 v32, v32, v34, vcc
	v_pk_mul_f32 v[28:29], v[28:29], v[32:33] op_sel_hi:[1,0]
	v_pk_mul_f32 v[20:21], v[20:21], v[32:33] op_sel_hi:[1,0]
	v_mul_f32_e32 v34, 0xbfb8aa3b, v28
	v_mul_f32_e32 v35, 0xbfb8aa3b, v29
	v_exp_f32_e32 v34, v34
	v_exp_f32_e32 v35, v35
	v_pk_mul_f32 v[22:23], v[22:23], v[32:33] op_sel_hi:[1,0]
	v_pk_mul_f32 v[24:25], v[24:25], v[32:33] op_sel_hi:[1,0]
	v_add_f32_e32 v34, 1.0, v34
	v_add_f32_e32 v35, 1.0, v35
	v_rcp_f32_e32 v34, v34
	v_rcp_f32_e32 v35, v35
	v_pk_mul_f32 v[16:17], v[16:17], v[32:33] op_sel_hi:[1,0]
	v_pk_mul_f32 v[18:19], v[18:19], v[32:33] op_sel_hi:[1,0]
	v_pk_mul_f32 v[28:29], v[28:29], v[34:35]
	s_nop 0
	v_pk_mul_f32 v[20:21], v[20:21], v[28:29]
	v_pk_mul_f32 v[28:29], v[30:31], v[32:33] op_sel_hi:[1,0]
	v_cvt_pk_bf16_f32 v20, v20, v21
	v_mul_f32_e32 v30, 0xbfb8aa3b, v28
	v_mul_f32_e32 v31, 0xbfb8aa3b, v29
	v_exp_f32_e32 v30, v30
	v_exp_f32_e32 v31, v31
	v_add_f32_e32 v30, 1.0, v30
	v_add_f32_e32 v31, 1.0, v31
	v_rcp_f32_e32 v30, v30
	v_rcp_f32_e32 v31, v31
	s_nop 0
	v_pk_mul_f32 v[28:29], v[28:29], v[30:31]
	s_nop 0
	v_pk_mul_f32 v[22:23], v[22:23], v[28:29]
	v_mul_f32_e32 v28, 0xbfb8aa3b, v24
	v_mul_f32_e32 v29, 0xbfb8aa3b, v25
	v_exp_f32_e32 v28, v28
	v_exp_f32_e32 v29, v29
	v_cvt_pk_bf16_f32 v21, v22, v23
	v_add_f32_e32 v28, 1.0, v28
	v_add_f32_e32 v29, 1.0, v29
	v_rcp_f32_e32 v28, v28
	v_rcp_f32_e32 v29, v29
	s_nop 0
	v_pk_mul_f32 v[24:25], v[24:25], v[28:29]
	s_nop 0
	v_pk_mul_f32 v[16:17], v[16:17], v[24:25]
	v_pk_mul_f32 v[24:25], v[26:27], v[32:33] op_sel_hi:[1,0]
	v_cvt_pk_bf16_f32 v22, v16, v17
	v_mul_f32_e32 v26, 0xbfb8aa3b, v24
	v_mul_f32_e32 v27, 0xbfb8aa3b, v25
	v_exp_f32_e32 v26, v26
	v_exp_f32_e32 v27, v27
	v_add_u32_e32 v17, 0xb0, v132
	v_add_f32_e32 v26, 1.0, v26
	v_add_f32_e32 v27, 1.0, v27
	v_rcp_f32_e32 v26, v26
	v_rcp_f32_e32 v27, v27
	s_nop 0
	v_pk_mul_f32 v[24:25], v[24:25], v[26:27]
	s_nop 0
	v_pk_mul_f32 v[18:19], v[18:19], v[24:25]
	v_mad_i64_i32 v[24:25], s[0:1], v33, s3, v[112:113]
	v_lshl_add_u64 v[24:25], v[24:25], 0, v[114:115]
	v_cvt_pk_bf16_f32 v23, v18, v19
	global_store_dwordx4 v[24:25], v[20:23], off nt
	v_fmamk_f32 v16, v167, 0x3a800000, v227
	v_cmp_gt_f32_e32 vcc, s2, v16
	v_mul_f32_e32 v18, 0x4b800000, v16
	s_nop 0
	v_cndmask_b32_e32 v16, v16, v18, vcc
	v_rsq_f32_e32 v16, v16
	s_nop 0
	v_mul_f32_e32 v18, 0x45800000, v16
	v_cndmask_b32_e32 v16, v16, v18, vcc
	v_pk_mul_f32 v[12:13], v[12:13], v[16:17] op_sel_hi:[1,0]
	v_pk_mul_f32 v[4:5], v[4:5], v[16:17] op_sel_hi:[1,0]
	v_mul_f32_e32 v18, 0xbfb8aa3b, v12
	v_mul_f32_e32 v19, 0xbfb8aa3b, v13
	v_exp_f32_e32 v18, v18
	v_exp_f32_e32 v19, v19
	v_pk_mul_f32 v[6:7], v[6:7], v[16:17] op_sel_hi:[1,0]
	v_pk_mul_f32 v[8:9], v[8:9], v[16:17] op_sel_hi:[1,0]
	v_add_f32_e32 v18, 1.0, v18
	v_add_f32_e32 v19, 1.0, v19
	v_rcp_f32_e32 v18, v18
	v_rcp_f32_e32 v19, v19
	v_pk_mul_f32 v[0:1], v[0:1], v[16:17] op_sel_hi:[1,0]
	v_pk_mul_f32 v[2:3], v[2:3], v[16:17] op_sel_hi:[1,0]
	s_andn2_b64 vcc, exec, s[6:7]
	v_pk_mul_f32 v[12:13], v[12:13], v[18:19]
	s_nop 0
	v_pk_mul_f32 v[4:5], v[4:5], v[12:13]
	v_pk_mul_f32 v[12:13], v[14:15], v[16:17] op_sel_hi:[1,0]
	s_nop 0
	v_mul_f32_e32 v14, 0xbfb8aa3b, v12
	v_mul_f32_e32 v15, 0xbfb8aa3b, v13
	v_exp_f32_e32 v14, v14
	v_exp_f32_e32 v15, v15
	v_add_f32_e32 v14, 1.0, v14
	v_add_f32_e32 v15, 1.0, v15
	v_rcp_f32_e32 v14, v14
	v_rcp_f32_e32 v15, v15
	s_nop 0
	v_pk_mul_f32 v[12:13], v[12:13], v[14:15]
	s_nop 0
	v_pk_mul_f32 v[6:7], v[6:7], v[12:13]
	v_mul_f32_e32 v12, 0xbfb8aa3b, v8
	v_mul_f32_e32 v13, 0xbfb8aa3b, v9
	v_exp_f32_e32 v12, v12
	v_exp_f32_e32 v13, v13
	v_add_f32_e32 v12, 1.0, v12
	v_add_f32_e32 v13, 1.0, v13
	v_rcp_f32_e32 v12, v12
	v_rcp_f32_e32 v13, v13
	s_nop 0
	v_pk_mul_f32 v[8:9], v[8:9], v[12:13]
	s_nop 0
	v_pk_mul_f32 v[8:9], v[0:1], v[8:9]
	v_pk_mul_f32 v[0:1], v[10:11], v[16:17] op_sel_hi:[1,0]
	s_nop 0
	v_mul_f32_e32 v10, 0xbfb8aa3b, v0
	v_mul_f32_e32 v11, 0xbfb8aa3b, v1
	v_exp_f32_e32 v10, v10
	v_exp_f32_e32 v11, v11
	v_add_f32_e32 v10, 1.0, v10
	v_add_f32_e32 v11, 1.0, v11
	v_rcp_f32_e32 v10, v10
	v_rcp_f32_e32 v11, v11
	s_nop 0
	v_pk_mul_f32 v[0:1], v[0:1], v[10:11]
	s_nop 0
	v_pk_mul_f32 v[10:11], v[2:3], v[0:1]
	v_mad_i64_i32 v[0:1], s[0:1], v17, s3, v[112:113]
	v_lshl_add_u64 v[12:13], v[0:1], 0, v[114:115]
	v_cvt_pk_bf16_f32 v0, v4, v5
	v_cvt_pk_bf16_f32 v1, v6, v7
	v_cvt_pk_bf16_f32 v2, v8, v9
	v_cvt_pk_bf16_f32 v3, v10, v11
	global_store_dwordx4 v[12:13], v[0:3], off nt
	s_cbranch_vccnz .LBB0_1912
	s_andn2_b64 vcc, exec, s[8:9]
	s_cbranch_vccnz .LBB0_1911
	s_barrier
	s_branch .LBB0_1911

.LBB0_1997:
	s_add_u32 s2, s10, 0xfff50080
	s_addc_u32 s3, s11, -1
	s_add_i32 s0, 0, 0x10000
	s_cmp_eq_u32 s83, 40
	s_cselect_b32 s3, s73, s3
	s_cselect_b32 s2, s72, s2
	s_cselect_b32 vcc_hi, s77, s55
	s_cselect_b32 vcc_lo, s76, s54
	s_add_i32 s1, 0, 0x14000
	v_add_u32_e32 v140, s0, v234
	v_add_u32_e32 v156, s1, v234
	ds_read_b128 v[128:131], v140
	ds_read_b128 v[132:135], v140 offset:1024
	ds_read_b128 v[136:139], v140 offset:2048
	ds_read_b128 v[140:143], v140 offset:3072
	ds_read_b128 v[144:147], v156
	ds_read_b128 v[148:151], v156 offset:1024
	ds_read_b128 v[152:155], v156 offset:2048
	ds_read_b128 v[156:159], v156 offset:3072
	v_lshl_add_u64 v[212:213], s[10:11], 0, v[202:203]
	s_add_i32 m0, s51, 0xc000
	ds_read_b128 v[160:163], v236
	ds_read_b128 v[164:167], v236 offset:1024
	ds_read_b128 v[168:171], v236 offset:2048
	ds_read_b128 v[172:175], v236 offset:3072
	ds_read_b128 v[176:179], v236 offset:4096
	ds_read_b128 v[180:183], v236 offset:5120
	ds_read_b128 v[204:207], v236 offset:6144
	ds_read_b128 v[208:211], v236 offset:7168
	global_load_lds_dwordx4 v[212:213], off
	v_lshl_add_u64 v[212:213], v[212:213], 0, s[62:63]
	s_add_i32 m0, s51, 0xe000
	s_nop 0
	global_load_lds_dwordx4 v[212:213], off
	s_waitcnt vmcnt(8)
	s_waitcnt lgkmcnt(0)
	s_barrier
	s_waitcnt lgkmcnt(0)
	v_mfma_f32_16x16x32_bf16 v[124:127], v[128:131], v[160:163], v[124:127]
	v_mfma_f32_16x16x32_bf16 v[120:123], v[136:139], v[160:163], v[120:123]
	v_mfma_f32_16x16x32_bf16 v[108:111], v[128:131], v[168:171], v[108:111]
	v_mfma_f32_16x16x32_bf16 v[104:107], v[136:139], v[168:171], v[104:107]
	v_mfma_f32_16x16x32_bf16 v[92:95], v[128:131], v[176:179], v[92:95]
	v_mfma_f32_16x16x32_bf16 v[88:91], v[136:139], v[176:179], v[88:91]
	v_mfma_f32_16x16x32_bf16 v[76:79], v[128:131], v[204:207], v[76:79]
	v_mfma_f32_16x16x32_bf16 v[72:75], v[136:139], v[204:207], v[72:75]
	v_mfma_f32_16x16x32_bf16 v[124:127], v[132:135], v[164:167], v[124:127]
	v_mfma_f32_16x16x32_bf16 v[120:123], v[140:143], v[164:167], v[120:123]
	v_mfma_f32_16x16x32_bf16 v[108:111], v[132:135], v[172:175], v[108:111]
	v_mfma_f32_16x16x32_bf16 v[104:107], v[140:143], v[172:175], v[104:107]
	v_mfma_f32_16x16x32_bf16 v[92:95], v[132:135], v[180:183], v[92:95]
	v_mfma_f32_16x16x32_bf16 v[88:91], v[140:143], v[180:183], v[88:91]
	v_mfma_f32_16x16x32_bf16 v[76:79], v[132:135], v[208:211], v[76:79]
	v_mfma_f32_16x16x32_bf16 v[72:75], v[140:143], v[208:211], v[72:75]
	v_mfma_f32_16x16x32_bf16 v[116:119], v[144:147], v[160:163], v[116:119]
	v_mfma_f32_16x16x32_bf16 v[112:115], v[152:155], v[160:163], v[112:115]
	v_mfma_f32_16x16x32_bf16 v[100:103], v[144:147], v[168:171], v[100:103]
	v_mfma_f32_16x16x32_bf16 v[96:99], v[152:155], v[168:171], v[96:99]
	v_mfma_f32_16x16x32_bf16 v[84:87], v[144:147], v[176:179], v[84:87]
	v_mfma_f32_16x16x32_bf16 v[80:83], v[152:155], v[176:179], v[80:83]
	v_mfma_f32_16x16x32_bf16 v[68:71], v[144:147], v[204:207], v[68:71]
	v_mfma_f32_16x16x32_bf16 v[64:67], v[152:155], v[204:207], v[64:67]
	v_mfma_f32_16x16x32_bf16 v[116:119], v[148:151], v[164:167], v[116:119]
	v_mfma_f32_16x16x32_bf16 v[112:115], v[156:159], v[164:167], v[112:115]
	v_mfma_f32_16x16x32_bf16 v[100:103], v[148:151], v[172:175], v[100:103]
	v_mfma_f32_16x16x32_bf16 v[96:99], v[156:159], v[172:175], v[96:99]
	v_mfma_f32_16x16x32_bf16 v[84:87], v[148:151], v[180:183], v[84:87]
	v_mfma_f32_16x16x32_bf16 v[80:83], v[156:159], v[180:183], v[80:83]
	v_mfma_f32_16x16x32_bf16 v[68:71], v[148:151], v[208:211], v[68:71]
	v_mfma_f32_16x16x32_bf16 v[64:67], v[156:159], v[208:211], v[64:67]
	s_barrier
	s_add_i32 s0, s0, s50
	v_lshl_add_u64 v[212:213], vcc, 0, v[184:185]
	s_mov_b32 m0, s0
	ds_read_b128 v[160:163], v236 offset:16384
	ds_read_b128 v[164:167], v236 offset:17408
	ds_read_b128 v[168:171], v236 offset:18432
	ds_read_b128 v[172:175], v236 offset:19456
	ds_read_b128 v[176:179], v236 offset:20480
	ds_read_b128 v[180:183], v236 offset:21504
	ds_read_b128 v[204:207], v236 offset:22528
	ds_read_b128 v[208:211], v236 offset:23552
	global_load_lds_dwordx4 v[212:213], off
	v_lshl_add_u64 v[214:215], v[212:213], 0, s[62:63]
	s_add_i32 m0, s0, 0x2000
	s_add_i32 s0, s1, s50
	global_load_lds_dwordx4 v[214:215], off
	v_lshl_add_u64 v[214:215], v[212:213], 0, s[42:43]
	s_mov_b32 m0, s0
	s_nop 0
	global_load_lds_dwordx4 v[214:215], off
	v_lshl_add_u64 v[214:215], v[212:213], 0, s[44:45]
	s_add_i32 m0, s0, 0x2000
	s_nop 0
	global_load_lds_dwordx4 v[214:215], off
	v_lshl_add_u64 v[214:215], s[2:3], 0, v[200:201]
	s_mov_b32 m0, s51
	v_lshl_add_u64 v[216:217], v[214:215], 0, s[62:63]
	global_load_lds_dwordx4 v[214:215], off
	s_mov_b32 m0, s66
	s_nop 0
	global_load_lds_dwordx4 v[216:217], off
	s_waitcnt vmcnt(8)
	s_waitcnt lgkmcnt(0)
	s_barrier
	s_waitcnt lgkmcnt(0)
	v_mfma_f32_16x16x32_bf16 v[60:63], v[128:131], v[160:163], v[60:63]
	v_mfma_f32_16x16x32_bf16 v[56:59], v[136:139], v[160:163], v[56:59]
	v_mfma_f32_16x16x32_bf16 v[44:47], v[128:131], v[168:171], v[44:47]
	v_mfma_f32_16x16x32_bf16 v[40:43], v[136:139], v[168:171], v[40:43]
	v_mfma_f32_16x16x32_bf16 v[28:31], v[128:131], v[176:179], v[28:31]
	v_mfma_f32_16x16x32_bf16 v[24:27], v[136:139], v[176:179], v[24:27]
	v_mfma_f32_16x16x32_bf16 v[12:15], v[128:131], v[204:207], v[12:15]
	v_mfma_f32_16x16x32_bf16 v[8:11], v[136:139], v[204:207], v[8:11]
	v_mfma_f32_16x16x32_bf16 v[60:63], v[132:135], v[164:167], v[60:63]
	v_mfma_f32_16x16x32_bf16 v[56:59], v[140:143], v[164:167], v[56:59]
	v_mfma_f32_16x16x32_bf16 v[44:47], v[132:135], v[172:175], v[44:47]
	v_mfma_f32_16x16x32_bf16 v[40:43], v[140:143], v[172:175], v[40:43]
	v_mfma_f32_16x16x32_bf16 v[28:31], v[132:135], v[180:183], v[28:31]
	v_mfma_f32_16x16x32_bf16 v[24:27], v[140:143], v[180:183], v[24:27]
	v_mfma_f32_16x16x32_bf16 v[12:15], v[132:135], v[208:211], v[12:15]
	v_mfma_f32_16x16x32_bf16 v[8:11], v[140:143], v[208:211], v[8:11]
	v_mfma_f32_16x16x32_bf16 v[52:55], v[144:147], v[160:163], v[52:55]
	v_mfma_f32_16x16x32_bf16 v[48:51], v[152:155], v[160:163], v[48:51]
	v_mfma_f32_16x16x32_bf16 v[36:39], v[144:147], v[168:171], v[36:39]
	v_mfma_f32_16x16x32_bf16 v[32:35], v[152:155], v[168:171], v[32:35]
	v_mfma_f32_16x16x32_bf16 v[20:23], v[144:147], v[176:179], v[20:23]
	v_mfma_f32_16x16x32_bf16 v[16:19], v[152:155], v[176:179], v[16:19]
	v_mfma_f32_16x16x32_bf16 v[4:7], v[144:147], v[204:207], v[4:7]
	v_mfma_f32_16x16x32_bf16 v[0:3], v[152:155], v[204:207], v[0:3]
	v_mfma_f32_16x16x32_bf16 v[52:55], v[148:151], v[164:167], v[52:55]
	v_mfma_f32_16x16x32_bf16 v[48:51], v[156:159], v[164:167], v[48:51]
	v_mfma_f32_16x16x32_bf16 v[36:39], v[148:151], v[172:175], v[36:39]
	v_mfma_f32_16x16x32_bf16 v[32:35], v[156:159], v[172:175], v[32:35]
	v_mfma_f32_16x16x32_bf16 v[20:23], v[148:151], v[180:183], v[20:23]
	v_mfma_f32_16x16x32_bf16 v[16:19], v[156:159], v[180:183], v[16:19]
	v_mfma_f32_16x16x32_bf16 v[4:7], v[148:151], v[208:211], v[4:7]
	v_mfma_f32_16x16x32_bf16 v[0:3], v[156:159], v[208:211], v[0:3]
	s_barrier
	s_add_i32 s0, 0, 0x18000
	s_add_i32 s1, 0, 0x1c000
	v_add_u32_e32 v140, s0, v234
	v_add_u32_e32 v156, s1, v234
	ds_read_b128 v[128:131], v140
	ds_read_b128 v[132:135], v140 offset:1024
	ds_read_b128 v[136:139], v140 offset:2048
	ds_read_b128 v[140:143], v140 offset:3072
	ds_read_b128 v[144:147], v156
	ds_read_b128 v[148:151], v156 offset:1024
	ds_read_b128 v[152:155], v156 offset:2048
	ds_read_b128 v[156:159], v156 offset:3072
	s_mov_b32 m0, s67
	v_lshl_add_u64 v[216:217], v[214:215], 0, s[42:43]
	ds_read_b128 v[160:163], v236 offset:32768
	ds_read_b128 v[164:167], v236 offset:33792
	ds_read_b128 v[168:171], v236 offset:34816
	ds_read_b128 v[172:175], v236 offset:35840
	ds_read_b128 v[176:179], v236 offset:36864
	ds_read_b128 v[180:183], v236 offset:37888
	ds_read_b128 v[204:207], v236 offset:38912
	ds_read_b128 v[208:211], v236 offset:39936
	global_load_lds_dwordx4 v[216:217], off
	v_lshl_add_u64 v[216:217], v[214:215], 0, s[44:45]
	s_mov_b32 m0, s78
	s_nop 0
	global_load_lds_dwordx4 v[216:217], off
	s_waitcnt vmcnt(8)
	s_waitcnt lgkmcnt(0)
	s_barrier
	s_waitcnt lgkmcnt(0)
	v_mfma_f32_16x16x32_bf16 v[124:127], v[128:131], v[160:163], v[124:127]
	v_mfma_f32_16x16x32_bf16 v[120:123], v[136:139], v[160:163], v[120:123]
	v_mfma_f32_16x16x32_bf16 v[108:111], v[128:131], v[168:171], v[108:111]
	v_mfma_f32_16x16x32_bf16 v[104:107], v[136:139], v[168:171], v[104:107]
	v_mfma_f32_16x16x32_bf16 v[92:95], v[128:131], v[176:179], v[92:95]
	v_mfma_f32_16x16x32_bf16 v[88:91], v[136:139], v[176:179], v[88:91]
	v_mfma_f32_16x16x32_bf16 v[76:79], v[128:131], v[204:207], v[76:79]
	v_mfma_f32_16x16x32_bf16 v[72:75], v[136:139], v[204:207], v[72:75]
	v_mfma_f32_16x16x32_bf16 v[124:127], v[132:135], v[164:167], v[124:127]
	v_mfma_f32_16x16x32_bf16 v[120:123], v[140:143], v[164:167], v[120:123]
	v_mfma_f32_16x16x32_bf16 v[108:111], v[132:135], v[172:175], v[108:111]
	v_mfma_f32_16x16x32_bf16 v[104:107], v[140:143], v[172:175], v[104:107]
	v_mfma_f32_16x16x32_bf16 v[92:95], v[132:135], v[180:183], v[92:95]
	v_mfma_f32_16x16x32_bf16 v[88:91], v[140:143], v[180:183], v[88:91]
	v_mfma_f32_16x16x32_bf16 v[76:79], v[132:135], v[208:211], v[76:79]
	v_mfma_f32_16x16x32_bf16 v[72:75], v[140:143], v[208:211], v[72:75]
	v_mfma_f32_16x16x32_bf16 v[116:119], v[144:147], v[160:163], v[116:119]
	v_mfma_f32_16x16x32_bf16 v[112:115], v[152:155], v[160:163], v[112:115]
	v_mfma_f32_16x16x32_bf16 v[100:103], v[144:147], v[168:171], v[100:103]
	v_mfma_f32_16x16x32_bf16 v[96:99], v[152:155], v[168:171], v[96:99]
	v_mfma_f32_16x16x32_bf16 v[84:87], v[144:147], v[176:179], v[84:87]
	v_mfma_f32_16x16x32_bf16 v[80:83], v[152:155], v[176:179], v[80:83]
	v_mfma_f32_16x16x32_bf16 v[68:71], v[144:147], v[204:207], v[68:71]
	v_mfma_f32_16x16x32_bf16 v[64:67], v[152:155], v[204:207], v[64:67]
	v_mfma_f32_16x16x32_bf16 v[116:119], v[148:151], v[164:167], v[116:119]
	v_mfma_f32_16x16x32_bf16 v[112:115], v[156:159], v[164:167], v[112:115]
	v_mfma_f32_16x16x32_bf16 v[100:103], v[148:151], v[172:175], v[100:103]
	v_mfma_f32_16x16x32_bf16 v[96:99], v[156:159], v[172:175], v[96:99]
	v_mfma_f32_16x16x32_bf16 v[84:87], v[148:151], v[180:183], v[84:87]
	v_mfma_f32_16x16x32_bf16 v[80:83], v[156:159], v[180:183], v[80:83]
	v_mfma_f32_16x16x32_bf16 v[68:71], v[148:151], v[208:211], v[68:71]
	v_mfma_f32_16x16x32_bf16 v[64:67], v[156:159], v[208:211], v[64:67]
	s_barrier
	s_add_i32 s0, s0, s50
	v_lshl_add_u64 v[216:217], v[212:213], 0, s[90:91]
	s_mov_b32 m0, s0
	ds_read_b128 v[160:163], v236 offset:49152
	ds_read_b128 v[164:167], v236 offset:50176
	ds_read_b128 v[168:171], v236 offset:51200
	ds_read_b128 v[172:175], v236 offset:52224
	ds_read_b128 v[176:179], v236 offset:53248
	ds_read_b128 v[180:183], v236 offset:54272
	ds_read_b128 v[204:207], v236 offset:55296
	ds_read_b128 v[208:211], v236 offset:56320
	global_load_lds_dwordx4 v[216:217], off
	v_lshl_add_u64 v[216:217], v[212:213], 0, s[56:57]
	s_add_i32 m0, s0, 0x2000
	s_add_i32 s0, s1, s50
	global_load_lds_dwordx4 v[216:217], off
	v_lshl_add_u64 v[216:217], v[212:213], 0, s[14:15]
	s_mov_b32 m0, s0
	v_lshl_add_u64 v[212:213], v[212:213], 0, s[52:53]
	global_load_lds_dwordx4 v[216:217], off
	s_add_i32 m0, s0, 0x2000
	s_nop 0
	global_load_lds_dwordx4 v[212:213], off
	v_lshl_add_u64 v[212:213], v[214:215], 0, s[90:91]
	s_mov_b32 m0, s48
	s_nop 0
	global_load_lds_dwordx4 v[212:213], off
	v_lshl_add_u64 v[212:213], v[214:215], 0, s[56:57]
	s_mov_b32 m0, s49
	s_nop 0
	global_load_lds_dwordx4 v[212:213], off
	s_waitcnt vmcnt(8)
	s_waitcnt lgkmcnt(0)
	s_barrier
	s_waitcnt lgkmcnt(0)
	v_mfma_f32_16x16x32_bf16 v[60:63], v[128:131], v[160:163], v[60:63]
	v_mfma_f32_16x16x32_bf16 v[56:59], v[136:139], v[160:163], v[56:59]
	v_mfma_f32_16x16x32_bf16 v[44:47], v[128:131], v[168:171], v[44:47]
	v_mfma_f32_16x16x32_bf16 v[40:43], v[136:139], v[168:171], v[40:43]
	v_mfma_f32_16x16x32_bf16 v[28:31], v[128:131], v[176:179], v[28:31]
	v_mfma_f32_16x16x32_bf16 v[24:27], v[136:139], v[176:179], v[24:27]
	v_mfma_f32_16x16x32_bf16 v[12:15], v[128:131], v[204:207], v[12:15]
	v_mfma_f32_16x16x32_bf16 v[8:11], v[136:139], v[204:207], v[8:11]
	v_mfma_f32_16x16x32_bf16 v[60:63], v[132:135], v[164:167], v[60:63]
	v_mfma_f32_16x16x32_bf16 v[56:59], v[140:143], v[164:167], v[56:59]
	v_mfma_f32_16x16x32_bf16 v[44:47], v[132:135], v[172:175], v[44:47]
	v_mfma_f32_16x16x32_bf16 v[40:43], v[140:143], v[172:175], v[40:43]
	v_mfma_f32_16x16x32_bf16 v[28:31], v[132:135], v[180:183], v[28:31]
	v_mfma_f32_16x16x32_bf16 v[24:27], v[140:143], v[180:183], v[24:27]
	v_mfma_f32_16x16x32_bf16 v[12:15], v[132:135], v[208:211], v[12:15]
	v_mfma_f32_16x16x32_bf16 v[8:11], v[140:143], v[208:211], v[8:11]
	v_mfma_f32_16x16x32_bf16 v[52:55], v[144:147], v[160:163], v[52:55]
	v_mfma_f32_16x16x32_bf16 v[48:51], v[152:155], v[160:163], v[48:51]
	v_mfma_f32_16x16x32_bf16 v[36:39], v[144:147], v[168:171], v[36:39]
	v_mfma_f32_16x16x32_bf16 v[32:35], v[152:155], v[168:171], v[32:35]
	v_mfma_f32_16x16x32_bf16 v[20:23], v[144:147], v[176:179], v[20:23]
	v_mfma_f32_16x16x32_bf16 v[16:19], v[152:155], v[176:179], v[16:19]
	v_mfma_f32_16x16x32_bf16 v[4:7], v[144:147], v[204:207], v[4:7]
	v_mfma_f32_16x16x32_bf16 v[0:3], v[152:155], v[204:207], v[0:3]
	v_mfma_f32_16x16x32_bf16 v[52:55], v[148:151], v[164:167], v[52:55]
	v_mfma_f32_16x16x32_bf16 v[48:51], v[156:159], v[164:167], v[48:51]
	v_mfma_f32_16x16x32_bf16 v[36:39], v[148:151], v[172:175], v[36:39]
	v_mfma_f32_16x16x32_bf16 v[32:35], v[156:159], v[172:175], v[32:35]
	v_mfma_f32_16x16x32_bf16 v[20:23], v[148:151], v[180:183], v[20:23]
	v_mfma_f32_16x16x32_bf16 v[16:19], v[156:159], v[180:183], v[16:19]
	v_mfma_f32_16x16x32_bf16 v[4:7], v[148:151], v[208:211], v[4:7]
	v_mfma_f32_16x16x32_bf16 v[0:3], v[156:159], v[208:211], v[0:3]
	s_barrier
	s_add_i32 s83, s83, 2
	s_add_u32 s10, s10, 0x100
	s_addc_u32 s11, s11, 0
	s_add_u32 s54, s54, 0x100
	s_addc_u32 s55, s55, 0
	s_cmp_gt_u32 s83, 41
	s_cbranch_scc0 .LBB0_1997
	s_and_b64 vcc, exec, s[36:37]
	s_cbranch_vccz .LBB0_2000
	s_barrier
